# gla_step1: counted waits for operand loads and U stores widened to dwordx4 via permlane16_swap; gla_step3: S-state loads left in flight during decay
# speedup vs baseline: 1.0181x; 1.0062x over previous
; #define LAS __attribute__((address_space(3)))
; __device__ __forceinline__ s16x4 trread(const LAS unsigned char* p) { return __builtin_bit_cast(s16x4, __builtin_amdgcn_ds_read_tr16_b64_v4i16((LAS s16x4*)p)); }
; __device__ __forceinline__ bf16x8 cat8(s16x4 lo, s16x4 hi) { return (bf16x8){lo[0], lo[1], lo[2], lo[3], hi[0], hi[1], hi[2], hi[3]}; }
; __device__ __forceinline__ void gla_step1(const Params& P, int l, LAS unsigned char* lds, int item, int next_item, int tid, G1Pre& R) {
;     ...
;     __syncthreads();
;     const int lane = tid & 63, w = tid >> 6, i = lane & 15, quad = lane >> 4; const int e0 = w * 32;
;     bf16x8 vf[2][2];
; #pragma unroll
;     for (int et = 0; et < 2; ++et)
; #pragma unroll
;         for (int ks = 0; ks < 2; ++ks) { const LAS unsigned char* p = VT + (ks * 32 + quad * 8 + (i >> 2)) * 544 + (e0 + et * 16 + 4 * (i & 3)) * 2; vf[et][ks] = cat8(trread(p), trread(p + 4 * 544)); }
.LBB0_361:
	v_bfe_u32 v19, v18, 4, 2
	v_ashrrev_i32_e32 v2, 1, v18
	v_and_b32_e32 v80, 0xffffffe0, v2
	v_lshlrev_b32_e32 v81, 3, v19
	v_bfe_u32 v2, v18, 2, 2
	v_lshlrev_b32_e32 v3, 2, v18
	v_and_b32_e32 v0, 15, v18
	v_or_b32_e32 v2, v81, v2
	v_and_or_b32 v3, v3, 12, v80
	v_mul_u32_u24_e32 v2, 0x220, v2
	v_lshlrev_b32_e32 v3, 1, v3
	v_lshlrev_b32_e32 v19, 4, v19
	v_mul_u32_u24_e32 v20, 0x90, v0
	v_add3_u32 v8, 0, v3, v2
	v_add3_u32 v19, 0, v19, v20
	s_waitcnt lgkmcnt(0)
	s_barrier
; #define LAS __attribute__((address_space(3)))
; __device__ __forceinline__ unsigned pk2(float lo, float hi) { const f32x2c_t v = {lo, hi}; return __builtin_bit_cast(unsigned, __builtin_convertvector(v, bf16x2c_t)); }
; #define MFMA16(a, b, c) __builtin_amdgcn_mfma_f32_16x16x32_bf16((a), (b), (c), 0, 0, 0)
; __device__ __forceinline__ s16x4 trread(const LAS unsigned char* p) { return __builtin_bit_cast(s16x4, __builtin_amdgcn_ds_read_tr16_b64_v4i16((LAS s16x4*)p)); }
; __device__ __forceinline__ bf16x8 cat8(s16x4 lo, s16x4 hi) { return (bf16x8){lo[0], lo[1], lo[2], lo[3], hi[0], hi[1], hi[2], hi[3]}; }
; __device__ __forceinline__ void gla_step1(const Params& P, int l, LAS unsigned char* lds, int item, int next_item, int tid, G1Pre& R) {
;     ...
;     const int lane = tid & 63, w = tid >> 6, i = lane & 15, quad = lane >> 4; const int e0 = w * 32;
;     bf16x8 vf[2][2];
; #pragma unroll
;     for (int et = 0; et < 2; ++et)
; #pragma unroll
;         for (int ks = 0; ks < 2; ++ks) { const LAS unsigned char* p = VT + (ks * 32 + quad * 8 + (i >> 2)) * 544 + (e0 + et * 16 + 4 * (i & 3)) * 2; vf[et][ks] = cat8(trread(p), trread(p + 4 * 544)); }
;     f32x4 acc[8][2];
; #pragma unroll
;     for (int dt = 0; dt < 8; ++dt) { acc[dt][0] = (f32x4){0.f, 0.f, 0.f, 0.f}; acc[dt][1] = (f32x4){0.f, 0.f, 0.f, 0.f};
; #pragma unroll
;         for (int ks = 0; ks < 2; ++ks) { const bf16x8 kf = *(const LAS bf16x8*)(KD + (dt * 16 + i) * 144 + (ks * 32 + quad * 8) * 2);
;             acc[dt][0] = MFMA16(kf, vf[0][ks], acc[dt][0]); acc[dt][1] = MFMA16(kf, vf[1][ks], acc[dt][1]); } }
;     bf16* Ut = (bf16*)(P.ws + WS_U) + (size_t)item * 256 * 128;
; #pragma unroll
;     for (int dt = 0; dt < 8; ++dt)
; #pragma unroll
;         for (int et = 0; et < 2; ++et) { const f32x4 a = acc[dt][et]; v2u o; o.x = pk2(a[0], a[1]); o.y = pk2(a[2], a[3]);
;             *(v2u*)(Ut + (size_t)(e0 + et * 16 + i) * 128 + dt * 16 + quad * 4) = o; }
	ds_read_b64_tr_b16 v[12:13], v8 offset:20608
	ds_read_b64_tr_b16 v[10:11], v8 offset:18432
	ds_read_b64_tr_b16 v[14:15], v8 offset:18464
	ds_read_b64_tr_b16 v[2:3], v8 offset:35840
	ds_read_b64_tr_b16 v[4:5], v8 offset:38016
	ds_read_b64_tr_b16 v[16:17], v8 offset:20640
	ds_read_b64_tr_b16 v[6:7], v8 offset:35872
	ds_read_b64_tr_b16 v[8:9], v8 offset:38048
	ds_read_b128 v[20:23], v19
	ds_read_b128 v[28:31], v19 offset:64
	s_waitcnt lgkmcnt(1)
	v_mfma_f32_16x16x32_bf16 v[24:27], v[20:23], v[10:13], 0
	ds_read_b128 v[36:39], v19 offset:2368
	s_add_u32 s4, s60, s8
	ds_read_b128 v[44:47], v19 offset:4672
	v_mfma_f32_16x16x32_bf16 v[20:23], v[20:23], v[14:17], 0
	s_addc_u32 s5, s61, s9
	s_add_i32 s13, s13, s49
	ds_read_b128 v[52:55], v19 offset:6976
	s_waitcnt lgkmcnt(3)
	v_mfma_f32_16x16x32_bf16 v[24:27], v[28:31], v[2:5], v[24:27]
	ds_read_b128 v[60:63], v19 offset:9280
	ds_read_b128 v[68:71], v19 offset:11584
	ds_read_b128 v[76:79], v19 offset:13888
	v_mfma_f32_16x16x32_bf16 v[20:23], v[28:31], v[6:9], v[20:23]
	ds_read_b128 v[28:31], v19 offset:2304
	s_waitcnt lgkmcnt(0)
	v_mfma_f32_16x16x32_bf16 v[32:35], v[28:31], v[10:13], 0
	v_mfma_f32_16x16x32_bf16 v[28:31], v[28:31], v[14:17], 0
	v_mfma_f32_16x16x32_bf16 v[32:35], v[36:39], v[2:5], v[32:35]
	v_mfma_f32_16x16x32_bf16 v[28:31], v[36:39], v[6:9], v[28:31]
	ds_read_b128 v[36:39], v19 offset:4608
	s_waitcnt lgkmcnt(0)
	v_mfma_f32_16x16x32_bf16 v[40:43], v[36:39], v[10:13], 0
	v_mfma_f32_16x16x32_bf16 v[36:39], v[36:39], v[14:17], 0
	v_mfma_f32_16x16x32_bf16 v[40:43], v[44:47], v[2:5], v[40:43]
	v_mfma_f32_16x16x32_bf16 v[36:39], v[44:47], v[6:9], v[36:39]
	ds_read_b128 v[44:47], v19 offset:6912
	s_waitcnt lgkmcnt(0)
	v_mfma_f32_16x16x32_bf16 v[48:51], v[44:47], v[10:13], 0
	v_mfma_f32_16x16x32_bf16 v[44:47], v[44:47], v[14:17], 0
	v_mfma_f32_16x16x32_bf16 v[48:51], v[52:55], v[2:5], v[48:51]
	v_mfma_f32_16x16x32_bf16 v[44:47], v[52:55], v[6:9], v[44:47]
	ds_read_b128 v[52:55], v19 offset:9216
	s_waitcnt lgkmcnt(0)
	v_mfma_f32_16x16x32_bf16 v[56:59], v[52:55], v[10:13], 0
	v_mfma_f32_16x16x32_bf16 v[52:55], v[52:55], v[14:17], 0
	v_mfma_f32_16x16x32_bf16 v[56:59], v[60:63], v[2:5], v[56:59]
	v_mfma_f32_16x16x32_bf16 v[52:55], v[60:63], v[6:9], v[52:55]
	ds_read_b128 v[60:63], v19 offset:11520
	s_waitcnt lgkmcnt(0)
	v_mfma_f32_16x16x32_bf16 v[64:67], v[60:63], v[10:13], 0
	v_mfma_f32_16x16x32_bf16 v[60:63], v[60:63], v[14:17], 0
	v_mfma_f32_16x16x32_bf16 v[64:67], v[68:71], v[2:5], v[64:67]
	v_mfma_f32_16x16x32_bf16 v[60:63], v[68:71], v[6:9], v[60:63]
	ds_read_b128 v[68:71], v19 offset:13824
	s_waitcnt lgkmcnt(0)
	v_mfma_f32_16x16x32_bf16 v[72:75], v[68:71], v[10:13], 0
	v_mfma_f32_16x16x32_bf16 v[68:71], v[68:71], v[14:17], 0
	v_mfma_f32_16x16x32_bf16 v[72:75], v[76:79], v[2:5], v[72:75]
	v_mfma_f32_16x16x32_bf16 v[68:71], v[76:79], v[6:9], v[68:71]
	ds_read_b128 v[76:79], v19 offset:16128
	s_waitcnt lgkmcnt(0)
	v_mfma_f32_16x16x32_bf16 v[10:13], v[76:79], v[10:13], 0
	v_mfma_f32_16x16x32_bf16 v[14:17], v[76:79], v[14:17], 0
	ds_read_b128 v[76:79], v19 offset:16192
	s_waitcnt lgkmcnt(0)
	v_mfma_f32_16x16x32_bf16 v[2:5], v[76:79], v[2:5], v[10:13]
	s_nop 3
	v_or_b32_e32 v10, v80, v0
	v_ashrrev_i32_e32 v11, 31, v10
	v_and_b32_e32 v200, 16, v18
	v_mfma_f32_16x16x32_bf16 v[6:9], v[76:79], v[6:9], v[14:17]
	v_lshrrev_b32_e32 v201, 1, v200
	v_add_u32_e32 v200, v200, v201
	v_mov_b32_e32 v201, 0
	s_nop 0
	v_lshlrev_b64 v[14:15], 8, v[10:11]
	v_or_b32_e32 v10, 16, v10
	v_or_b32_e32 v14, v14, v81
	v_ashrrev_i32_e32 v11, 31, v10
	v_lshl_add_u64 v[14:15], s[4:5], 0, v[14:15]
	v_lshlrev_b64 v[10:11], 8, v[10:11]
	v_add_co_u32_e32 v14, vcc, s72, v14
	v_or_b32_e32 v10, v10, v81
	s_nop 0
	v_addc_co_u32_e32 v15, vcc, 0, v15, vcc
	v_lshl_add_u64 v[10:11], s[4:5], 0, v[10:11]
	v_add_co_u32_e32 v10, vcc, s72, v10
	v_lshl_add_u64 v[14:15], v[14:15], 0, v[200:201]
	s_nop 0
	v_addc_co_u32_e32 v11, vcc, 0, v11, vcc
	v_lshl_add_u64 v[10:11], v[10:11], 0, v[200:201]
	v_cvt_pk_bf16_f32 v192, v24, v25
	v_cvt_pk_bf16_f32 v193, v26, v27
	v_cvt_pk_bf16_f32 v194, v32, v33
	v_cvt_pk_bf16_f32 v195, v34, v35
	s_nop 1
	v_permlane16_swap_b32_e32 v192, v194
	v_permlane16_swap_b32_e32 v193, v195
	global_store_dwordx4 v[14:15], v[192:195], off
	v_cvt_pk_bf16_f32 v204, v20, v21
	v_cvt_pk_bf16_f32 v205, v22, v23
	v_cvt_pk_bf16_f32 v206, v28, v29
	v_cvt_pk_bf16_f32 v207, v30, v31
	s_nop 1
	v_permlane16_swap_b32_e32 v204, v206
	v_permlane16_swap_b32_e32 v205, v207
	global_store_dwordx4 v[10:11], v[204:207], off
	v_cvt_pk_bf16_f32 v196, v40, v41
	v_cvt_pk_bf16_f32 v197, v42, v43
	v_cvt_pk_bf16_f32 v198, v48, v49
	v_cvt_pk_bf16_f32 v199, v50, v51
	s_nop 1
	v_permlane16_swap_b32_e32 v196, v198
	v_permlane16_swap_b32_e32 v197, v199
	global_store_dwordx4 v[14:15], v[196:199], off offset:64
	v_cvt_pk_bf16_f32 v208, v36, v37
	v_cvt_pk_bf16_f32 v209, v38, v39
	v_cvt_pk_bf16_f32 v210, v44, v45
	v_cvt_pk_bf16_f32 v211, v46, v47
	s_nop 1
	v_permlane16_swap_b32_e32 v208, v210
	v_permlane16_swap_b32_e32 v209, v211
	global_store_dwordx4 v[10:11], v[208:211], off offset:64
	v_cvt_pk_bf16_f32 v192, v56, v57
	v_cvt_pk_bf16_f32 v193, v58, v59
	v_cvt_pk_bf16_f32 v194, v64, v65
	v_cvt_pk_bf16_f32 v195, v66, v67
	s_nop 1
	v_permlane16_swap_b32_e32 v192, v194
	v_permlane16_swap_b32_e32 v193, v195
	global_store_dwordx4 v[14:15], v[192:195], off offset:128
	v_cvt_pk_bf16_f32 v204, v52, v53
	v_cvt_pk_bf16_f32 v205, v54, v55
	v_cvt_pk_bf16_f32 v206, v60, v61
	v_cvt_pk_bf16_f32 v207, v62, v63
	s_nop 1
	v_permlane16_swap_b32_e32 v204, v206
	v_permlane16_swap_b32_e32 v205, v207
	global_store_dwordx4 v[10:11], v[204:207], off offset:128
	v_cvt_pk_bf16_f32 v196, v72, v73
	v_cvt_pk_bf16_f32 v197, v74, v75
	v_cvt_pk_bf16_f32 v198, v2, v3
	v_cvt_pk_bf16_f32 v199, v4, v5
	s_nop 1
	v_permlane16_swap_b32_e32 v196, v198
	v_permlane16_swap_b32_e32 v197, v199
	global_store_dwordx4 v[14:15], v[196:199], off offset:192
	v_cvt_pk_bf16_f32 v208, v68, v69
	v_cvt_pk_bf16_f32 v209, v70, v71
	v_cvt_pk_bf16_f32 v210, v6, v7
	v_cvt_pk_bf16_f32 v211, v8, v9
	s_nop 1
	v_permlane16_swap_b32_e32 v208, v210
	v_permlane16_swap_b32_e32 v209, v211
	global_store_dwordx4 v[10:11], v[208:211], off offset:192
	v_readlane_b32 s4, v254, 58
	v_readlane_b32 s5, v254, 60
	s_nop 3
	s_add_i32 s14, s14, s4
	s_add_i32 s12, s12, s5
	v_readlane_b32 s4, v254, 61
	v_readlane_b32 s5, v254, 62
	s_nop 3
	s_add_u32 s8, s8, s4
	s_addc_u32 s9, s9, s5
	v_readlane_b32 s4, v255, 8
	v_readlane_b32 s5, v255, 9
	s_nop 3
	s_add_u32 s6, s6, s4
	s_addc_u32 s7, s7, s5
	s_and_b64 vcc, exec, s[0:1]
	s_cbranch_vccnz .LBB0_358

; #define LAS __attribute__((address_space(3)))
; __device__ __forceinline__ void gla_step1(const Params& P, int l, LAS unsigned char* lds, int item, int next_item, int tid, G1Pre& R) {
;     const int bh = item >> 6, n = item & 63, b = bh >> 2, h = bh & 3; const int t0 = b * SEQ + n * 64;
;     const bf16* z = (const bf16*)(P.ws + WS_Z); const float* zs = (const float*)(P.ws + WS_ZS);
;     LAS unsigned char* KD = lds; LAS unsigned char* VT = lds + 18432; LAS float* GD = (LAS float*)(lds + 53248); LAS float* TOT = (LAS float*)(lds + 57344);
;     const int d = tid & 127, rg = tid >> 7;
;     f32x4 gdr = (f32x4){0.f, 0.f, 0.f, 0.f}; if (tid < 256) gdr = *(const f32x4*)(zs + (size_t)t0 * 32 + (tid >> 2) * 32 + (tid & 3) * 4);
;     float wv[16]; { const float* wup = P.w_gk_up + (size_t)l * 16 * 512 + h * 128;
; #pragma unroll
;       for (int r = 0; r < 16; ++r) wv[r] = wup[r * 512 + d]; }
;     const float bias = P.b_gk[l * 512 + h * 128 + d];
;     bf16 kraw[16];
; #pragma unroll
;     for (int c = 0; c < 16; ++c) kraw[c] = z[(size_t)(t0 + rg * 16 + c) * ZP + ZC_GK + h * 128 + d];
;     __syncthreads();
;     if (tid < 256) *(LAS f32x4*)(GD + (tid >> 2) * 16 + (tid & 3) * 4) = gdr;
.LBB0_364:
	s_or_b64 exec, exec, s[0:1]
	s_and_b32 s5, s12, 0x180
	s_lshl_b32 s0, s5, 2
	v_readlane_b32 s1, v253, 2
	v_and_b32_e32 v19, 0x7f, v18
	s_add_u32 s0, s1, s0
	v_readlane_b32 s1, v255, 50
	s_addc_u32 s1, s1, 0
	v_lshlrev_b32_e32 v0, 2, v19
	v_lshl_add_u64 v[28:29], s[0:1], 0, v[0:1]
	s_nop 1
	global_load_dword v6, v0, s[0:1]
	global_load_dword v10, v0, s[0:1] offset:2048
	v_add_co_u32_e64 v8, s[0:1], s68, v28
	v_readlane_b32 s16, v253, 9
	s_nop 0
	v_addc_co_u32_e64 v9, s[0:1], 0, v29, s[0:1]
	v_add_co_u32_e64 v14, s[0:1], s42, v28
	v_readlane_b32 s26, v253, 19
	s_nop 0
	v_addc_co_u32_e64 v15, s[0:1], 0, v29, s[0:1]
	s_movk_i32 s0, 0x3000
	global_load_dword v12, v[14:15], off offset:-4096
	s_nop 0
	global_load_dword v8, v[8:9], off offset:2048
	s_nop 0
	global_load_dword v7, v[14:15], off
	global_load_dword v11, v[14:15], off offset:2048
	v_add_co_u32_e64 v14, s[0:1], s0, v28
	v_readlane_b32 s27, v253, 20
	s_nop 0
	v_addc_co_u32_e64 v15, s[0:1], 0, v29, s[0:1]
	s_movk_i32 s0, 0x4000
	s_nop 0
	v_add_co_u32_e64 v16, s[0:1], s0, v28
	v_ashrrev_i32_e32 v25, 7, v18
	s_nop 0
	v_addc_co_u32_e64 v17, s[0:1], 0, v29, s[0:1]
	s_movk_i32 s0, 0x5000
	s_nop 0
	v_add_co_u32_e64 v20, s[0:1], s0, v28
	global_load_dword v13, v[16:17], off offset:-4096
	global_load_dword v9, v[14:15], off offset:2048
	s_nop 0
	global_load_dword v14, v[16:17], off
	s_nop 0
	global_load_dword v16, v[16:17], off offset:2048
	v_addc_co_u32_e64 v21, s[0:1], 0, v29, s[0:1]
	v_add_co_u32_e64 v30, s[0:1], s80, v28
	s_lshl_b32 s76, s5, 1
	s_nop 0
	v_addc_co_u32_e64 v31, s[0:1], 0, v29, s[0:1]
	s_movk_i32 s0, 0x7000
	s_nop 0
	v_add_co_u32_e64 v28, s[0:1], s0, v28
	global_load_dword v22, v[30:31], off offset:-4096
	s_nop 0
	global_load_dword v20, v[20:21], off offset:2048
	s_nop 0
	global_load_dword v15, v[30:31], off
	global_load_dword v17, v[30:31], off offset:2048
	v_addc_co_u32_e64 v29, s[0:1], 0, v29, s[0:1]
	v_readlane_b32 s0, v255, 51
	s_or_b32 s0, s5, s0
	global_load_dword v23, v[28:29], off
	global_load_dword v21, v[28:29], off offset:2048
	v_or_b32_e32 v0, s0, v19
	v_readlane_b32 s0, v253, 57
	v_lshl_add_u64 v[28:29], v[0:1], 2, s[26:27]
	v_lshlrev_b32_e32 v0, 1, v19
	v_readlane_b32 s1, v253, 58
	global_load_dword v43, v[28:29], off
	v_lshl_add_u32 v42, v25, 4, s4
	v_lshl_add_u64 v[28:29], s[0:1], 0, v[0:1]
	v_lshl_add_u64 v[44:45], v[28:29], 0, s[76:77]
	v_mad_i64_i32 v[28:29], s[0:1], v42, s80, v[44:45]
	v_or_b32_e32 v0, 1, v42
	global_load_ushort v31, v[28:29], off
	v_mad_i64_i32 v[28:29], s[0:1], v0, s80, v[44:45]
	v_or_b32_e32 v0, 2, v42
	global_load_ushort v37, v[28:29], off
	v_mad_i64_i32 v[28:29], s[0:1], v0, s80, v[44:45]
	v_or_b32_e32 v0, 3, v42
	v_mad_i64_i32 v[32:33], s[0:1], v0, s80, v[44:45]
	v_or_b32_e32 v0, 4, v42
	global_load_ushort v29, v[28:29], off
	v_readlane_b32 s17, v253, 10
	global_load_ushort v35, v[32:33], off
	v_mad_i64_i32 v[32:33], s[0:1], v0, s80, v[44:45]
	v_or_b32_e32 v0, 5, v42
	global_load_ushort v28, v[32:33], off
	v_mad_i64_i32 v[32:33], s[0:1], v0, s80, v[44:45]
	v_or_b32_e32 v0, 6, v42
	v_mad_i64_i32 v[38:39], s[0:1], v0, s80, v[44:45]
	v_or_b32_e32 v0, 7, v42
	global_load_ushort v33, v[32:33], off
	v_readlane_b32 s18, v253, 11
	global_load_ushort v27, v[38:39], off
	v_mad_i64_i32 v[38:39], s[0:1], v0, s80, v[44:45]
	v_or_b32_e32 v0, 8, v42
	global_load_ushort v41, v[38:39], off
	v_mad_i64_i32 v[38:39], s[0:1], v0, s80, v[44:45]
	v_or_b32_e32 v0, 9, v42
	global_load_ushort v36, v[38:39], off
	v_mad_i64_i32 v[38:39], s[0:1], v0, s80, v[44:45]
	v_or_b32_e32 v0, 10, v42
	global_load_ushort v40, v[38:39], off
	v_mad_i64_i32 v[38:39], s[0:1], v0, s80, v[44:45]
	v_or_b32_e32 v0, 11, v42
	global_load_ushort v34, v[38:39], off
	v_mad_i64_i32 v[38:39], s[0:1], v0, s80, v[44:45]
	v_or_b32_e32 v0, 12, v42
	v_mad_i64_i32 v[46:47], s[0:1], v0, s80, v[44:45]
	v_or_b32_e32 v0, 13, v42
	global_load_ushort v39, v[38:39], off
	v_readlane_b32 s19, v253, 12
	global_load_ushort v32, v[46:47], off
	v_mad_i64_i32 v[46:47], s[0:1], v0, s80, v[44:45]
	v_or_b32_e32 v0, 14, v42
	global_load_ushort v38, v[46:47], off
	v_mad_i64_i32 v[46:47], s[0:1], v0, s80, v[44:45]
	v_or_b32_e32 v0, 15, v42
	v_mad_i64_i32 v[44:45], s[0:1], v0, s80, v[44:45]
	global_load_ushort v30, v[46:47], off
	global_load_ushort v42, v[44:45], off
	v_readlane_b32 s20, v253, 13
	v_readlane_b32 s21, v253, 14
	v_readlane_b32 s22, v253, 15
	v_readlane_b32 s23, v253, 16
	v_readlane_b32 s24, v253, 17
	v_readlane_b32 s25, v253, 18
	v_readlane_b32 s28, v253, 21
	v_readlane_b32 s29, v253, 22
	v_readlane_b32 s30, v253, 23
	v_readlane_b32 s31, v253, 24
	s_barrier
	s_and_saveexec_b64 s[0:1], vcc
	s_cbranch_execz .LBB0_366
	v_and_b32_e32 v0, 0xffffffc0, v26
	v_add3_u32 v0, 0, v0, v24
	s_waitcnt vmcnt(33)
	ds_write_b128 v0, v[2:5] offset:53248
; #define LAS __attribute__((address_space(3)))
; __device__ __forceinline__ float logsig(float x) { return fminf(x, 0.f) - __logf(1.f + __expf(-fabsf(x))); }
; __device__ __forceinline__ void gla_decay(LAS float* gd, LAS float* tot, int tid, const float (&w)[16], float bias, float (&bv)[16], float& blast) {
;     const int d = tid & 127, rg = tid >> 7;
;     float run = 0.f;
; #pragma unroll
;     for (int c = 0; c < 16; ++c) { const LAS f32x4* g4 = (const LAS f32x4*)(gd + (rg * 16 + c) * 16); float a = bias;
; #pragma unroll
;         for (int q = 0; q < 4; ++q) { const f32x4 g = g4[q]; a += g[0] * w[4 * q] + g[1] * w[4 * q + 1] + g[2] * w[4 * q + 2] + g[3] * w[4 * q + 3]; }
;         run += logsig(a) * 0.0625f; bv[c] = run; }
; __device__ __forceinline__ void gla_step1(const Params& P, int l, LAS unsigned char* lds, int item, int next_item, int tid, G1Pre& R) {
;     ...
;     if (tid < 256) *(LAS f32x4*)(GD + (tid >> 2) * 16 + (tid & 3) * 4) = gdr;
;     store_v(VT, tid, R.vr);
;     __syncthreads();
;     float bv[16], blast;
;     gla_decay(GD, TOT, tid, wv, bias, bv, blast);
.LBB0_366:
	s_or_b64 exec, exec, s[0:1]
	v_and_b32_e32 v0, 0x1f0, v26
	s_waitcnt vmcnt(33)
	v_add_u32_e32 v2, 0, v0
	v_ashrrev_i32_e32 v4, 5, v18
	s_movk_i32 s4, 0x220
	v_mad_u64_u32 v[44:45], s[0:1], v4, s4, v[2:3]
	v_add_u32_e32 v3, 0x200, v18
	v_ashrrev_i32_e32 v5, 5, v3
	ds_write_b128 v44, v[128:131] offset:18432
	v_mad_u64_u32 v[44:45], s[0:1], v5, s4, v[2:3]
	v_add_u32_e32 v3, 0x400, v18
	v_ashrrev_i32_e32 v24, 5, v3
	ds_write_b128 v44, v[132:135] offset:18432
	v_mad_u64_u32 v[44:45], s[0:1], v24, s4, v[2:3]
	v_add_u32_e32 v3, 0x600, v18
	v_ashrrev_i32_e32 v26, 5, v3
	v_mad_u64_u32 v[2:3], s[0:1], v26, s4, v[2:3]
	ds_write_b128 v44, v[136:139] offset:18432
	ds_write_b128 v2, v[140:143] offset:18432
	v_lshl_add_u32 v2, v25, 10, 0
	s_waitcnt lgkmcnt(0)
	s_barrier
	ds_read_b128 v[44:47], v2 offset:53248
	ds_read_b128 v[48:51], v2 offset:53264
	ds_read_b128 v[52:55], v2 offset:53280
	ds_read_b128 v[56:59], v2 offset:53296
	s_waitcnt vmcnt(16)
	s_waitcnt lgkmcnt(3)
	v_mov_b32_e32 v60, v44
	s_waitcnt lgkmcnt(2)
	v_mov_b32_e32 v61, v48
	v_mov_b32_e32 v48, v45
	v_pk_mul_f32 v[44:45], v[10:11], v[48:49]
	v_mov_b32_e32 v48, v46
	v_pk_fma_f32 v[44:45], v[6:7], v[60:61], v[44:45]
	v_mov_b32_e32 v49, v50
	v_pk_fma_f32 v[44:45], v[12:13], v[48:49], v[44:45]
	v_mov_b32_e32 v50, v47
	v_pk_fma_f32 v[44:45], v[8:9], v[50:51], v[44:45]
	s_nop 0
	v_add_f32_e32 v3, v43, v44
	v_add_f32_e32 v3, v3, v45
	s_waitcnt lgkmcnt(0)
	v_mov_b32_e32 v45, v56
	v_mov_b32_e32 v56, v53
	v_mov_b32_e32 v44, v52
	v_pk_mul_f32 v[46:47], v[16:17], v[56:57]
	s_nop 0
	v_pk_fma_f32 v[44:45], v[14:15], v[44:45], v[46:47]
	v_mov_b32_e32 v46, v54
	v_mov_b32_e32 v47, v58
	v_pk_fma_f32 v[44:45], v[22:23], v[46:47], v[44:45]
	v_mov_b32_e32 v58, v55
	v_pk_fma_f32 v[44:45], v[20:21], v[58:59], v[44:45]
	s_nop 0
	v_add_f32_e32 v3, v3, v44
	v_add_f32_e32 v3, v3, v45
	v_mul_f32_e64 v44, |v3|, s90
	v_exp_f32_e32 v44, v44
	v_min_f32_e32 v3, 0, v3
	v_add_f32_e32 v44, 1.0, v44
	v_cmp_gt_f32_e32 vcc, s74, v44
	s_nop 1
	v_cndmask_b32_e64 v45, 0, 32, vcc
	v_ldexp_f32 v44, v44, v45
	v_log_f32_e32 v56, v44
	ds_read_b128 v[44:47], v2 offset:53312
	ds_read_b128 v[48:51], v2 offset:53328
	v_mul_f32_e32 v52, 0x3f317217, v56
	v_fma_f32 v57, v56, s75, -v52
	s_waitcnt lgkmcnt(0)
	v_mov_b32_e32 v53, v48
	v_mov_b32_e32 v48, v45
	v_mov_b32_e32 v52, v44
	v_pk_mul_f32 v[44:45], v[10:11], v[48:49]
	v_mov_b32_e32 v48, v46
	v_pk_fma_f32 v[44:45], v[6:7], v[52:53], v[44:45]
	v_mov_b32_e32 v49, v50
	v_pk_fma_f32 v[48:49], v[12:13], v[48:49], v[44:45]
	v_mov_b32_e32 v50, v47
	ds_read_b128 v[44:47], v2 offset:53344
	ds_read_b128 v[52:55], v2 offset:53360
	v_pk_fma_f32 v[48:49], v[8:9], v[50:51], v[48:49]
	v_fmac_f32_e32 v57, 0x3377d1cf, v56
	v_add_f32_e32 v48, v43, v48
	v_add_f32_e32 v50, v48, v49
	s_waitcnt lgkmcnt(0)
	v_mov_b32_e32 v49, v52
	v_mov_b32_e32 v52, v45
	v_mov_b32_e32 v48, v44
	v_pk_mul_f32 v[44:45], v[16:17], v[52:53]
	v_fmac_f32_e32 v57, 0x3f317217, v56
	v_pk_fma_f32 v[44:45], v[14:15], v[48:49], v[44:45]
	v_mov_b32_e32 v48, v46
	v_mov_b32_e32 v49, v54
	v_pk_fma_f32 v[44:45], v[22:23], v[48:49], v[44:45]
	v_mov_b32_e32 v54, v47
	v_pk_fma_f32 v[44:45], v[20:21], v[54:55], v[44:45]
	v_cmp_lt_f32_e64 s[0:1], |v56|, s63
	v_add_f32_e32 v44, v50, v44
	v_add_f32_e32 v44, v44, v45
	v_mul_f32_e64 v45, |v44|, s90
	v_exp_f32_e32 v45, v45
	v_cndmask_b32_e64 v46, v56, v57, s[0:1]
	v_cndmask_b32_e32 v47, 0, v240, vcc
	v_sub_f32_e32 v46, v46, v47
	v_add_f32_e32 v45, 1.0, v45
	v_cmp_gt_f32_e32 vcc, s74, v45
	v_sub_f32_e32 v3, v3, v46
	v_min_f32_e32 v57, 0, v44
	v_cndmask_b32_e64 v47, 0, 32, vcc
	v_ldexp_f32 v45, v45, v47
	v_log_f32_e32 v56, v45
	ds_read_b128 v[44:47], v2 offset:53376
	ds_read_b128 v[48:51], v2 offset:53392
	s_mov_b32 s0, 0x3d800000
	v_fma_f32 v3, v3, s0, 0
	v_mul_f32_e32 v52, 0x3f317217, v56
	v_fma_f32 v58, v56, s75, -v52
	s_waitcnt lgkmcnt(0)
	v_mov_b32_e32 v53, v48
	v_mov_b32_e32 v48, v45
	v_mov_b32_e32 v52, v44
	v_pk_mul_f32 v[44:45], v[10:11], v[48:49]
	v_mov_b32_e32 v48, v46
	v_pk_fma_f32 v[44:45], v[6:7], v[52:53], v[44:45]
	v_mov_b32_e32 v49, v50
	v_pk_fma_f32 v[48:49], v[12:13], v[48:49], v[44:45]
	v_mov_b32_e32 v50, v47
	ds_read_b128 v[44:47], v2 offset:53408
	ds_read_b128 v[52:55], v2 offset:53424
	v_pk_fma_f32 v[48:49], v[8:9], v[50:51], v[48:49]
	v_fmac_f32_e32 v58, 0x3377d1cf, v56
	v_add_f32_e32 v48, v43, v48
	v_add_f32_e32 v50, v48, v49
	s_waitcnt lgkmcnt(0)
	v_mov_b32_e32 v49, v52
	v_mov_b32_e32 v52, v45
	v_mov_b32_e32 v48, v44
	v_pk_mul_f32 v[44:45], v[16:17], v[52:53]
	v_fmac_f32_e32 v58, 0x3f317217, v56
	v_pk_fma_f32 v[44:45], v[14:15], v[48:49], v[44:45]
	v_mov_b32_e32 v48, v46
	v_mov_b32_e32 v49, v54
	v_pk_fma_f32 v[44:45], v[22:23], v[48:49], v[44:45]
	v_mov_b32_e32 v54, v47
	v_pk_fma_f32 v[44:45], v[20:21], v[54:55], v[44:45]
	v_cmp_lt_f32_e64 s[0:1], |v56|, s63
	v_add_f32_e32 v44, v50, v44
	v_add_f32_e32 v45, v44, v45
	v_mul_f32_e64 v44, |v45|, s90
	v_exp_f32_e32 v44, v44
	v_cndmask_b32_e64 v46, v56, v58, s[0:1]
	v_cndmask_b32_e32 v47, 0, v240, vcc
	v_sub_f32_e32 v46, v46, v47
	v_add_f32_e32 v44, 1.0, v44
	v_cmp_gt_f32_e32 vcc, s74, v44
	v_min_f32_e32 v45, 0, v45
	s_nop 0
	v_cndmask_b32_e64 v47, 0, 32, vcc
	v_ldexp_f32 v44, v44, v47
	v_log_f32_e32 v58, v44
	v_sub_f32_e32 v44, v57, v46
	ds_read_b128 v[46:49], v2 offset:53440
	ds_read_b128 v[50:53], v2 offset:53456
	v_fmamk_f32 v44, v44, 0x3d800000, v3
	v_mul_f32_e32 v54, 0x3f317217, v58
	v_fma_f32 v59, v58, s75, -v54
	s_waitcnt lgkmcnt(1)
	v_mov_b32_e32 v54, v46
	s_waitcnt lgkmcnt(0)
; #define LAS __attribute__((address_space(3)))
; __device__ __forceinline__ float logsig(float x) { return fminf(x, 0.f) - __logf(1.f + __expf(-fabsf(x))); }
; __device__ __forceinline__ void gla_decay(LAS float* gd, LAS float* tot, int tid, const float (&w)[16], float bias, float (&bv)[16], float& blast) {
;     const int d = tid & 127, rg = tid >> 7;
;     float run = 0.f;
; #pragma unroll
;     for (int c = 0; c < 16; ++c) { const LAS f32x4* g4 = (const LAS f32x4*)(gd + (rg * 16 + c) * 16); float a = bias;
; #pragma unroll
;         for (int q = 0; q < 4; ++q) { const f32x4 g = g4[q]; a += g[0] * w[4 * q] + g[1] * w[4 * q + 1] + g[2] * w[4 * q + 2] + g[3] * w[4 * q + 3]; }
;         run += logsig(a) * 0.0625f; bv[c] = run; }
	v_mov_b32_e32 v55, v50
	v_mov_b32_e32 v50, v47
	v_pk_mul_f32 v[46:47], v[10:11], v[50:51]
	v_mov_b32_e32 v50, v48
	v_pk_fma_f32 v[46:47], v[6:7], v[54:55], v[46:47]
	v_mov_b32_e32 v51, v52
	v_pk_fma_f32 v[50:51], v[12:13], v[50:51], v[46:47]
	v_mov_b32_e32 v52, v49
	ds_read_b128 v[46:49], v2 offset:53472
	ds_read_b128 v[54:57], v2 offset:53488
	v_pk_fma_f32 v[50:51], v[8:9], v[52:53], v[50:51]
	v_fmac_f32_e32 v59, 0x3377d1cf, v58
	v_add_f32_e32 v50, v43, v50
	v_add_f32_e32 v52, v50, v51
	s_waitcnt lgkmcnt(0)
	v_mov_b32_e32 v51, v54
	v_mov_b32_e32 v54, v47
	v_mov_b32_e32 v50, v46
	v_pk_mul_f32 v[46:47], v[16:17], v[54:55]
	v_fmac_f32_e32 v59, 0x3f317217, v58
	v_pk_fma_f32 v[46:47], v[14:15], v[50:51], v[46:47]
	v_mov_b32_e32 v50, v48
	v_mov_b32_e32 v51, v56
	v_pk_fma_f32 v[46:47], v[22:23], v[50:51], v[46:47]
	v_mov_b32_e32 v56, v49
	v_pk_fma_f32 v[46:47], v[20:21], v[56:57], v[46:47]
	v_cmp_lt_f32_e64 s[0:1], |v58|, s63
	v_add_f32_e32 v46, v52, v46
	v_add_f32_e32 v46, v46, v47
	v_mul_f32_e64 v47, |v46|, s90
	v_exp_f32_e32 v47, v47
	v_cndmask_b32_e64 v48, v58, v59, s[0:1]
	v_cndmask_b32_e32 v49, 0, v240, vcc
	v_sub_f32_e32 v48, v48, v49
	v_add_f32_e32 v47, 1.0, v47
	v_cmp_gt_f32_e32 vcc, s74, v47
	v_sub_f32_e32 v45, v45, v48
	v_min_f32_e32 v59, 0, v46
	v_cndmask_b32_e64 v49, 0, 32, vcc
	v_ldexp_f32 v47, v47, v49
	v_log_f32_e32 v58, v47
	ds_read_b128 v[46:49], v2 offset:53504
	ds_read_b128 v[50:53], v2 offset:53520
	v_fmamk_f32 v45, v45, 0x3d800000, v44
	v_mul_f32_e32 v54, 0x3f317217, v58
	v_fma_f32 v60, v58, s75, -v54
	s_waitcnt lgkmcnt(0)
	v_mov_b32_e32 v55, v50
	v_mov_b32_e32 v50, v47
	v_mov_b32_e32 v54, v46
	v_pk_mul_f32 v[46:47], v[10:11], v[50:51]
	v_mov_b32_e32 v50, v48
	v_pk_fma_f32 v[46:47], v[6:7], v[54:55], v[46:47]
	v_mov_b32_e32 v51, v52
	v_pk_fma_f32 v[50:51], v[12:13], v[50:51], v[46:47]
	v_mov_b32_e32 v52, v49
	ds_read_b128 v[46:49], v2 offset:53536
	ds_read_b128 v[54:57], v2 offset:53552
	v_pk_fma_f32 v[50:51], v[8:9], v[52:53], v[50:51]
	v_fmac_f32_e32 v60, 0x3377d1cf, v58
	v_add_f32_e32 v50, v43, v50
	v_add_f32_e32 v52, v50, v51
	s_waitcnt lgkmcnt(0)
	v_mov_b32_e32 v51, v54
	v_mov_b32_e32 v54, v47
	v_mov_b32_e32 v50, v46
	v_pk_mul_f32 v[46:47], v[16:17], v[54:55]
	v_fmac_f32_e32 v60, 0x3f317217, v58
	v_pk_fma_f32 v[46:47], v[14:15], v[50:51], v[46:47]
	v_mov_b32_e32 v50, v48
	v_mov_b32_e32 v51, v56
	v_pk_fma_f32 v[46:47], v[22:23], v[50:51], v[46:47]
	v_mov_b32_e32 v56, v49
	v_pk_fma_f32 v[46:47], v[20:21], v[56:57], v[46:47]
	v_cmp_lt_f32_e64 s[0:1], |v58|, s63
	v_add_f32_e32 v46, v52, v46
	v_add_f32_e32 v47, v46, v47
	v_mul_f32_e64 v46, |v47|, s90
	v_exp_f32_e32 v46, v46
	v_cndmask_b32_e64 v48, v58, v60, s[0:1]
	v_cndmask_b32_e32 v49, 0, v240, vcc
	v_sub_f32_e32 v48, v48, v49
	v_add_f32_e32 v46, 1.0, v46
	v_cmp_gt_f32_e32 vcc, s74, v46
	v_min_f32_e32 v47, 0, v47
	s_nop 0
	v_cndmask_b32_e64 v49, 0, 32, vcc
	v_ldexp_f32 v46, v46, v49
	v_log_f32_e32 v60, v46
	v_sub_f32_e32 v46, v59, v48
	ds_read_b128 v[48:51], v2 offset:53568
	ds_read_b128 v[52:55], v2 offset:53584
	v_fmamk_f32 v46, v46, 0x3d800000, v45
	v_mul_f32_e32 v56, 0x3f317217, v60
	v_fma_f32 v61, v60, s75, -v56
	s_waitcnt lgkmcnt(1)
	v_mov_b32_e32 v56, v48
	s_waitcnt lgkmcnt(0)
	v_mov_b32_e32 v57, v52
	v_mov_b32_e32 v52, v49
	v_pk_mul_f32 v[48:49], v[10:11], v[52:53]
	v_mov_b32_e32 v52, v50
	v_pk_fma_f32 v[48:49], v[6:7], v[56:57], v[48:49]
	v_mov_b32_e32 v53, v54
	v_pk_fma_f32 v[52:53], v[12:13], v[52:53], v[48:49]
	v_mov_b32_e32 v54, v51
	ds_read_b128 v[48:51], v2 offset:53600
	ds_read_b128 v[56:59], v2 offset:53616
	v_pk_fma_f32 v[52:53], v[8:9], v[54:55], v[52:53]
	v_fmac_f32_e32 v61, 0x3377d1cf, v60
	v_add_f32_e32 v52, v43, v52
	v_add_f32_e32 v54, v52, v53
	s_waitcnt lgkmcnt(0)
	v_mov_b32_e32 v53, v56
	v_mov_b32_e32 v56, v49
	v_mov_b32_e32 v52, v48
	v_pk_mul_f32 v[48:49], v[16:17], v[56:57]
	v_fmac_f32_e32 v61, 0x3f317217, v60
	v_pk_fma_f32 v[48:49], v[14:15], v[52:53], v[48:49]
	v_mov_b32_e32 v52, v50
	v_mov_b32_e32 v53, v58
	v_pk_fma_f32 v[48:49], v[22:23], v[52:53], v[48:49]
	v_mov_b32_e32 v58, v51
	v_pk_fma_f32 v[48:49], v[20:21], v[58:59], v[48:49]
	v_cmp_lt_f32_e64 s[0:1], |v60|, s63
	v_add_f32_e32 v48, v54, v48
	v_add_f32_e32 v48, v48, v49
	v_mul_f32_e64 v49, |v48|, s90
	v_exp_f32_e32 v49, v49
	v_cndmask_b32_e64 v50, v60, v61, s[0:1]
	v_cndmask_b32_e32 v51, 0, v240, vcc
	v_sub_f32_e32 v50, v50, v51
	v_add_f32_e32 v49, 1.0, v49
	v_cmp_gt_f32_e32 vcc, s74, v49
	v_sub_f32_e32 v47, v47, v50
	v_min_f32_e32 v61, 0, v48
	v_cndmask_b32_e64 v51, 0, 32, vcc
	v_ldexp_f32 v49, v49, v51
	v_log_f32_e32 v60, v49
	ds_read_b128 v[48:51], v2 offset:53632
	ds_read_b128 v[52:55], v2 offset:53648
	v_fmamk_f32 v47, v47, 0x3d800000, v46
	v_mul_f32_e32 v56, 0x3f317217, v60
	v_fma_f32 v62, v60, s75, -v56
	s_waitcnt lgkmcnt(0)
	v_mov_b32_e32 v57, v52
	v_mov_b32_e32 v52, v49
	v_mov_b32_e32 v56, v48
	v_pk_mul_f32 v[48:49], v[10:11], v[52:53]
	v_mov_b32_e32 v52, v50
	v_pk_fma_f32 v[48:49], v[6:7], v[56:57], v[48:49]
	v_mov_b32_e32 v53, v54
	v_pk_fma_f32 v[52:53], v[12:13], v[52:53], v[48:49]
	v_mov_b32_e32 v54, v51
	ds_read_b128 v[48:51], v2 offset:53664
	ds_read_b128 v[56:59], v2 offset:53680
	v_pk_fma_f32 v[52:53], v[8:9], v[54:55], v[52:53]
	v_fmac_f32_e32 v62, 0x3377d1cf, v60
	v_add_f32_e32 v52, v43, v52
	v_add_f32_e32 v54, v52, v53
	s_waitcnt lgkmcnt(0)
; #define LAS __attribute__((address_space(3)))
; __device__ __forceinline__ float logsig(float x) { return fminf(x, 0.f) - __logf(1.f + __expf(-fabsf(x))); }
; __device__ __forceinline__ void gla_decay(LAS float* gd, LAS float* tot, int tid, const float (&w)[16], float bias, float (&bv)[16], float& blast) {
;     const int d = tid & 127, rg = tid >> 7;
;     float run = 0.f;
; #pragma unroll
;     for (int c = 0; c < 16; ++c) { const LAS f32x4* g4 = (const LAS f32x4*)(gd + (rg * 16 + c) * 16); float a = bias;
; #pragma unroll
;         for (int q = 0; q < 4; ++q) { const f32x4 g = g4[q]; a += g[0] * w[4 * q] + g[1] * w[4 * q + 1] + g[2] * w[4 * q + 2] + g[3] * w[4 * q + 3]; }
;         run += logsig(a) * 0.0625f; bv[c] = run; }
	v_mov_b32_e32 v53, v56
	v_mov_b32_e32 v56, v49
	v_mov_b32_e32 v52, v48
	v_pk_mul_f32 v[48:49], v[16:17], v[56:57]
	v_fmac_f32_e32 v62, 0x3f317217, v60
	v_pk_fma_f32 v[48:49], v[14:15], v[52:53], v[48:49]
	v_mov_b32_e32 v52, v50
	v_mov_b32_e32 v53, v58
	v_pk_fma_f32 v[48:49], v[22:23], v[52:53], v[48:49]
	v_mov_b32_e32 v58, v51
	v_pk_fma_f32 v[48:49], v[20:21], v[58:59], v[48:49]
	v_cmp_lt_f32_e64 s[0:1], |v60|, s63
	v_add_f32_e32 v48, v54, v48
	v_add_f32_e32 v49, v48, v49
	v_mul_f32_e64 v48, |v49|, s90
	v_exp_f32_e32 v48, v48
	v_cndmask_b32_e64 v50, v60, v62, s[0:1]
	v_cndmask_b32_e32 v51, 0, v240, vcc
	v_sub_f32_e32 v50, v50, v51
	v_add_f32_e32 v48, 1.0, v48
	v_cmp_gt_f32_e32 vcc, s74, v48
	v_min_f32_e32 v49, 0, v49
	s_nop 0
	v_cndmask_b32_e64 v51, 0, 32, vcc
	v_ldexp_f32 v48, v48, v51
	v_log_f32_e32 v62, v48
	v_sub_f32_e32 v48, v61, v50
	ds_read_b128 v[50:53], v2 offset:53696
	ds_read_b128 v[54:57], v2 offset:53712
	v_fmamk_f32 v48, v48, 0x3d800000, v47
	v_mul_f32_e32 v58, 0x3f317217, v62
	v_fma_f32 v63, v62, s75, -v58
	s_waitcnt lgkmcnt(1)
	v_mov_b32_e32 v58, v50
	s_waitcnt lgkmcnt(0)
	v_mov_b32_e32 v59, v54
	v_mov_b32_e32 v54, v51
	v_pk_mul_f32 v[50:51], v[10:11], v[54:55]
	v_mov_b32_e32 v54, v52
	v_pk_fma_f32 v[50:51], v[6:7], v[58:59], v[50:51]
	v_mov_b32_e32 v55, v56
	v_pk_fma_f32 v[54:55], v[12:13], v[54:55], v[50:51]
	v_mov_b32_e32 v56, v53
	ds_read_b128 v[50:53], v2 offset:53728
	ds_read_b128 v[58:61], v2 offset:53744
	v_pk_fma_f32 v[54:55], v[8:9], v[56:57], v[54:55]
	v_fmac_f32_e32 v63, 0x3377d1cf, v62
	v_add_f32_e32 v54, v43, v54
	v_add_f32_e32 v56, v54, v55
	s_waitcnt lgkmcnt(0)
	v_mov_b32_e32 v55, v58
	v_mov_b32_e32 v58, v51
	v_mov_b32_e32 v54, v50
	v_pk_mul_f32 v[50:51], v[16:17], v[58:59]
	v_fmac_f32_e32 v63, 0x3f317217, v62
	v_pk_fma_f32 v[50:51], v[14:15], v[54:55], v[50:51]
	v_mov_b32_e32 v54, v52
	v_mov_b32_e32 v55, v60
	v_pk_fma_f32 v[50:51], v[22:23], v[54:55], v[50:51]
	v_mov_b32_e32 v60, v53
	v_pk_fma_f32 v[50:51], v[20:21], v[60:61], v[50:51]
	v_cmp_lt_f32_e64 s[0:1], |v62|, s63
	v_add_f32_e32 v50, v56, v50
	v_add_f32_e32 v50, v50, v51
	v_mul_f32_e64 v51, |v50|, s90
	v_exp_f32_e32 v51, v51
	v_cndmask_b32_e64 v52, v62, v63, s[0:1]
	v_cndmask_b32_e32 v53, 0, v240, vcc
	v_sub_f32_e32 v52, v52, v53
	v_add_f32_e32 v51, 1.0, v51
	v_cmp_gt_f32_e32 vcc, s74, v51
	v_sub_f32_e32 v49, v49, v52
	v_min_f32_e32 v63, 0, v50
	v_cndmask_b32_e64 v53, 0, 32, vcc
	v_ldexp_f32 v51, v51, v53
	v_log_f32_e32 v62, v51
	ds_read_b128 v[50:53], v2 offset:53760
	ds_read_b128 v[54:57], v2 offset:53776
	v_fmamk_f32 v49, v49, 0x3d800000, v48
	v_mul_f32_e32 v58, 0x3f317217, v62
	v_fma_f32 v64, v62, s75, -v58
	s_waitcnt lgkmcnt(0)
	v_mov_b32_e32 v59, v54
	v_mov_b32_e32 v54, v51
	v_mov_b32_e32 v58, v50
	v_pk_mul_f32 v[50:51], v[10:11], v[54:55]
	v_mov_b32_e32 v54, v52
	v_pk_fma_f32 v[50:51], v[6:7], v[58:59], v[50:51]
	v_mov_b32_e32 v55, v56
	v_pk_fma_f32 v[54:55], v[12:13], v[54:55], v[50:51]
	v_mov_b32_e32 v56, v53
	ds_read_b128 v[50:53], v2 offset:53792
	ds_read_b128 v[58:61], v2 offset:53808
	v_pk_fma_f32 v[54:55], v[8:9], v[56:57], v[54:55]
	v_fmac_f32_e32 v64, 0x3377d1cf, v62
	v_add_f32_e32 v54, v43, v54
	v_add_f32_e32 v56, v54, v55
	s_waitcnt lgkmcnt(0)
	v_mov_b32_e32 v55, v58
	v_mov_b32_e32 v58, v51
	v_mov_b32_e32 v54, v50
	v_pk_mul_f32 v[50:51], v[16:17], v[58:59]
	v_fmac_f32_e32 v64, 0x3f317217, v62
	v_pk_fma_f32 v[50:51], v[14:15], v[54:55], v[50:51]
	v_mov_b32_e32 v54, v52
	v_mov_b32_e32 v55, v60
	v_pk_fma_f32 v[50:51], v[22:23], v[54:55], v[50:51]
	v_mov_b32_e32 v60, v53
	v_pk_fma_f32 v[50:51], v[20:21], v[60:61], v[50:51]
	v_cmp_lt_f32_e64 s[0:1], |v62|, s63
	v_add_f32_e32 v50, v56, v50
	v_add_f32_e32 v51, v50, v51
	v_mul_f32_e64 v50, |v51|, s90
	v_exp_f32_e32 v50, v50
	v_cndmask_b32_e64 v52, v62, v64, s[0:1]
	v_cndmask_b32_e32 v53, 0, v240, vcc
	v_sub_f32_e32 v52, v52, v53
	v_add_f32_e32 v50, 1.0, v50
	v_cmp_gt_f32_e32 vcc, s74, v50
	v_min_f32_e32 v51, 0, v51
	s_nop 0
	v_cndmask_b32_e64 v53, 0, 32, vcc
	v_ldexp_f32 v50, v50, v53
	v_log_f32_e32 v64, v50
	v_sub_f32_e32 v50, v63, v52
	ds_read_b128 v[52:55], v2 offset:53824
	ds_read_b128 v[56:59], v2 offset:53840
	v_fmamk_f32 v50, v50, 0x3d800000, v49
	v_mul_f32_e32 v60, 0x3f317217, v64
	v_fma_f32 v65, v64, s75, -v60
	s_waitcnt lgkmcnt(1)
	v_mov_b32_e32 v60, v52
	s_waitcnt lgkmcnt(0)
	v_mov_b32_e32 v61, v56
	v_mov_b32_e32 v56, v53
	v_pk_mul_f32 v[52:53], v[10:11], v[56:57]
	v_mov_b32_e32 v56, v54
	v_pk_fma_f32 v[52:53], v[6:7], v[60:61], v[52:53]
	v_mov_b32_e32 v57, v58
	v_pk_fma_f32 v[56:57], v[12:13], v[56:57], v[52:53]
	v_mov_b32_e32 v58, v55
	ds_read_b128 v[52:55], v2 offset:53856
	ds_read_b128 v[60:63], v2 offset:53872
	v_pk_fma_f32 v[56:57], v[8:9], v[58:59], v[56:57]
	v_fmac_f32_e32 v65, 0x3377d1cf, v64
	v_add_f32_e32 v56, v43, v56
	v_add_f32_e32 v58, v56, v57
	s_waitcnt lgkmcnt(0)
	v_mov_b32_e32 v57, v60
	v_mov_b32_e32 v60, v53
	v_mov_b32_e32 v56, v52
	v_pk_mul_f32 v[52:53], v[16:17], v[60:61]
	v_fmac_f32_e32 v65, 0x3f317217, v64
	v_pk_fma_f32 v[52:53], v[14:15], v[56:57], v[52:53]
	v_mov_b32_e32 v56, v54
	v_mov_b32_e32 v57, v62
	v_pk_fma_f32 v[52:53], v[22:23], v[56:57], v[52:53]
	v_mov_b32_e32 v62, v55
	v_pk_fma_f32 v[52:53], v[20:21], v[62:63], v[52:53]
	v_cmp_lt_f32_e64 s[0:1], |v64|, s63
	v_add_f32_e32 v52, v58, v52
	v_add_f32_e32 v52, v52, v53
	v_mul_f32_e64 v53, |v52|, s90
	v_exp_f32_e32 v53, v53
	v_cndmask_b32_e64 v54, v64, v65, s[0:1]
	v_cndmask_b32_e32 v55, 0, v240, vcc
	v_sub_f32_e32 v54, v54, v55
	v_add_f32_e32 v53, 1.0, v53
	v_cmp_gt_f32_e32 vcc, s74, v53
	v_sub_f32_e32 v51, v51, v54
	v_min_f32_e32 v65, 0, v52
	v_cndmask_b32_e64 v55, 0, 32, vcc
	v_ldexp_f32 v53, v53, v55
	v_log_f32_e32 v64, v53
	ds_read_b128 v[52:55], v2 offset:53888
	ds_read_b128 v[56:59], v2 offset:53904
	v_fmamk_f32 v51, v51, 0x3d800000, v50
	v_mul_f32_e32 v60, 0x3f317217, v64
	v_fma_f32 v66, v64, s75, -v60
	s_waitcnt lgkmcnt(0)
; #define LAS __attribute__((address_space(3)))
; __device__ __forceinline__ float logsig(float x) { return fminf(x, 0.f) - __logf(1.f + __expf(-fabsf(x))); }
; __device__ __forceinline__ void gla_decay(LAS float* gd, LAS float* tot, int tid, const float (&w)[16], float bias, float (&bv)[16], float& blast) {
;     ...
;     for (int c = 0; c < 16; ++c) { const LAS f32x4* g4 = (const LAS f32x4*)(gd + (rg * 16 + c) * 16); float a = bias;
; #pragma unroll
;         for (int q = 0; q < 4; ++q) { const f32x4 g = g4[q]; a += g[0] * w[4 * q] + g[1] * w[4 * q + 1] + g[2] * w[4 * q + 2] + g[3] * w[4 * q + 3]; }
;         run += logsig(a) * 0.0625f; bv[c] = run; }
	v_mov_b32_e32 v61, v56
	v_mov_b32_e32 v56, v53
	v_mov_b32_e32 v60, v52
	v_pk_mul_f32 v[52:53], v[10:11], v[56:57]
	v_mov_b32_e32 v56, v54
	v_pk_fma_f32 v[52:53], v[6:7], v[60:61], v[52:53]
	v_mov_b32_e32 v57, v58
	v_pk_fma_f32 v[56:57], v[12:13], v[56:57], v[52:53]
	v_mov_b32_e32 v58, v55
	ds_read_b128 v[52:55], v2 offset:53920
	ds_read_b128 v[60:63], v2 offset:53936
	v_pk_fma_f32 v[56:57], v[8:9], v[58:59], v[56:57]
	v_fmac_f32_e32 v66, 0x3377d1cf, v64
	v_add_f32_e32 v56, v43, v56
	v_add_f32_e32 v58, v56, v57
	s_waitcnt lgkmcnt(0)
	v_mov_b32_e32 v57, v60
	v_mov_b32_e32 v60, v53
	v_mov_b32_e32 v56, v52
	v_pk_mul_f32 v[52:53], v[16:17], v[60:61]
	v_fmac_f32_e32 v66, 0x3f317217, v64
	v_pk_fma_f32 v[52:53], v[14:15], v[56:57], v[52:53]
	v_mov_b32_e32 v56, v54
	v_mov_b32_e32 v57, v62
	v_pk_fma_f32 v[52:53], v[22:23], v[56:57], v[52:53]
	v_mov_b32_e32 v62, v55
	v_pk_fma_f32 v[52:53], v[20:21], v[62:63], v[52:53]
	v_cmp_lt_f32_e64 s[0:1], |v64|, s63
	v_add_f32_e32 v52, v58, v52
	v_add_f32_e32 v52, v52, v53
	v_mul_f32_e64 v53, |v52|, s90
	v_exp_f32_e32 v53, v53
	v_cndmask_b32_e64 v54, v64, v66, s[0:1]
	v_cndmask_b32_e32 v55, 0, v240, vcc
	v_sub_f32_e32 v54, v54, v55
	v_add_f32_e32 v53, 1.0, v53
	v_cmp_gt_f32_e32 vcc, s74, v53
	v_min_f32_e32 v66, 0, v52
	s_nop 0
	v_cndmask_b32_e64 v55, 0, 32, vcc
	v_ldexp_f32 v53, v53, v55
	v_log_f32_e32 v64, v53
	v_sub_f32_e32 v53, v65, v54
	v_fmamk_f32 v65, v53, 0x3d800000, v51
	ds_read_b128 v[52:55], v2 offset:53952
	ds_read_b128 v[56:59], v2 offset:53968
	v_mul_f32_e32 v60, 0x3f317217, v64
	v_fma_f32 v67, v64, s75, -v60
	v_fmac_f32_e32 v67, 0x3377d1cf, v64
	s_waitcnt lgkmcnt(1)
	v_mov_b32_e32 v60, v52
	s_waitcnt lgkmcnt(0)
	v_mov_b32_e32 v61, v56
	v_mov_b32_e32 v56, v53
	v_pk_mul_f32 v[52:53], v[10:11], v[56:57]
	v_mov_b32_e32 v56, v54
	v_pk_fma_f32 v[52:53], v[6:7], v[60:61], v[52:53]
	v_mov_b32_e32 v57, v58
	v_pk_fma_f32 v[56:57], v[12:13], v[56:57], v[52:53]
	v_mov_b32_e32 v58, v55
	ds_read_b128 v[52:55], v2 offset:53984
	ds_read_b128 v[60:63], v2 offset:54000
	v_pk_fma_f32 v[56:57], v[8:9], v[58:59], v[56:57]
	v_fmac_f32_e32 v67, 0x3f317217, v64
	v_add_f32_e32 v56, v43, v56
	v_add_f32_e32 v58, v56, v57
	s_waitcnt lgkmcnt(0)
	v_mov_b32_e32 v57, v60
	v_mov_b32_e32 v60, v53
	v_mov_b32_e32 v56, v52
	v_pk_mul_f32 v[52:53], v[16:17], v[60:61]
	v_cmp_lt_f32_e64 s[0:1], |v64|, s63
	v_pk_fma_f32 v[52:53], v[14:15], v[56:57], v[52:53]
	v_mov_b32_e32 v56, v54
	v_mov_b32_e32 v57, v62
	v_pk_fma_f32 v[52:53], v[22:23], v[56:57], v[52:53]
	v_mov_b32_e32 v62, v55
	v_pk_fma_f32 v[52:53], v[20:21], v[62:63], v[52:53]
	v_cndmask_b32_e64 v54, v64, v67, s[0:1]
	v_add_f32_e32 v52, v58, v52
	v_add_f32_e32 v52, v52, v53
	v_mul_f32_e64 v53, |v52|, s90
	v_exp_f32_e32 v53, v53
	v_cndmask_b32_e32 v55, 0, v240, vcc
	v_sub_f32_e32 v54, v54, v55
	v_min_f32_e32 v67, 0, v52
	v_add_f32_e32 v53, 1.0, v53
	v_cmp_gt_f32_e32 vcc, s74, v53
	s_nop 1
	v_cndmask_b32_e64 v55, 0, 32, vcc
	v_ldexp_f32 v53, v53, v55
	v_log_f32_e32 v64, v53
	v_sub_f32_e32 v53, v66, v54
	v_fmamk_f32 v66, v53, 0x3d800000, v65
	ds_read_b128 v[52:55], v2 offset:54016
	ds_read_b128 v[56:59], v2 offset:54032
	v_mul_f32_e32 v60, 0x3f317217, v64
	v_fma_f32 v68, v64, s75, -v60
	v_fmac_f32_e32 v68, 0x3377d1cf, v64
	s_waitcnt lgkmcnt(1)
	v_mov_b32_e32 v60, v52
	s_waitcnt lgkmcnt(0)
	v_mov_b32_e32 v61, v56
	v_mov_b32_e32 v56, v53
	v_pk_mul_f32 v[52:53], v[10:11], v[56:57]
	v_mov_b32_e32 v56, v54
	v_pk_fma_f32 v[52:53], v[6:7], v[60:61], v[52:53]
	v_mov_b32_e32 v57, v58
	v_pk_fma_f32 v[56:57], v[12:13], v[56:57], v[52:53]
	v_mov_b32_e32 v58, v55
	ds_read_b128 v[52:55], v2 offset:54048
	ds_read_b128 v[60:63], v2 offset:54064
	v_pk_fma_f32 v[56:57], v[8:9], v[58:59], v[56:57]
	v_fmac_f32_e32 v68, 0x3f317217, v64
	v_add_f32_e32 v56, v43, v56
	v_add_f32_e32 v58, v56, v57
	s_waitcnt lgkmcnt(0)
	v_mov_b32_e32 v57, v60
	v_mov_b32_e32 v60, v53
	v_mov_b32_e32 v56, v52
	v_pk_mul_f32 v[52:53], v[16:17], v[60:61]
	v_cmp_lt_f32_e64 s[0:1], |v64|, s63
	v_pk_fma_f32 v[52:53], v[14:15], v[56:57], v[52:53]
	v_mov_b32_e32 v56, v54
	v_mov_b32_e32 v57, v62
	v_pk_fma_f32 v[52:53], v[22:23], v[56:57], v[52:53]
	v_mov_b32_e32 v62, v55
	v_pk_fma_f32 v[52:53], v[20:21], v[62:63], v[52:53]
	v_cndmask_b32_e64 v54, v64, v68, s[0:1]
	v_add_f32_e32 v52, v58, v52
	v_add_f32_e32 v52, v52, v53
	v_mul_f32_e64 v53, |v52|, s90
	v_exp_f32_e32 v53, v53
	v_cndmask_b32_e32 v55, 0, v240, vcc
	v_sub_f32_e32 v54, v54, v55
	v_min_f32_e32 v68, 0, v52
	v_add_f32_e32 v53, 1.0, v53
	v_cmp_gt_f32_e32 vcc, s74, v53
	s_nop 1
	v_cndmask_b32_e64 v55, 0, 32, vcc
	v_ldexp_f32 v53, v53, v55
	v_log_f32_e32 v64, v53
	v_sub_f32_e32 v53, v67, v54
	v_fmamk_f32 v67, v53, 0x3d800000, v66
	ds_read_b128 v[52:55], v2 offset:54080
	ds_read_b128 v[56:59], v2 offset:54096
	v_mul_f32_e32 v60, 0x3f317217, v64
	v_fma_f32 v69, v64, s75, -v60
	v_fmac_f32_e32 v69, 0x3377d1cf, v64
	s_waitcnt lgkmcnt(1)
	v_mov_b32_e32 v60, v52
	s_waitcnt lgkmcnt(0)
	v_mov_b32_e32 v61, v56
	v_mov_b32_e32 v56, v53
	v_pk_mul_f32 v[52:53], v[10:11], v[56:57]
	v_mov_b32_e32 v56, v54
	v_pk_fma_f32 v[52:53], v[6:7], v[60:61], v[52:53]
	v_mov_b32_e32 v57, v58
	v_pk_fma_f32 v[56:57], v[12:13], v[56:57], v[52:53]
	v_mov_b32_e32 v58, v55
	ds_read_b128 v[52:55], v2 offset:54112
	ds_read_b128 v[60:63], v2 offset:54128
	v_pk_fma_f32 v[56:57], v[8:9], v[58:59], v[56:57]
	v_fmac_f32_e32 v69, 0x3f317217, v64
	v_add_f32_e32 v56, v43, v56
	v_add_f32_e32 v58, v56, v57
	s_waitcnt lgkmcnt(0)
; #define LAS __attribute__((address_space(3)))
; __device__ __forceinline__ float logsig(float x) { return fminf(x, 0.f) - __logf(1.f + __expf(-fabsf(x))); }
; __device__ __forceinline__ void gla_decay(LAS float* gd, LAS float* tot, int tid, const float (&w)[16], float bias, float (&bv)[16], float& blast) {
;     ...
;     for (int c = 0; c < 16; ++c) { const LAS f32x4* g4 = (const LAS f32x4*)(gd + (rg * 16 + c) * 16); float a = bias;
; #pragma unroll
;         for (int q = 0; q < 4; ++q) { const f32x4 g = g4[q]; a += g[0] * w[4 * q] + g[1] * w[4 * q + 1] + g[2] * w[4 * q + 2] + g[3] * w[4 * q + 3]; }
;         run += logsig(a) * 0.0625f; bv[c] = run; }
;     tot[rg * 128 + d] = run;
;     __syncthreads();
	v_mov_b32_e32 v57, v60
	v_mov_b32_e32 v60, v53
	v_mov_b32_e32 v56, v52
	v_pk_mul_f32 v[52:53], v[16:17], v[60:61]
	v_cmp_lt_f32_e64 s[0:1], |v64|, s63
	v_pk_fma_f32 v[52:53], v[14:15], v[56:57], v[52:53]
	v_mov_b32_e32 v56, v54
	v_mov_b32_e32 v57, v62
	v_pk_fma_f32 v[52:53], v[22:23], v[56:57], v[52:53]
	v_mov_b32_e32 v62, v55
	v_pk_fma_f32 v[52:53], v[20:21], v[62:63], v[52:53]
	v_cndmask_b32_e64 v54, v64, v69, s[0:1]
	v_add_f32_e32 v52, v58, v52
	v_add_f32_e32 v52, v52, v53
	v_mul_f32_e64 v53, |v52|, s90
	v_exp_f32_e32 v53, v53
	v_cndmask_b32_e32 v55, 0, v240, vcc
	v_sub_f32_e32 v54, v54, v55
	v_min_f32_e32 v69, 0, v52
	v_add_f32_e32 v53, 1.0, v53
	v_cmp_gt_f32_e32 vcc, s74, v53
	s_nop 1
	v_cndmask_b32_e64 v55, 0, 32, vcc
	v_ldexp_f32 v53, v53, v55
	v_log_f32_e32 v64, v53
	v_sub_f32_e32 v53, v68, v54
	v_fmamk_f32 v68, v53, 0x3d800000, v67
	ds_read_b128 v[52:55], v2 offset:54144
	ds_read_b128 v[56:59], v2 offset:54160
	v_mul_f32_e32 v60, 0x3f317217, v64
	v_fma_f32 v70, v64, s75, -v60
	v_fmac_f32_e32 v70, 0x3377d1cf, v64
	s_waitcnt lgkmcnt(1)
	v_mov_b32_e32 v60, v52
	s_waitcnt lgkmcnt(0)
	v_mov_b32_e32 v61, v56
	v_mov_b32_e32 v56, v53
	v_pk_mul_f32 v[52:53], v[10:11], v[56:57]
	v_mov_b32_e32 v56, v54
	v_pk_fma_f32 v[52:53], v[6:7], v[60:61], v[52:53]
	v_mov_b32_e32 v57, v58
	v_pk_fma_f32 v[56:57], v[12:13], v[56:57], v[52:53]
	v_mov_b32_e32 v58, v55
	ds_read_b128 v[52:55], v2 offset:54176
	ds_read_b128 v[60:63], v2 offset:54192
	v_pk_fma_f32 v[56:57], v[8:9], v[58:59], v[56:57]
	v_fmac_f32_e32 v70, 0x3f317217, v64
	v_add_f32_e32 v56, v43, v56
	v_add_f32_e32 v58, v56, v57
	s_waitcnt lgkmcnt(0)
	v_mov_b32_e32 v57, v60
	v_mov_b32_e32 v60, v53
	v_mov_b32_e32 v56, v52
	v_pk_mul_f32 v[52:53], v[16:17], v[60:61]
	v_cmp_lt_f32_e64 s[0:1], |v64|, s63
	v_pk_fma_f32 v[52:53], v[14:15], v[56:57], v[52:53]
	v_mov_b32_e32 v56, v54
	v_mov_b32_e32 v57, v62
	v_pk_fma_f32 v[52:53], v[22:23], v[56:57], v[52:53]
	v_mov_b32_e32 v62, v55
	v_pk_fma_f32 v[52:53], v[20:21], v[62:63], v[52:53]
	v_cndmask_b32_e64 v54, v64, v70, s[0:1]
	v_add_f32_e32 v52, v58, v52
	v_add_f32_e32 v52, v52, v53
	v_mul_f32_e64 v53, |v52|, s90
	v_exp_f32_e32 v53, v53
	v_cndmask_b32_e32 v55, 0, v240, vcc
	v_sub_f32_e32 v54, v54, v55
	v_min_f32_e32 v64, 0, v52
	v_add_f32_e32 v53, 1.0, v53
	v_cmp_gt_f32_e32 vcc, s74, v53
	s_nop 1
	v_cndmask_b32_e64 v55, 0, 32, vcc
	v_ldexp_f32 v53, v53, v55
	v_log_f32_e32 v62, v53
	v_sub_f32_e32 v53, v69, v54
	v_fmamk_f32 v63, v53, 0x3d800000, v68
	ds_read_b128 v[52:55], v2 offset:54208
	ds_read_b128 v[56:59], v2 offset:54224
	v_mul_f32_e32 v60, 0x3f317217, v62
	v_fma_f32 v69, v62, s75, -v60
	v_fmac_f32_e32 v69, 0x3377d1cf, v62
	s_waitcnt lgkmcnt(1)
	v_mov_b32_e32 v60, v52
	s_waitcnt lgkmcnt(0)
	v_mov_b32_e32 v61, v56
	v_mov_b32_e32 v56, v53
	v_pk_mul_f32 v[10:11], v[10:11], v[56:57]
	v_fmac_f32_e32 v69, 0x3f317217, v62
	v_pk_fma_f32 v[6:7], v[6:7], v[60:61], v[10:11]
	v_mov_b32_e32 v10, v54
	v_mov_b32_e32 v11, v58
	v_pk_fma_f32 v[6:7], v[12:13], v[10:11], v[6:7]
	v_mov_b32_e32 v58, v55
	ds_read_b128 v[10:13], v2 offset:54240
	ds_read_b128 v[52:55], v2 offset:54256
	v_pk_fma_f32 v[6:7], v[8:9], v[58:59], v[6:7]
	v_cmp_lt_f32_e64 s[0:1], |v62|, s63
	v_add_f32_e32 v2, v43, v6
	v_add_f32_e32 v2, v2, v7
	s_waitcnt lgkmcnt(0)
	v_mov_b32_e32 v7, v52
	v_mov_b32_e32 v52, v11
	v_mov_b32_e32 v6, v10
	v_pk_mul_f32 v[8:9], v[16:17], v[52:53]
	s_nop 0
	v_pk_fma_f32 v[6:7], v[14:15], v[6:7], v[8:9]
	v_mov_b32_e32 v8, v12
	v_mov_b32_e32 v9, v54
	v_pk_fma_f32 v[6:7], v[22:23], v[8:9], v[6:7]
	v_mov_b32_e32 v54, v13
	v_pk_fma_f32 v[6:7], v[20:21], v[54:55], v[6:7]
	v_cndmask_b32_e32 v8, 0, v240, vcc
	v_add_f32_e32 v2, v2, v6
	v_add_f32_e32 v2, v2, v7
	v_mul_f32_e64 v6, |v2|, s90
	v_exp_f32_e32 v6, v6
	v_cndmask_b32_e64 v7, v62, v69, s[0:1]
	v_sub_f32_e32 v7, v7, v8
	v_sub_f32_e32 v7, v64, v7
	v_add_f32_e32 v6, 1.0, v6
	v_cmp_gt_f32_e32 vcc, s74, v6
	v_fmamk_f32 v16, v7, 0x3d800000, v63
	v_min_f32_e32 v2, 0, v2
	v_cndmask_b32_e64 v8, 0, 32, vcc
	v_ldexp_f32 v6, v6, v8
	v_log_f32_e32 v6, v6
	v_lshl_add_u32 v20, v19, 2, 0
	v_mul_f32_e32 v7, 0x3f317217, v6
	v_fma_f32 v7, v6, s75, -v7
	v_fmac_f32_e32 v7, 0x3377d1cf, v6
	v_fmac_f32_e32 v7, 0x3f317217, v6
	v_cmp_lt_f32_e64 s[0:1], |v6|, s63
	s_nop 1
	v_cndmask_b32_e64 v6, v6, v7, s[0:1]
	v_cndmask_b32_e32 v7, 0, v240, vcc
	v_sub_f32_e32 v6, v6, v7
	v_sub_f32_e32 v2, v2, v6
	v_lshl_add_u32 v6, v18, 2, 0
	v_fmamk_f32 v7, v2, 0x3d800000, v16
	ds_write_b32 v6, v7 offset:57344
	s_waitcnt lgkmcnt(0)
	s_barrier
; #define LAS __attribute__((address_space(3)))
; __device__ __forceinline__ unsigned pk2(float lo, float hi) { const f32x2c_t v = {lo, hi}; return __builtin_bit_cast(unsigned, __builtin_convertvector(v, bf16x2c_t)); }
; __device__ __forceinline__ float bf2f(bf16 v) { return __uint_as_float(((unsigned)v) << 16); }
; __device__ __forceinline__ void gla_decay(LAS float* gd, LAS float* tot, int tid, const float (&w)[16], float bias, float (&bv)[16], float& blast) {
;     ...
;     tot[rg * 128 + d] = run;
;     __syncthreads();
;     const float t0 = tot[d], t1 = tot[128 + d], t2 = tot[256 + d], t3 = tot[384 + d];
;     const float off = (rg > 0 ? t0 : 0.f) + (rg > 1 ? t1 : 0.f) + (rg > 2 ? t2 : 0.f);
;     blast = (t0 + t1) + (t2 + t3);
; #pragma unroll
;     for (int c = 0; c < 16; ++c) bv[c] += off;
; __device__ __forceinline__ void gla_step1(const Params& P, int l, LAS unsigned char* lds, int item, int next_item, int tid, G1Pre& R) {
;     ...
;     { unsigned pk[8];
; #pragma unroll
;       for (int c = 0; c < 16; c += 2) { const float k0 = bf2f(kraw[c]) * __expf(blast - bv[c]), k1 = bf2f(kraw[c + 1]) * __expf(blast - bv[c + 1]); pk[c >> 1] = pk2(k0, k1); }
;       *(LAS v4u*)(KD + d * 144 + rg * 32) = (v4u){pk[0], pk[1], pk[2], pk[3]}; *(LAS v4u*)(KD + d * 144 + rg * 32 + 16) = (v4u){pk[4], pk[5], pk[6], pk[7]}; }
;     if (rg == 0) ((float*)(P.ws + WS_DV))[(size_t)item * 128 + d] = __expf(blast);
	ds_read2st64_b32 v[8:9], v20 offset0:224 offset1:226
	ds_read2st64_b32 v[10:11], v20 offset0:228 offset1:230
	v_cmp_lt_i32_e32 vcc, 0, v25
	s_movk_i32 s0, 0x80
	s_waitcnt lgkmcnt(1)
	v_mov_b32_e32 v12, v8
	v_cndmask_b32_e32 v2, 0, v8, vcc
	v_cmp_lt_i32_e32 vcc, 1, v25
	v_mov_b32_e32 v14, v9
	s_nop 0
	v_cndmask_b32_e32 v6, 0, v9, vcc
	v_cmp_lt_i32_e32 vcc, 2, v25
	v_add_f32_e32 v13, v2, v6
	s_waitcnt lgkmcnt(0)
	v_add_f32_e32 v6, v10, v11
	v_cndmask_b32_e32 v15, 0, v10, vcc
	v_pk_add_f32 v[8:9], v[12:13], v[14:15]
	v_cmp_gt_u32_e32 vcc, s0, v18
	v_add_f32_e32 v10, v3, v9
	v_add_f32_e32 v11, v44, v9
	v_pk_add_f32 v[2:3], v[8:9], v[6:7]
	v_add_f32_e32 v12, v45, v9
	v_sub_f32_e32 v6, v2, v10
	v_sub_f32_e32 v7, v2, v11
	v_mul_f32_e32 v6, 0x3fb8aa3b, v6
	v_mul_f32_e32 v7, 0x3fb8aa3b, v7
	v_exp_f32_e32 v6, v6
	v_exp_f32_e32 v7, v7
	v_add_f32_e32 v13, v46, v9
	v_add_f32_e32 v14, v47, v9
	v_add_f32_e32 v15, v48, v9
	v_add_f32_e32 v17, v49, v9
	v_add_f32_e32 v21, v50, v9
	v_add_f32_e32 v22, v51, v9
	v_add_f32_e32 v23, v65, v9
	v_add_f32_e32 v43, v66, v9
	v_add_f32_e32 v44, v67, v9
	v_add_f32_e32 v45, v68, v9
	v_add_f32_e32 v46, v63, v9
	v_add_f32_e32 v16, v9, v16
	s_waitcnt vmcnt(0)
	v_lshlrev_b32_e32 v9, 16, v37
	v_lshlrev_b32_e32 v8, 16, v31
	v_pk_mul_f32 v[6:7], v[6:7], v[8:9]
	v_sub_f32_e32 v8, v2, v12
	v_sub_f32_e32 v9, v2, v13
	v_mul_f32_e32 v8, 0x3fb8aa3b, v8
	v_mul_f32_e32 v9, 0x3fb8aa3b, v9
	v_exp_f32_e32 v8, v8
	v_exp_f32_e32 v9, v9
	v_cvt_pk_bf16_f32 v6, v6, v7
	v_sub_f32_e32 v7, v2, v14
	v_lshlrev_b32_e32 v11, 16, v35
	v_lshlrev_b32_e32 v10, 16, v29
	v_mul_f32_e32 v7, 0x3fb8aa3b, v7
	v_pk_mul_f32 v[8:9], v[8:9], v[10:11]
	v_exp_f32_e32 v10, v7
	v_sub_f32_e32 v7, v2, v15
	v_mul_f32_e32 v7, 0x3fb8aa3b, v7
	v_exp_f32_e32 v11, v7
	v_cvt_pk_bf16_f32 v7, v8, v9
	v_lshlrev_b32_e32 v9, 16, v33
	v_lshlrev_b32_e32 v8, 16, v28
	v_pk_mul_f32 v[8:9], v[10:11], v[8:9]
	v_sub_f32_e32 v10, v2, v17
	v_sub_f32_e32 v11, v2, v21
	v_mul_f32_e32 v10, 0x3fb8aa3b, v10
	v_mul_f32_e32 v11, 0x3fb8aa3b, v11
	v_exp_f32_e32 v10, v10
	v_exp_f32_e32 v11, v11
	v_cvt_pk_bf16_f32 v8, v8, v9
	v_sub_f32_e32 v9, v2, v22
	v_lshlrev_b32_e32 v13, 16, v41
	v_lshlrev_b32_e32 v12, 16, v27
	v_mul_f32_e32 v9, 0x3fb8aa3b, v9
	v_pk_mul_f32 v[10:11], v[10:11], v[12:13]
	v_exp_f32_e32 v12, v9
	v_sub_f32_e32 v9, v2, v23
	v_mul_f32_e32 v9, 0x3fb8aa3b, v9
	v_exp_f32_e32 v13, v9
	v_cvt_pk_bf16_f32 v9, v10, v11
	v_lshlrev_b32_e32 v11, 16, v40
	v_lshlrev_b32_e32 v10, 16, v36
	v_pk_mul_f32 v[10:11], v[12:13], v[10:11]
	v_sub_f32_e32 v12, v2, v43
	v_sub_f32_e32 v13, v2, v44
	v_mul_f32_e32 v12, 0x3fb8aa3b, v12
	v_mul_f32_e32 v13, 0x3fb8aa3b, v13
	v_exp_f32_e32 v12, v12
	v_exp_f32_e32 v13, v13
	v_cvt_pk_bf16_f32 v10, v10, v11
	v_sub_f32_e32 v11, v2, v45
	v_lshlrev_b32_e32 v15, 16, v39
	v_lshlrev_b32_e32 v14, 16, v34
	v_mul_f32_e32 v11, 0x3fb8aa3b, v11
	v_pk_mul_f32 v[12:13], v[12:13], v[14:15]
	v_exp_f32_e32 v14, v11
	v_sub_f32_e32 v11, v2, v46
	v_mul_f32_e32 v11, 0x3fb8aa3b, v11
	v_exp_f32_e32 v15, v11
	v_cvt_pk_bf16_f32 v11, v12, v13
	v_lshlrev_b32_e32 v13, 16, v38
	v_lshlrev_b32_e32 v12, 16, v32
	v_pk_mul_f32 v[12:13], v[14:15], v[12:13]
	v_sub_f32_e32 v14, v2, v16
	v_sub_f32_e32 v3, v2, v3
	v_mul_f32_e32 v14, 0x3fb8aa3b, v14
	v_mul_f32_e32 v3, 0x3fb8aa3b, v3
	v_exp_f32_e32 v14, v14
	v_exp_f32_e32 v15, v3
	v_lshlrev_b32_e32 v17, 16, v42
	v_lshlrev_b32_e32 v16, 16, v30
	v_cvt_pk_bf16_f32 v12, v12, v13
	v_pk_mul_f32 v[14:15], v[14:15], v[16:17]
	v_mul_u32_u24_e32 v3, 0x8c, v19
	v_cvt_pk_bf16_f32 v13, v14, v15
	v_lshlrev_b32_e32 v14, 5, v25
	v_add3_u32 v3, v20, v3, v14
	ds_write_b128 v3, v[6:9]
	ds_write_b128 v3, v[10:13] offset:16
	s_and_saveexec_b64 s[0:1], vcc
	s_cbranch_execz .LBB0_368
	v_mul_f32_e32 v2, 0x3fb8aa3b, v2
	v_exp_f32_e32 v6, v2
	s_add_u32 s4, s60, s6
	v_mov_b32_e32 v19, v1
	s_addc_u32 s5, s61, s7
	v_lshl_add_u64 v[2:3], v[18:19], 2, s[4:5]
	global_store_dword v[2:3], v6, off

; __device__ __forceinline__ void gla_step3(const Params& P, int l, LAS unsigned char* lds, int item, int tid) {
;     ...
;     f32x4 gdr = (f32x4){0.f, 0.f, 0.f, 0.f}; if (tid < 256) gdr = *(const f32x4*)(zs + (size_t)t0 * 32 + (tid >> 2) * 32 + (tid & 3) * 4);
;     float wv[16]; { const float* wup = P.w_gk_up + (size_t)l * 16 * 512 + h * 128;
; #pragma unroll
;       for (int r = 0; r < 16; ++r) wv[r] = wup[r * 512 + d]; }
;     const float bias = P.b_gk[l * 512 + h * 128 + d];
;     bf16 qraw[16], kraw[16];
; #pragma unroll
;     for (int c = 0; c < 16; ++c) { const size_t zo = (size_t)(t0 + rg * 16 + c) * ZP + h * 128 + d; qraw[c] = z[zo + ZC_GQ]; kraw[c] = z[zo + ZC_GK]; }
;     v4u vr[4]; load_v(z + (size_t)t0 * ZP + ZC_GV + h * 256, tid, vr);
;     bf16x8 sfr[2][4];
;     { const bf16* St = (const bf16*)(P.ws + WS_Y) + (size_t)item * 32768;
; #pragma unroll
;       for (int et = 0; et < 2; ++et)
; #pragma unroll
;           for (int ks = 0; ks < 4; ++ks) sfr[et][ks] = *(const bf16x8*)(St + (size_t)(e0 + et * 16 + i) * 128 + ks * 32 + quad * 8); }
;     __syncthreads();
.LBB0_638:
	s_or_b64 exec, exec, s[0:1]
	s_bfe_u32 s15, s14, 0x20006
	s_lshl_b32 s16, s15, 7
	s_lshl_b32 s9, s15, 9
	v_readlane_b32 s0, v253, 2
	v_and_b32_e32 v83, 0x7f, v59
	s_add_u32 s0, s0, s9
	v_readlane_b32 s1, v255, 50
	s_addc_u32 s1, s1, 0
	v_lshlrev_b32_e32 v0, 2, v83
	v_lshl_add_u64 v[4:5], s[0:1], 0, v[0:1]
	s_nop 1
	global_load_dword v106, v0, s[0:1]
	global_load_dword v107, v0, s[0:1] offset:2048
	v_add_co_u32_e64 v6, s[0:1], s68, v4
	v_ashrrev_i32_e32 v77, 7, v59
	s_nop 0
	v_addc_co_u32_e64 v7, s[0:1], 0, v5, s[0:1]
	v_add_co_u32_e64 v8, s[0:1], s42, v4
	v_lshlrev_b32_e32 v60, 4, v77
	s_nop 0
	v_addc_co_u32_e64 v9, s[0:1], 0, v5, s[0:1]
	s_movk_i32 s0, 0x3000
	global_load_dword v110, v[8:9], off offset:-4096
	global_load_dword v111, v[6:7], off offset:2048
	global_load_dword v98, v[8:9], off
	global_load_dword v99, v[8:9], off offset:2048
	v_add_co_u32_e64 v6, s[0:1], s0, v4
	s_lshl_b32 s76, s15, 8
	s_nop 0
	v_addc_co_u32_e64 v7, s[0:1], 0, v5, s[0:1]
	s_movk_i32 s0, 0x4000
	s_nop 0
	v_add_co_u32_e64 v8, s[0:1], s0, v4
	v_add_u32_e32 v3, s8, v60
	s_nop 0
	v_addc_co_u32_e64 v9, s[0:1], 0, v5, s[0:1]
	s_movk_i32 s0, 0x5000
	global_load_dword v104, v[8:9], off offset:-4096
	global_load_dword v105, v[6:7], off offset:2048
	global_load_dword v100, v[8:9], off
	global_load_dword v101, v[8:9], off offset:2048
	v_add_co_u32_e64 v6, s[0:1], s0, v4
	v_and_b32_e32 v2, 0xf8, v2
	s_nop 0
	v_addc_co_u32_e64 v7, s[0:1], 0, v5, s[0:1]
	v_add_co_u32_e64 v8, s[0:1], s80, v4
	v_lshlrev_b32_e32 v2, 1, v2
	s_nop 0
	v_addc_co_u32_e64 v9, s[0:1], 0, v5, s[0:1]
	s_movk_i32 s0, 0x7000
	s_nop 0
	v_add_co_u32_e64 v4, s[0:1], s0, v4
	global_load_dword v108, v[8:9], off offset:-4096
	global_load_dword v109, v[6:7], off offset:2048
	global_load_dword v96, v[8:9], off
	global_load_dword v97, v[8:9], off offset:2048
	v_addc_co_u32_e64 v5, s[0:1], 0, v5, s[0:1]
	v_readlane_b32 s0, v255, 51
	s_or_b32 s0, s16, s0
	v_readlane_b32 s16, v253, 9
	v_or_b32_e32 v0, s0, v83
	v_readlane_b32 s26, v253, 19
	v_readlane_b32 s27, v253, 20
	global_load_dword v103, v[4:5], off
	global_load_dword v102, v[4:5], off offset:2048
	v_lshl_add_u64 v[4:5], v[0:1], 2, s[26:27]
	v_lshlrev_b32_e32 v0, 1, v83
	global_load_dword v112, v[4:5], off
	v_lshl_add_u64 v[4:5], s[92:93], 0, v[0:1]
	v_lshl_add_u64 v[4:5], v[4:5], 0, s[76:77]
	v_mad_i64_i32 v[6:7], s[0:1], v3, s80, v[4:5]
	global_load_ushort v95, v[6:7], off
	global_load_ushort v94, v[6:7], off offset:1024
	v_or_b32_e32 v6, 1, v3
	v_mad_i64_i32 v[6:7], s[0:1], v6, s80, v[4:5]
	global_load_ushort v93, v[6:7], off
	global_load_ushort v92, v[6:7], off offset:1024
	v_or_b32_e32 v6, 2, v3
	v_mad_i64_i32 v[6:7], s[0:1], v6, s80, v[4:5]
	global_load_ushort v91, v[6:7], off
	global_load_ushort v90, v[6:7], off offset:1024
	v_or_b32_e32 v6, 3, v3
	v_mad_i64_i32 v[6:7], s[0:1], v6, s80, v[4:5]
	global_load_ushort v89, v[6:7], off
	global_load_ushort v88, v[6:7], off offset:1024
	v_or_b32_e32 v6, 4, v3
	v_mad_i64_i32 v[6:7], s[0:1], v6, s80, v[4:5]
	global_load_ushort v87, v[6:7], off
	global_load_ushort v86, v[6:7], off offset:1024
	v_or_b32_e32 v6, 5, v3
	v_mad_i64_i32 v[6:7], s[0:1], v6, s80, v[4:5]
	global_load_ushort v85, v[6:7], off
	global_load_ushort v84, v[6:7], off offset:1024
	v_or_b32_e32 v6, 6, v3
	v_mad_i64_i32 v[6:7], s[0:1], v6, s80, v[4:5]
	global_load_ushort v82, v[6:7], off
	global_load_ushort v81, v[6:7], off offset:1024
	v_or_b32_e32 v6, 7, v3
	v_mad_i64_i32 v[6:7], s[0:1], v6, s80, v[4:5]
	global_load_ushort v80, v[6:7], off
	global_load_ushort v79, v[6:7], off offset:1024
	v_or_b32_e32 v6, 8, v3
	v_mad_i64_i32 v[6:7], s[0:1], v6, s80, v[4:5]
	global_load_ushort v78, v[6:7], off
	global_load_ushort v76, v[6:7], off offset:1024
	v_or_b32_e32 v6, 9, v3
	v_mad_i64_i32 v[6:7], s[0:1], v6, s80, v[4:5]
	global_load_ushort v75, v[6:7], off
	global_load_ushort v74, v[6:7], off offset:1024
	v_or_b32_e32 v6, 10, v3
	v_mad_i64_i32 v[6:7], s[0:1], v6, s80, v[4:5]
	global_load_ushort v73, v[6:7], off
	global_load_ushort v72, v[6:7], off offset:1024
	v_or_b32_e32 v6, 11, v3
	v_mad_i64_i32 v[6:7], s[0:1], v6, s80, v[4:5]
	global_load_ushort v71, v[6:7], off
	global_load_ushort v70, v[6:7], off offset:1024
	v_or_b32_e32 v6, 12, v3
	v_mad_i64_i32 v[6:7], s[0:1], v6, s80, v[4:5]
	global_load_ushort v69, v[6:7], off
	global_load_ushort v68, v[6:7], off offset:1024
	v_or_b32_e32 v6, 13, v3
	v_mad_i64_i32 v[6:7], s[0:1], v6, s80, v[4:5]
	global_load_ushort v67, v[6:7], off
	global_load_ushort v66, v[6:7], off offset:1024
	v_or_b32_e32 v6, 14, v3
	v_or_b32_e32 v3, 15, v3
	v_mad_i64_i32 v[6:7], s[0:1], v6, s80, v[4:5]
	v_mad_i64_i32 v[4:5], s[0:1], v3, s80, v[4:5]
	s_mul_i32 s1, s8, 0x6000
	s_mul_hi_i32 s0, s8, 0x6000
	s_add_u32 s1, s92, s1
	s_addc_u32 s15, s93, s0
	s_add_u32 s0, s1, s9
	s_addc_u32 s1, s15, 0
	v_mov_b32_e32 v3, v1
	v_lshl_add_u64 v[2:3], s[0:1], 0, v[2:3]
	v_ashrrev_i32_e32 v115, 5, v59
	global_load_ushort v65, v[6:7], off
	global_load_ushort v64, v[6:7], off offset:1024
	global_load_ushort v63, v[4:5], off
	global_load_ushort v62, v[4:5], off offset:1024
	v_mad_i64_i32 v[4:5], s[0:1], v115, s80, v[2:3]
	global_load_dwordx4 v[38:41], v[4:5], off offset:2048
	v_add_u32_e32 v4, 0x200, v59
	v_ashrrev_i32_e32 v116, 5, v4
	v_mad_i64_i32 v[4:5], s[0:1], v116, s80, v[2:3]
	global_load_dwordx4 v[42:45], v[4:5], off offset:2048
	v_add_u32_e32 v4, 0x400, v59
	v_ashrrev_i32_e32 v58, 6, v59
	v_ashrrev_i32_e32 v117, 5, v4
	v_and_b32_e32 v61, 15, v59
	v_lshlrev_b32_e32 v54, 5, v58
	v_mad_i64_i32 v[4:5], s[0:1], v117, s80, v[2:3]
	global_load_dwordx4 v[46:49], v[4:5], off offset:2048
	v_add_u32_e32 v4, 0x600, v59
	v_or_b32_e32 v56, v54, v61
	v_ashrrev_i32_e32 v118, 5, v4
	v_or_b32_e32 v6, 16, v56
	v_mad_i64_i32 v[2:3], s[0:1], v118, s80, v[2:3]
	v_ashrrev_i32_e32 v57, 31, v56
	v_ashrrev_i32_e32 v7, 31, v6
	global_load_dwordx4 v[50:53], v[2:3], off offset:2048
	v_lshlrev_b64 v[2:3], 8, v[56:57]
	v_and_b32_e32 v8, 48, v59
	v_lshlrev_b64 v[6:7], 8, v[6:7]
	v_or_b32_e32 v2, v2, v8
	v_or_b32_e32 v6, v6, v8
	v_lshl_add_u64 v[2:3], s[6:7], 0, v[2:3]
	v_lshl_add_u64 v[6:7], s[6:7], 0, v[6:7]
	global_load_dwordx4 v[26:29], v[2:3], off
	global_load_dwordx4 v[14:17], v[2:3], off offset:64
	global_load_dwordx4 v[10:13], v[2:3], off offset:128
	s_nop 0
	global_load_dwordx4 v[2:5], v[2:3], off offset:192
	s_nop 0
	global_load_dwordx4 v[30:33], v[6:7], off
	global_load_dwordx4 v[22:25], v[6:7], off offset:64
	global_load_dwordx4 v[18:21], v[6:7], off offset:128
	s_nop 0
	global_load_dwordx4 v[6:9], v[6:7], off offset:192
	v_and_b32_e32 v55, 12, v113
	v_readlane_b32 s17, v253, 10
	v_readlane_b32 s18, v253, 11
	v_readlane_b32 s19, v253, 12
	v_readlane_b32 s20, v253, 13
	v_readlane_b32 s21, v253, 14
	v_readlane_b32 s22, v253, 15
	v_readlane_b32 s23, v253, 16
	v_readlane_b32 s24, v253, 17
	v_readlane_b32 s25, v253, 18
	v_readlane_b32 s28, v253, 21
	v_readlane_b32 s29, v253, 22
	v_readlane_b32 s30, v253, 23
	v_readlane_b32 s31, v253, 24
	s_waitcnt vmcnt(63) expcnt(7) lgkmcnt(15)
	s_barrier
; #define LAS __attribute__((address_space(3)))
; __device__ __forceinline__ float logsig(float x) { return fminf(x, 0.f) - __logf(1.f + __expf(-fabsf(x))); }
; __device__ __forceinline__ void gla_decay(LAS float* gd, LAS float* tot, int tid, const float (&w)[16], float bias, float (&bv)[16], float& blast) {
;     ...
;     for (int c = 0; c < 16; ++c) { const LAS f32x4* g4 = (const LAS f32x4*)(gd + (rg * 16 + c) * 16); float a = bias;
; #pragma unroll
;         for (int q = 0; q < 4; ++q) { const f32x4 g = g4[q]; a += g[0] * w[4 * q] + g[1] * w[4 * q + 1] + g[2] * w[4 * q + 2] + g[3] * w[4 * q + 3]; }
;         run += logsig(a) * 0.0625f; bv[c] = run; }
; __device__ __forceinline__ void gla_step3(const Params& P, int l, LAS unsigned char* lds, int item, int tid) {
;     ...
;     __syncthreads();
;     if (tid < 256) *(LAS f32x4*)(GD + (tid >> 2) * 16 + (tid & 3) * 4) = gdr;
;     store_v(VT, tid, vr);
;     __syncthreads();
;     float bv[16], blast;
;     gla_decay(GD, TOT, tid, wv, bias, bv, blast);
	s_and_saveexec_b64 s[0:1], vcc
	s_xor_b64 s[0:1], exec, s[0:1]
	v_and_b32_e32 v55, 12, v113
	s_andn2_saveexec_b64 s[0:1], s[0:1]
	s_cbranch_execz .LBB0_642
	v_and_b32_e32 v113, 0x3ffffff0, v113
	v_lshlrev_b32_e32 v113, 2, v113
	v_lshlrev_b32_e32 v119, 2, v55
	v_readlane_b32 s9, v255, 18
	s_nop 1
	v_add3_u32 v113, s9, v113, v119
	s_waitcnt vmcnt(8)
	ds_write_b128 v113, v[34:37]
.LBB0_642:
	s_or_b64 exec, exec, s[0:1]
	s_waitcnt vmcnt(8)
	v_and_b32_e32 v36, 0x1f0, v114
	v_add_u32_e32 v36, 0, v36
	s_movk_i32 s15, 0x220
	v_mad_u64_u32 v[114:115], s[0:1], v115, s15, v[36:37]
	ds_write_b128 v114, v[38:41] offset:34816
	v_mad_u64_u32 v[38:39], s[0:1], v116, s15, v[36:37]
	ds_write_b128 v38, v[42:45] offset:34816
	v_mad_u64_u32 v[38:39], s[0:1], v117, s15, v[36:37]
	v_mad_u64_u32 v[36:37], s[0:1], v118, s15, v[36:37]
	v_readlane_b32 s17, v255, 18
	ds_write_b128 v38, v[46:49] offset:34816
	ds_write_b128 v36, v[50:53] offset:34816
	v_lshl_add_u32 v37, v77, 10, s17
	s_waitcnt lgkmcnt(0)
	s_barrier
	ds_read_b128 v[192:195], v37
	ds_read_b128 v[196:199], v37 offset:16
	ds_read_b128 v[200:203], v37 offset:32
	ds_read_b128 v[204:207], v37 offset:48
	ds_read_b128 v[208:211], v37 offset:64
	ds_read_b128 v[212:215], v37 offset:80
	ds_read_b128 v[216:219], v37 offset:96
	ds_read_b128 v[220:223], v37 offset:112
	v_bfe_u32 v35, v59, 4, 2
	s_waitcnt lgkmcnt(4)
	v_mul_f32_e32 v36, v107, v193
	v_fmac_f32_e32 v36, v106, v192
	v_mul_f32_e32 v38, v99, v197
	v_fmac_f32_e32 v36, v110, v194
	v_fmac_f32_e32 v38, v98, v196
	v_fmac_f32_e32 v36, v111, v195
	v_fmac_f32_e32 v38, v104, v198
	v_add_f32_e32 v36, v112, v36
	v_fmac_f32_e32 v38, v105, v199
	v_add_f32_e32 v36, v36, v38
	v_mul_f32_e32 v38, v101, v201
	v_fmac_f32_e32 v38, v100, v200
	v_fmac_f32_e32 v38, v108, v202
	v_fmac_f32_e32 v38, v109, v203
	v_add_f32_e32 v36, v36, v38
	v_mul_f32_e32 v38, v97, v205
	v_fmac_f32_e32 v38, v96, v204
	v_fmac_f32_e32 v38, v103, v206
	v_fmac_f32_e32 v38, v102, v207
	ds_read_b128 v[192:195], v37 offset:128
	ds_read_b128 v[196:199], v37 offset:144
	ds_read_b128 v[200:203], v37 offset:160
	ds_read_b128 v[204:207], v37 offset:176
	v_add_f32_e32 v36, v36, v38
	v_min_f32_e32 v38, 0, v36
	v_mul_f32_e64 v36, |v36|, s90
	v_exp_f32_e32 v36, v36
	s_movk_i32 s16, 0x110
	v_lshlrev_b32_e32 v34, 3, v35
	v_add_f32_e32 v36, 1.0, v36
	v_cmp_gt_f32_e32 vcc, s74, v36
	s_movk_i32 s9, 0x90
	s_nop 0
	v_cndmask_b32_e64 v39, 0, 32, vcc
	v_ldexp_f32 v36, v36, v39
	v_log_f32_e32 v36, v36
	s_nop 0
	v_mul_f32_e32 v39, 0x3f317217, v36
	v_fma_f32 v39, v36, s75, -v39
	v_fmac_f32_e32 v39, 0x3377d1cf, v36
	v_fmac_f32_e32 v39, 0x3f317217, v36
	v_cmp_lt_f32_e64 s[0:1], |v36|, s63
	s_nop 1
	v_cndmask_b32_e64 v36, v36, v39, s[0:1]
	v_cndmask_b32_e32 v39, 0, v240, vcc
	v_sub_f32_e32 v36, v36, v39
	v_sub_f32_e32 v36, v38, v36
	s_mov_b32 s0, 0x3d800000
	v_fma_f32 v36, v36, s0, 0
	s_waitcnt lgkmcnt(4)
	v_mul_f32_e32 v39, v107, v209
	v_fmac_f32_e32 v39, v106, v208
	v_fmac_f32_e32 v39, v110, v210
	v_fmac_f32_e32 v39, v111, v211
	v_add_f32_e32 v42, v112, v39
	v_mul_f32_e32 v39, v99, v213
	v_fmac_f32_e32 v39, v98, v212
	v_fmac_f32_e32 v39, v104, v214
	v_fmac_f32_e32 v39, v105, v215
	v_add_f32_e32 v42, v42, v39
	v_mul_f32_e32 v39, v101, v217
	v_fmac_f32_e32 v39, v100, v216
	v_fmac_f32_e32 v39, v108, v218
	v_fmac_f32_e32 v39, v109, v219
	v_add_f32_e32 v42, v42, v39
	v_mul_f32_e32 v39, v97, v221
	v_fmac_f32_e32 v39, v96, v220
	v_fmac_f32_e32 v39, v103, v222
	v_fmac_f32_e32 v39, v102, v223
	ds_read_b128 v[208:211], v37 offset:192
	ds_read_b128 v[212:215], v37 offset:208
	ds_read_b128 v[216:219], v37 offset:224
	ds_read_b128 v[220:223], v37 offset:240
	v_add_f32_e32 v38, v42, v39
	v_min_f32_e32 v39, 0, v38
	v_mul_f32_e64 v38, |v38|, s90
	v_exp_f32_e32 v38, v38
	s_nop 0
	v_add_f32_e32 v38, 1.0, v38
	v_cmp_gt_f32_e32 vcc, s74, v38
	s_nop 1
	v_cndmask_b32_e64 v40, 0, 32, vcc
	v_ldexp_f32 v38, v38, v40
	v_log_f32_e32 v38, v38
	s_nop 0
	v_mul_f32_e32 v40, 0x3f317217, v38
	v_fma_f32 v40, v38, s75, -v40
	v_fmac_f32_e32 v40, 0x3377d1cf, v38
	v_fmac_f32_e32 v40, 0x3f317217, v38
	v_cmp_lt_f32_e64 s[0:1], |v38|, s63
	s_nop 1
	v_cndmask_b32_e64 v38, v38, v40, s[0:1]
	v_cndmask_b32_e32 v40, 0, v240, vcc
	v_sub_f32_e32 v38, v38, v40
	v_sub_f32_e32 v38, v39, v38
	v_fmamk_f32 v38, v38, 0x3d800000, v36
	s_waitcnt lgkmcnt(4)
	v_mul_f32_e32 v39, v107, v193
	v_fmac_f32_e32 v39, v106, v192
	v_fmac_f32_e32 v39, v110, v194
	v_fmac_f32_e32 v39, v111, v195
	v_add_f32_e32 v39, v112, v39
	v_mul_f32_e32 v41, v99, v197
	v_fmac_f32_e32 v41, v98, v196
	v_fmac_f32_e32 v41, v104, v198
	v_fmac_f32_e32 v41, v105, v199
	v_add_f32_e32 v39, v39, v41
	v_mul_f32_e32 v41, v101, v201
	v_fmac_f32_e32 v41, v100, v200
	v_fmac_f32_e32 v41, v108, v202
	v_fmac_f32_e32 v41, v109, v203
	v_add_f32_e32 v39, v39, v41
	v_mul_f32_e32 v41, v97, v205
	v_fmac_f32_e32 v41, v96, v204
	v_fmac_f32_e32 v41, v103, v206
	v_fmac_f32_e32 v41, v102, v207
	ds_read_b128 v[192:195], v37 offset:256
	ds_read_b128 v[196:199], v37 offset:272
	ds_read_b128 v[200:203], v37 offset:288
	ds_read_b128 v[204:207], v37 offset:304
	v_add_f32_e32 v39, v39, v41
	v_min_f32_e32 v40, 0, v39
	v_mul_f32_e64 v39, |v39|, s90
	v_exp_f32_e32 v39, v39
	s_nop 0
	v_add_f32_e32 v39, 1.0, v39
	v_cmp_gt_f32_e32 vcc, s74, v39
	s_nop 1
	v_cndmask_b32_e64 v41, 0, 32, vcc
	v_ldexp_f32 v39, v39, v41
	v_log_f32_e32 v39, v39
	s_nop 0
	v_mul_f32_e32 v41, 0x3f317217, v39
	v_fma_f32 v41, v39, s75, -v41
	v_fmac_f32_e32 v41, 0x3377d1cf, v39
	v_fmac_f32_e32 v41, 0x3f317217, v39
	v_cmp_lt_f32_e64 s[0:1], |v39|, s63
	s_nop 1
	v_cndmask_b32_e64 v39, v39, v41, s[0:1]
	v_cndmask_b32_e32 v41, 0, v240, vcc
	v_sub_f32_e32 v39, v39, v41
	v_sub_f32_e32 v39, v40, v39
	v_fmamk_f32 v39, v39, 0x3d800000, v38
	s_waitcnt lgkmcnt(4)
; #define LAS __attribute__((address_space(3)))
; __device__ __forceinline__ float logsig(float x) { return fminf(x, 0.f) - __logf(1.f + __expf(-fabsf(x))); }
; __device__ __forceinline__ void gla_decay(LAS float* gd, LAS float* tot, int tid, const float (&w)[16], float bias, float (&bv)[16], float& blast) {
;     ...
;     for (int c = 0; c < 16; ++c) { const LAS f32x4* g4 = (const LAS f32x4*)(gd + (rg * 16 + c) * 16); float a = bias;
; #pragma unroll
;         for (int q = 0; q < 4; ++q) { const f32x4 g = g4[q]; a += g[0] * w[4 * q] + g[1] * w[4 * q + 1] + g[2] * w[4 * q + 2] + g[3] * w[4 * q + 3]; }
;         run += logsig(a) * 0.0625f; bv[c] = run; }
	v_mul_f32_e32 v41, v107, v209
	v_fmac_f32_e32 v41, v106, v208
	v_fmac_f32_e32 v41, v110, v210
	v_fmac_f32_e32 v41, v111, v211
	v_add_f32_e32 v44, v112, v41
	v_mul_f32_e32 v41, v99, v213
	v_fmac_f32_e32 v41, v98, v212
	v_fmac_f32_e32 v41, v104, v214
	v_fmac_f32_e32 v41, v105, v215
	v_add_f32_e32 v44, v44, v41
	v_mul_f32_e32 v41, v101, v217
	v_fmac_f32_e32 v41, v100, v216
	v_fmac_f32_e32 v41, v108, v218
	v_fmac_f32_e32 v41, v109, v219
	v_add_f32_e32 v44, v44, v41
	v_mul_f32_e32 v41, v97, v221
	v_fmac_f32_e32 v41, v96, v220
	v_fmac_f32_e32 v41, v103, v222
	v_fmac_f32_e32 v41, v102, v223
	ds_read_b128 v[208:211], v37 offset:320
	ds_read_b128 v[212:215], v37 offset:336
	ds_read_b128 v[216:219], v37 offset:352
	ds_read_b128 v[220:223], v37 offset:368
	v_add_f32_e32 v40, v44, v41
	v_min_f32_e32 v41, 0, v40
	v_mul_f32_e64 v40, |v40|, s90
	v_exp_f32_e32 v40, v40
	s_nop 0
	v_add_f32_e32 v40, 1.0, v40
	v_cmp_gt_f32_e32 vcc, s74, v40
	s_nop 1
	v_cndmask_b32_e64 v42, 0, 32, vcc
	v_ldexp_f32 v40, v40, v42
	v_log_f32_e32 v40, v40
	s_nop 0
	v_mul_f32_e32 v42, 0x3f317217, v40
	v_fma_f32 v42, v40, s75, -v42
	v_fmac_f32_e32 v42, 0x3377d1cf, v40
	v_fmac_f32_e32 v42, 0x3f317217, v40
	v_cmp_lt_f32_e64 s[0:1], |v40|, s63
	s_nop 1
	v_cndmask_b32_e64 v40, v40, v42, s[0:1]
	v_cndmask_b32_e32 v42, 0, v240, vcc
	v_sub_f32_e32 v40, v40, v42
	v_sub_f32_e32 v40, v41, v40
	v_fmamk_f32 v40, v40, 0x3d800000, v39
	s_waitcnt lgkmcnt(4)
	v_mul_f32_e32 v41, v107, v193
	v_fmac_f32_e32 v41, v106, v192
	v_fmac_f32_e32 v41, v110, v194
	v_fmac_f32_e32 v41, v111, v195
	v_add_f32_e32 v41, v112, v41
	v_mul_f32_e32 v43, v99, v197
	v_fmac_f32_e32 v43, v98, v196
	v_fmac_f32_e32 v43, v104, v198
	v_fmac_f32_e32 v43, v105, v199
	v_add_f32_e32 v41, v41, v43
	v_mul_f32_e32 v43, v101, v201
	v_fmac_f32_e32 v43, v100, v200
	v_fmac_f32_e32 v43, v108, v202
	v_fmac_f32_e32 v43, v109, v203
	v_add_f32_e32 v41, v41, v43
	v_mul_f32_e32 v43, v97, v205
	v_fmac_f32_e32 v43, v96, v204
	v_fmac_f32_e32 v43, v103, v206
	v_fmac_f32_e32 v43, v102, v207
	ds_read_b128 v[192:195], v37 offset:384
	ds_read_b128 v[196:199], v37 offset:400
	ds_read_b128 v[200:203], v37 offset:416
	ds_read_b128 v[204:207], v37 offset:432
	v_add_f32_e32 v41, v41, v43
	v_min_f32_e32 v42, 0, v41
	v_mul_f32_e64 v41, |v41|, s90
	v_exp_f32_e32 v41, v41
	s_nop 0
	v_add_f32_e32 v41, 1.0, v41
	v_cmp_gt_f32_e32 vcc, s74, v41
	s_nop 1
	v_cndmask_b32_e64 v43, 0, 32, vcc
	v_ldexp_f32 v41, v41, v43
	v_log_f32_e32 v41, v41
	s_nop 0
	v_mul_f32_e32 v43, 0x3f317217, v41
	v_fma_f32 v43, v41, s75, -v43
	v_fmac_f32_e32 v43, 0x3377d1cf, v41
	v_fmac_f32_e32 v43, 0x3f317217, v41
	v_cmp_lt_f32_e64 s[0:1], |v41|, s63
	s_nop 1
	v_cndmask_b32_e64 v41, v41, v43, s[0:1]
	v_cndmask_b32_e32 v43, 0, v240, vcc
	v_sub_f32_e32 v41, v41, v43
	v_sub_f32_e32 v41, v42, v41
	v_fmamk_f32 v41, v41, 0x3d800000, v40
	s_waitcnt lgkmcnt(4)
	v_mul_f32_e32 v43, v107, v209
	v_fmac_f32_e32 v43, v106, v208
	v_fmac_f32_e32 v43, v110, v210
	v_fmac_f32_e32 v43, v111, v211
	v_add_f32_e32 v46, v112, v43
	v_mul_f32_e32 v43, v99, v213
	v_fmac_f32_e32 v43, v98, v212
	v_fmac_f32_e32 v43, v104, v214
	v_fmac_f32_e32 v43, v105, v215
	v_add_f32_e32 v46, v46, v43
	v_mul_f32_e32 v43, v101, v217
	v_fmac_f32_e32 v43, v100, v216
	v_fmac_f32_e32 v43, v108, v218
	v_fmac_f32_e32 v43, v109, v219
	v_add_f32_e32 v46, v46, v43
	v_mul_f32_e32 v43, v97, v221
	v_fmac_f32_e32 v43, v96, v220
	v_fmac_f32_e32 v43, v103, v222
	v_fmac_f32_e32 v43, v102, v223
	ds_read_b128 v[208:211], v37 offset:448
	ds_read_b128 v[212:215], v37 offset:464
	ds_read_b128 v[216:219], v37 offset:480
	ds_read_b128 v[220:223], v37 offset:496
	v_add_f32_e32 v42, v46, v43
	v_min_f32_e32 v43, 0, v42
	v_mul_f32_e64 v42, |v42|, s90
	v_exp_f32_e32 v42, v42
	s_nop 0
	v_add_f32_e32 v42, 1.0, v42
	v_cmp_gt_f32_e32 vcc, s74, v42
	s_nop 1
	v_cndmask_b32_e64 v44, 0, 32, vcc
	v_ldexp_f32 v42, v42, v44
	v_log_f32_e32 v42, v42
	s_nop 0
	v_mul_f32_e32 v44, 0x3f317217, v42
	v_fma_f32 v44, v42, s75, -v44
	v_fmac_f32_e32 v44, 0x3377d1cf, v42
	v_fmac_f32_e32 v44, 0x3f317217, v42
	v_cmp_lt_f32_e64 s[0:1], |v42|, s63
	s_nop 1
	v_cndmask_b32_e64 v42, v42, v44, s[0:1]
	v_cndmask_b32_e32 v44, 0, v240, vcc
	v_sub_f32_e32 v42, v42, v44
	v_sub_f32_e32 v42, v43, v42
	v_fmamk_f32 v42, v42, 0x3d800000, v41
	s_waitcnt lgkmcnt(4)
	v_mul_f32_e32 v43, v107, v193
	v_fmac_f32_e32 v43, v106, v192
	v_fmac_f32_e32 v43, v110, v194
	v_fmac_f32_e32 v43, v111, v195
	v_add_f32_e32 v43, v112, v43
	v_mul_f32_e32 v45, v99, v197
	v_fmac_f32_e32 v45, v98, v196
	v_fmac_f32_e32 v45, v104, v198
	v_fmac_f32_e32 v45, v105, v199
	v_add_f32_e32 v43, v43, v45
	v_mul_f32_e32 v45, v101, v201
	v_fmac_f32_e32 v45, v100, v200
	v_fmac_f32_e32 v45, v108, v202
	v_fmac_f32_e32 v45, v109, v203
	v_add_f32_e32 v43, v43, v45
	v_mul_f32_e32 v45, v97, v205
	v_fmac_f32_e32 v45, v96, v204
	v_fmac_f32_e32 v45, v103, v206
	v_fmac_f32_e32 v45, v102, v207
	ds_read_b128 v[192:195], v37 offset:512
	ds_read_b128 v[196:199], v37 offset:528
	ds_read_b128 v[200:203], v37 offset:544
	ds_read_b128 v[204:207], v37 offset:560
	v_add_f32_e32 v43, v43, v45
	v_min_f32_e32 v44, 0, v43
	v_mul_f32_e64 v43, |v43|, s90
	v_exp_f32_e32 v43, v43
	s_nop 0
	v_add_f32_e32 v43, 1.0, v43
	v_cmp_gt_f32_e32 vcc, s74, v43
	s_nop 1
	v_cndmask_b32_e64 v45, 0, 32, vcc
	v_ldexp_f32 v43, v43, v45
	v_log_f32_e32 v43, v43
	s_nop 0
	v_mul_f32_e32 v45, 0x3f317217, v43
	v_fma_f32 v45, v43, s75, -v45
	v_fmac_f32_e32 v45, 0x3377d1cf, v43
	v_fmac_f32_e32 v45, 0x3f317217, v43
	v_cmp_lt_f32_e64 s[0:1], |v43|, s63
	s_nop 1
	v_cndmask_b32_e64 v43, v43, v45, s[0:1]
	v_cndmask_b32_e32 v45, 0, v240, vcc
	v_sub_f32_e32 v43, v43, v45
	v_sub_f32_e32 v43, v44, v43
	v_fmamk_f32 v43, v43, 0x3d800000, v42
	s_waitcnt lgkmcnt(4)
; #define LAS __attribute__((address_space(3)))
; __device__ __forceinline__ float logsig(float x) { return fminf(x, 0.f) - __logf(1.f + __expf(-fabsf(x))); }
; __device__ __forceinline__ void gla_decay(LAS float* gd, LAS float* tot, int tid, const float (&w)[16], float bias, float (&bv)[16], float& blast) {
;     ...
;     for (int c = 0; c < 16; ++c) { const LAS f32x4* g4 = (const LAS f32x4*)(gd + (rg * 16 + c) * 16); float a = bias;
; #pragma unroll
;         for (int q = 0; q < 4; ++q) { const f32x4 g = g4[q]; a += g[0] * w[4 * q] + g[1] * w[4 * q + 1] + g[2] * w[4 * q + 2] + g[3] * w[4 * q + 3]; }
;         run += logsig(a) * 0.0625f; bv[c] = run; }
	v_mul_f32_e32 v45, v107, v209
	v_fmac_f32_e32 v45, v106, v208
	v_fmac_f32_e32 v45, v110, v210
	v_fmac_f32_e32 v45, v111, v211
	v_add_f32_e32 v48, v112, v45
	v_mul_f32_e32 v45, v99, v213
	v_fmac_f32_e32 v45, v98, v212
	v_fmac_f32_e32 v45, v104, v214
	v_fmac_f32_e32 v45, v105, v215
	v_add_f32_e32 v48, v48, v45
	v_mul_f32_e32 v45, v101, v217
	v_fmac_f32_e32 v45, v100, v216
	v_fmac_f32_e32 v45, v108, v218
	v_fmac_f32_e32 v45, v109, v219
	v_add_f32_e32 v48, v48, v45
	v_mul_f32_e32 v45, v97, v221
	v_fmac_f32_e32 v45, v96, v220
	v_fmac_f32_e32 v45, v103, v222
	v_fmac_f32_e32 v45, v102, v223
	ds_read_b128 v[208:211], v37 offset:576
	ds_read_b128 v[212:215], v37 offset:592
	ds_read_b128 v[216:219], v37 offset:608
	ds_read_b128 v[220:223], v37 offset:624
	v_add_f32_e32 v44, v48, v45
	v_min_f32_e32 v45, 0, v44
	v_mul_f32_e64 v44, |v44|, s90
	v_exp_f32_e32 v44, v44
	s_nop 0
	v_add_f32_e32 v44, 1.0, v44
	v_cmp_gt_f32_e32 vcc, s74, v44
	s_nop 1
	v_cndmask_b32_e64 v46, 0, 32, vcc
	v_ldexp_f32 v44, v44, v46
	v_log_f32_e32 v44, v44
	s_nop 0
	v_mul_f32_e32 v46, 0x3f317217, v44
	v_fma_f32 v46, v44, s75, -v46
	v_fmac_f32_e32 v46, 0x3377d1cf, v44
	v_fmac_f32_e32 v46, 0x3f317217, v44
	v_cmp_lt_f32_e64 s[0:1], |v44|, s63
	s_nop 1
	v_cndmask_b32_e64 v44, v44, v46, s[0:1]
	v_cndmask_b32_e32 v46, 0, v240, vcc
	v_sub_f32_e32 v44, v44, v46
	v_sub_f32_e32 v44, v45, v44
	v_fmamk_f32 v44, v44, 0x3d800000, v43
	s_waitcnt lgkmcnt(4)
	v_mul_f32_e32 v45, v107, v193
	v_fmac_f32_e32 v45, v106, v192
	v_fmac_f32_e32 v45, v110, v194
	v_fmac_f32_e32 v45, v111, v195
	v_add_f32_e32 v45, v112, v45
	v_mul_f32_e32 v47, v99, v197
	v_fmac_f32_e32 v47, v98, v196
	v_fmac_f32_e32 v47, v104, v198
	v_fmac_f32_e32 v47, v105, v199
	v_add_f32_e32 v45, v45, v47
	v_mul_f32_e32 v47, v101, v201
	v_fmac_f32_e32 v47, v100, v200
	v_fmac_f32_e32 v47, v108, v202
	v_fmac_f32_e32 v47, v109, v203
	v_add_f32_e32 v45, v45, v47
	v_mul_f32_e32 v47, v97, v205
	v_fmac_f32_e32 v47, v96, v204
	v_fmac_f32_e32 v47, v103, v206
	v_fmac_f32_e32 v47, v102, v207
	ds_read_b128 v[192:195], v37 offset:640
	ds_read_b128 v[196:199], v37 offset:656
	ds_read_b128 v[200:203], v37 offset:672
	ds_read_b128 v[204:207], v37 offset:688
	v_add_f32_e32 v45, v45, v47
	v_min_f32_e32 v46, 0, v45
	v_mul_f32_e64 v45, |v45|, s90
	v_exp_f32_e32 v45, v45
	s_nop 0
	v_add_f32_e32 v45, 1.0, v45
	v_cmp_gt_f32_e32 vcc, s74, v45
	s_nop 1
	v_cndmask_b32_e64 v47, 0, 32, vcc
	v_ldexp_f32 v45, v45, v47
	v_log_f32_e32 v45, v45
	s_nop 0
	v_mul_f32_e32 v47, 0x3f317217, v45
	v_fma_f32 v47, v45, s75, -v47
	v_fmac_f32_e32 v47, 0x3377d1cf, v45
	v_fmac_f32_e32 v47, 0x3f317217, v45
	v_cmp_lt_f32_e64 s[0:1], |v45|, s63
	s_nop 1
	v_cndmask_b32_e64 v45, v45, v47, s[0:1]
	v_cndmask_b32_e32 v47, 0, v240, vcc
	v_sub_f32_e32 v45, v45, v47
	v_sub_f32_e32 v45, v46, v45
	v_fmamk_f32 v45, v45, 0x3d800000, v44
	s_waitcnt lgkmcnt(4)
	v_mul_f32_e32 v47, v107, v209
	v_fmac_f32_e32 v47, v106, v208
	v_fmac_f32_e32 v47, v110, v210
	v_fmac_f32_e32 v47, v111, v211
	v_add_f32_e32 v50, v112, v47
	v_mul_f32_e32 v47, v99, v213
	v_fmac_f32_e32 v47, v98, v212
	v_fmac_f32_e32 v47, v104, v214
	v_fmac_f32_e32 v47, v105, v215
	v_add_f32_e32 v50, v50, v47
	v_mul_f32_e32 v47, v101, v217
	v_fmac_f32_e32 v47, v100, v216
	v_fmac_f32_e32 v47, v108, v218
	v_fmac_f32_e32 v47, v109, v219
	v_add_f32_e32 v50, v50, v47
	v_mul_f32_e32 v47, v97, v221
	v_fmac_f32_e32 v47, v96, v220
	v_fmac_f32_e32 v47, v103, v222
	v_fmac_f32_e32 v47, v102, v223
	ds_read_b128 v[208:211], v37 offset:704
	ds_read_b128 v[212:215], v37 offset:720
	ds_read_b128 v[216:219], v37 offset:736
	ds_read_b128 v[220:223], v37 offset:752
	v_add_f32_e32 v46, v50, v47
	v_min_f32_e32 v47, 0, v46
	v_mul_f32_e64 v46, |v46|, s90
	v_exp_f32_e32 v46, v46
	s_nop 0
	v_add_f32_e32 v46, 1.0, v46
	v_cmp_gt_f32_e32 vcc, s74, v46
	s_nop 1
	v_cndmask_b32_e64 v48, 0, 32, vcc
	v_ldexp_f32 v46, v46, v48
	v_log_f32_e32 v46, v46
	s_nop 0
	v_mul_f32_e32 v48, 0x3f317217, v46
	v_fma_f32 v48, v46, s75, -v48
	v_fmac_f32_e32 v48, 0x3377d1cf, v46
	v_fmac_f32_e32 v48, 0x3f317217, v46
	v_cmp_lt_f32_e64 s[0:1], |v46|, s63
	s_nop 1
	v_cndmask_b32_e64 v46, v46, v48, s[0:1]
	v_cndmask_b32_e32 v48, 0, v240, vcc
	v_sub_f32_e32 v46, v46, v48
	v_sub_f32_e32 v46, v47, v46
	v_fmamk_f32 v46, v46, 0x3d800000, v45
	s_waitcnt lgkmcnt(4)
	v_mul_f32_e32 v47, v107, v193
	v_fmac_f32_e32 v47, v106, v192
	v_fmac_f32_e32 v47, v110, v194
	v_fmac_f32_e32 v47, v111, v195
	v_add_f32_e32 v47, v112, v47
	v_mul_f32_e32 v49, v99, v197
	v_fmac_f32_e32 v49, v98, v196
	v_fmac_f32_e32 v49, v104, v198
	v_fmac_f32_e32 v49, v105, v199
	v_add_f32_e32 v47, v47, v49
	v_mul_f32_e32 v49, v101, v201
	v_fmac_f32_e32 v49, v100, v200
	v_fmac_f32_e32 v49, v108, v202
	v_fmac_f32_e32 v49, v109, v203
	v_add_f32_e32 v47, v47, v49
	v_mul_f32_e32 v49, v97, v205
	v_fmac_f32_e32 v49, v96, v204
	v_fmac_f32_e32 v49, v103, v206
	v_fmac_f32_e32 v49, v102, v207
	ds_read_b128 v[192:195], v37 offset:768
	ds_read_b128 v[196:199], v37 offset:784
	ds_read_b128 v[200:203], v37 offset:800
	ds_read_b128 v[204:207], v37 offset:816
	v_add_f32_e32 v47, v47, v49
	v_min_f32_e32 v48, 0, v47
	v_mul_f32_e64 v47, |v47|, s90
	v_exp_f32_e32 v47, v47
	s_nop 0
	v_add_f32_e32 v47, 1.0, v47
	v_cmp_gt_f32_e32 vcc, s74, v47
	s_nop 1
	v_cndmask_b32_e64 v49, 0, 32, vcc
	v_ldexp_f32 v47, v47, v49
	v_log_f32_e32 v47, v47
	s_nop 0
	v_mul_f32_e32 v49, 0x3f317217, v47
	v_fma_f32 v49, v47, s75, -v49
	v_fmac_f32_e32 v49, 0x3377d1cf, v47
	v_fmac_f32_e32 v49, 0x3f317217, v47
	v_cmp_lt_f32_e64 s[0:1], |v47|, s63
	s_nop 1
	v_cndmask_b32_e64 v47, v47, v49, s[0:1]
	v_cndmask_b32_e32 v49, 0, v240, vcc
	v_sub_f32_e32 v47, v47, v49
	v_sub_f32_e32 v47, v48, v47
	v_fmamk_f32 v47, v47, 0x3d800000, v46
	s_waitcnt lgkmcnt(4)
; #define LAS __attribute__((address_space(3)))
; __device__ __forceinline__ float logsig(float x) { return fminf(x, 0.f) - __logf(1.f + __expf(-fabsf(x))); }
; __device__ __forceinline__ void gla_decay(LAS float* gd, LAS float* tot, int tid, const float (&w)[16], float bias, float (&bv)[16], float& blast) {
;     ...
;     for (int c = 0; c < 16; ++c) { const LAS f32x4* g4 = (const LAS f32x4*)(gd + (rg * 16 + c) * 16); float a = bias;
; #pragma unroll
;         for (int q = 0; q < 4; ++q) { const f32x4 g = g4[q]; a += g[0] * w[4 * q] + g[1] * w[4 * q + 1] + g[2] * w[4 * q + 2] + g[3] * w[4 * q + 3]; }
;         run += logsig(a) * 0.0625f; bv[c] = run; }
;     tot[rg * 128 + d] = run;
;     __syncthreads();
	v_mul_f32_e32 v49, v107, v209
	v_fmac_f32_e32 v49, v106, v208
	v_fmac_f32_e32 v49, v110, v210
	v_fmac_f32_e32 v49, v111, v211
	v_add_f32_e32 v52, v112, v49
	v_mul_f32_e32 v49, v99, v213
	v_fmac_f32_e32 v49, v98, v212
	v_fmac_f32_e32 v49, v104, v214
	v_fmac_f32_e32 v49, v105, v215
	v_add_f32_e32 v52, v52, v49
	v_mul_f32_e32 v49, v101, v217
	v_fmac_f32_e32 v49, v100, v216
	v_fmac_f32_e32 v49, v108, v218
	v_fmac_f32_e32 v49, v109, v219
	v_add_f32_e32 v52, v52, v49
	v_mul_f32_e32 v49, v97, v221
	v_fmac_f32_e32 v49, v96, v220
	v_fmac_f32_e32 v49, v103, v222
	v_fmac_f32_e32 v49, v102, v223
	ds_read_b128 v[208:211], v37 offset:832
	ds_read_b128 v[212:215], v37 offset:848
	ds_read_b128 v[216:219], v37 offset:864
	ds_read_b128 v[220:223], v37 offset:880
	v_add_f32_e32 v48, v52, v49
	v_min_f32_e32 v49, 0, v48
	v_mul_f32_e64 v48, |v48|, s90
	v_exp_f32_e32 v48, v48
	s_nop 0
	v_add_f32_e32 v48, 1.0, v48
	v_cmp_gt_f32_e32 vcc, s74, v48
	s_nop 1
	v_cndmask_b32_e64 v50, 0, 32, vcc
	v_ldexp_f32 v48, v48, v50
	v_log_f32_e32 v48, v48
	s_nop 0
	v_mul_f32_e32 v50, 0x3f317217, v48
	v_fma_f32 v50, v48, s75, -v50
	v_fmac_f32_e32 v50, 0x3377d1cf, v48
	v_fmac_f32_e32 v50, 0x3f317217, v48
	v_cmp_lt_f32_e64 s[0:1], |v48|, s63
	s_nop 1
	v_cndmask_b32_e64 v48, v48, v50, s[0:1]
	v_cndmask_b32_e32 v50, 0, v240, vcc
	v_sub_f32_e32 v48, v48, v50
	v_sub_f32_e32 v48, v49, v48
	v_fmamk_f32 v48, v48, 0x3d800000, v47
	s_waitcnt lgkmcnt(4)
	v_mul_f32_e32 v49, v107, v193
	v_fmac_f32_e32 v49, v106, v192
	v_fmac_f32_e32 v49, v110, v194
	v_fmac_f32_e32 v49, v111, v195
	v_add_f32_e32 v49, v112, v49
	v_mul_f32_e32 v51, v99, v197
	v_fmac_f32_e32 v51, v98, v196
	v_fmac_f32_e32 v51, v104, v198
	v_fmac_f32_e32 v51, v105, v199
	v_add_f32_e32 v49, v49, v51
	v_mul_f32_e32 v51, v101, v201
	v_fmac_f32_e32 v51, v100, v200
	v_fmac_f32_e32 v51, v108, v202
	v_fmac_f32_e32 v51, v109, v203
	v_add_f32_e32 v49, v49, v51
	v_mul_f32_e32 v51, v97, v205
	v_fmac_f32_e32 v51, v96, v204
	v_fmac_f32_e32 v51, v103, v206
	v_fmac_f32_e32 v51, v102, v207
	ds_read_b128 v[192:195], v37 offset:896
	ds_read_b128 v[196:199], v37 offset:912
	ds_read_b128 v[200:203], v37 offset:928
	ds_read_b128 v[204:207], v37 offset:944
	v_add_f32_e32 v49, v49, v51
	v_min_f32_e32 v50, 0, v49
	v_mul_f32_e64 v49, |v49|, s90
	v_exp_f32_e32 v49, v49
	s_nop 0
	v_add_f32_e32 v49, 1.0, v49
	v_cmp_gt_f32_e32 vcc, s74, v49
	s_nop 1
	v_cndmask_b32_e64 v51, 0, 32, vcc
	v_ldexp_f32 v49, v49, v51
	v_log_f32_e32 v49, v49
	s_nop 0
	v_mul_f32_e32 v51, 0x3f317217, v49
	v_fma_f32 v51, v49, s75, -v51
	v_fmac_f32_e32 v51, 0x3377d1cf, v49
	v_fmac_f32_e32 v51, 0x3f317217, v49
	v_cmp_lt_f32_e64 s[0:1], |v49|, s63
	s_nop 1
	v_cndmask_b32_e64 v49, v49, v51, s[0:1]
	v_cndmask_b32_e32 v51, 0, v240, vcc
	v_sub_f32_e32 v49, v49, v51
	v_sub_f32_e32 v49, v50, v49
	v_fmamk_f32 v49, v49, 0x3d800000, v48
	s_waitcnt lgkmcnt(4)
	v_mul_f32_e32 v51, v107, v209
	v_fmac_f32_e32 v51, v106, v208
	v_fmac_f32_e32 v51, v110, v210
	v_fmac_f32_e32 v51, v111, v211
	v_add_f32_e32 v113, v112, v51
	v_mul_f32_e32 v51, v99, v213
	v_fmac_f32_e32 v51, v98, v212
	v_fmac_f32_e32 v51, v104, v214
	v_fmac_f32_e32 v51, v105, v215
	v_add_f32_e32 v113, v113, v51
	v_mul_f32_e32 v51, v101, v217
	v_fmac_f32_e32 v51, v100, v216
	v_fmac_f32_e32 v51, v108, v218
	v_fmac_f32_e32 v51, v109, v219
	v_add_f32_e32 v113, v113, v51
	v_mul_f32_e32 v51, v97, v221
	v_fmac_f32_e32 v51, v96, v220
	v_fmac_f32_e32 v51, v103, v222
	v_fmac_f32_e32 v51, v102, v223
	ds_read_b128 v[208:211], v37 offset:960
	ds_read_b128 v[212:215], v37 offset:976
	ds_read_b128 v[216:219], v37 offset:992
	ds_read_b128 v[220:223], v37 offset:1008
	v_add_f32_e32 v50, v113, v51
	v_min_f32_e32 v51, 0, v50
	v_mul_f32_e64 v50, |v50|, s90
	v_exp_f32_e32 v50, v50
	s_nop 0
	v_add_f32_e32 v50, 1.0, v50
	v_cmp_gt_f32_e32 vcc, s74, v50
	s_nop 1
	v_cndmask_b32_e64 v52, 0, 32, vcc
	v_ldexp_f32 v50, v50, v52
	v_log_f32_e32 v50, v50
	s_nop 0
	v_mul_f32_e32 v52, 0x3f317217, v50
	v_fma_f32 v52, v50, s75, -v52
	v_fmac_f32_e32 v52, 0x3377d1cf, v50
	v_fmac_f32_e32 v52, 0x3f317217, v50
	v_cmp_lt_f32_e64 s[0:1], |v50|, s63
	s_nop 1
	v_cndmask_b32_e64 v50, v50, v52, s[0:1]
	v_cndmask_b32_e32 v52, 0, v240, vcc
	v_sub_f32_e32 v50, v50, v52
	v_sub_f32_e32 v50, v51, v50
	s_waitcnt lgkmcnt(4)
	v_mul_f32_e32 v51, v107, v193
	v_fmac_f32_e32 v51, v106, v192
	v_fmac_f32_e32 v51, v110, v194
	v_fmac_f32_e32 v51, v111, v195
	v_add_f32_e32 v51, v112, v51
	v_fmamk_f32 v50, v50, 0x3d800000, v49
	v_mul_f32_e32 v52, v99, v197
	v_fmac_f32_e32 v52, v98, v196
	v_fmac_f32_e32 v52, v104, v198
	v_fmac_f32_e32 v52, v105, v199
	v_add_f32_e32 v51, v51, v52
	v_mul_f32_e32 v52, v101, v201
	v_fmac_f32_e32 v52, v100, v200
	v_fmac_f32_e32 v52, v108, v202
	v_fmac_f32_e32 v52, v109, v203
	v_add_f32_e32 v51, v51, v52
	v_mul_f32_e32 v52, v97, v205
	v_fmac_f32_e32 v52, v96, v204
	v_fmac_f32_e32 v52, v103, v206
	v_fmac_f32_e32 v52, v102, v207
	v_add_f32_e32 v51, v51, v52
	v_min_f32_e32 v52, 0, v51
	v_mul_f32_e64 v51, |v51|, s90
	v_exp_f32_e32 v51, v51
	s_nop 0
	v_add_f32_e32 v51, 1.0, v51
	v_cmp_gt_f32_e32 vcc, s74, v51
	s_nop 1
	v_cndmask_b32_e64 v53, 0, 32, vcc
	v_ldexp_f32 v51, v51, v53
	v_log_f32_e32 v51, v51
	s_nop 0
	v_mul_f32_e32 v53, 0x3f317217, v51
	v_fma_f32 v53, v51, s75, -v53
	v_fmac_f32_e32 v53, 0x3377d1cf, v51
	v_fmac_f32_e32 v53, 0x3f317217, v51
	v_cmp_lt_f32_e64 s[0:1], |v51|, s63
	s_nop 1
	v_cndmask_b32_e64 v51, v51, v53, s[0:1]
	v_cndmask_b32_e32 v53, 0, v240, vcc
	v_sub_f32_e32 v51, v51, v53
	v_sub_f32_e32 v51, v52, v51
	s_waitcnt lgkmcnt(0)
	v_mul_f32_e32 v52, v107, v209
	v_fmac_f32_e32 v52, v106, v208
	v_fmac_f32_e32 v52, v110, v210
	v_fmac_f32_e32 v52, v111, v211
	v_add_f32_e32 v52, v112, v52
	v_fmamk_f32 v51, v51, 0x3d800000, v50
	v_mul_f32_e32 v53, v99, v213
	v_fmac_f32_e32 v53, v98, v212
	v_fmac_f32_e32 v53, v104, v214
	v_fmac_f32_e32 v53, v105, v215
	v_add_f32_e32 v52, v52, v53
	v_mul_f32_e32 v53, v101, v217
	v_fmac_f32_e32 v53, v100, v216
	v_fmac_f32_e32 v53, v108, v218
	v_fmac_f32_e32 v53, v109, v219
	v_add_f32_e32 v52, v52, v53
	v_mul_f32_e32 v37, v97, v221
	v_fmac_f32_e32 v37, v96, v220
	v_fmac_f32_e32 v37, v103, v222
	v_fmac_f32_e32 v37, v102, v223
	v_add_f32_e32 v37, v52, v37
	v_min_f32_e32 v52, 0, v37
	v_mul_f32_e64 v37, |v37|, s90
	v_exp_f32_e32 v37, v37
	s_nop 0
	v_add_f32_e32 v37, 1.0, v37
	v_cmp_gt_f32_e32 vcc, s74, v37
	s_nop 1
	v_cndmask_b32_e64 v53, 0, 32, vcc
	v_ldexp_f32 v37, v37, v53
	v_log_f32_e32 v37, v37
	s_nop 0
	v_mul_f32_e32 v53, 0x3f317217, v37
	v_fma_f32 v53, v37, s75, -v53
	v_fmac_f32_e32 v53, 0x3377d1cf, v37
	v_fmac_f32_e32 v53, 0x3f317217, v37
	v_cmp_lt_f32_e64 s[0:1], |v37|, s63
	s_nop 1
	v_cndmask_b32_e64 v37, v37, v53, s[0:1]
	v_cndmask_b32_e32 v53, 0, v240, vcc
	v_sub_f32_e32 v37, v37, v53
	v_sub_f32_e32 v37, v52, v37
	v_readlane_b32 s0, v255, 19
	v_fmamk_f32 v96, v37, 0x3d800000, v51
	v_cmp_lt_i32_e32 vcc, 0, v77
	v_lshl_add_u32 v37, v59, 2, s0
	ds_write_b32 v37, v96
	v_lshl_add_u32 v37, v83, 2, s0
	s_waitcnt lgkmcnt(0)
	s_barrier
; #define LAS __attribute__((address_space(3)))
; __device__ __forceinline__ unsigned f2bf(float f) { return pk2(f, 0.f) & 0xffffu; }
; __device__ __forceinline__ float bf2f(bf16 v) { return __uint_as_float(((unsigned)v) << 16); }
; __device__ __forceinline__ void gla_decay(LAS float* gd, LAS float* tot, int tid, const float (&w)[16], float bias, float (&bv)[16], float& blast) {
;     ...
;     tot[rg * 128 + d] = run;
;     __syncthreads();
;     const float t0 = tot[d], t1 = tot[128 + d], t2 = tot[256 + d], t3 = tot[384 + d];
;     const float off = (rg > 0 ? t0 : 0.f) + (rg > 1 ? t1 : 0.f) + (rg > 2 ? t2 : 0.f);
;     blast = (t0 + t1) + (t2 + t3);
; #pragma unroll
;     for (int c = 0; c < 16; ++c) bv[c] += off;
; __device__ __forceinline__ void gla_step3(const Params& P, int l, LAS unsigned char* lds, int item, int tid) {
;     ...
; #pragma unroll
;     for (int c = 0; c < 16; ++c) { const int row = rg * 16 + c;
;         const float q = bf2f(qraw[c]) * 0.08838834764831845f * __expf(bv[c]), k = bf2f(kraw[c]) * __expf(-bv[c]);
;         *(LAS bf16*)(QT + row * 272 + d * 2) = (bf16)f2bf(q); *(LAS bf16*)(KT + row * 272 + d * 2) = (bf16)f2bf(k); }
	ds_read2st64_b32 v[52:53], v37 offset1:2
	ds_read_b32 v37, v37 offset:1024
	s_waitcnt lgkmcnt(1)
	v_cndmask_b32_e32 v52, 0, v52, vcc
	v_cmp_lt_i32_e32 vcc, 1, v77
	s_nop 1
	v_cndmask_b32_e32 v53, 0, v53, vcc
	v_cmp_lt_i32_e32 vcc, 2, v77
	v_add_f32_e32 v52, v52, v53
	s_waitcnt lgkmcnt(0)
	v_cndmask_b32_e32 v37, 0, v37, vcc
	v_add_f32_e32 v52, v52, v37
	v_add_f32_e32 v53, v36, v52
	v_add_f32_e32 v38, v38, v52
	v_add_f32_e32 v39, v39, v52
	v_add_f32_e32 v40, v40, v52
	v_add_f32_e32 v41, v41, v52
	v_add_f32_e32 v42, v42, v52
	v_add_f32_e32 v43, v43, v52
	v_add_f32_e32 v44, v44, v52
	v_add_f32_e32 v45, v45, v52
	v_add_f32_e32 v46, v46, v52
	v_add_f32_e32 v47, v47, v52
	v_add_f32_e32 v48, v48, v52
	v_add_f32_e32 v49, v49, v52
	v_add_f32_e32 v50, v50, v52
	v_add_f32_e32 v37, v52, v51
	v_add_f32_e32 v36, v52, v96
	v_mul_f32_e32 v52, 0x3fb8aa3b, v53
	v_exp_f32_e32 v52, v52
	v_mul_f32_e32 v53, 0xbfb8aa3b, v53
	v_lshlrev_b32_e32 v51, 16, v95
	v_exp_f32_e32 v53, v53
	v_mul_f32_e32 v51, 0x3db504f3, v51
	v_mul_f32_e32 v51, v51, v52
	v_lshlrev_b32_e32 v52, 16, v94
	v_cvt_pk_bf16_f32 v51, v51, s0
	s_movk_i32 s0, 0x1100
	v_mul_f32_e32 v52, v53, v52
	v_mul_lo_u32 v53, v77, s0
	v_add3_u32 v0, 0, v0, v53
	ds_write_b16 v0, v51
	v_cvt_pk_bf16_f32 v51, v52, s0
	v_mul_f32_e32 v52, 0x3fb8aa3b, v38
	v_exp_f32_e32 v52, v52
	ds_write_b16 v0, v51 offset:17408
	v_lshlrev_b32_e32 v51, 16, v93
	v_mul_f32_e32 v38, 0xbfb8aa3b, v38
	v_mul_f32_e32 v51, 0x3db504f3, v51
	v_exp_f32_e32 v38, v38
	v_mul_f32_e32 v51, v51, v52
	v_cvt_pk_bf16_f32 v51, v51, s0
	v_lshlrev_b32_e32 v52, 16, v92
	ds_write_b16 v0, v51 offset:272
	v_mul_f32_e32 v51, 0x3fb8aa3b, v39
	v_mul_f32_e32 v38, v38, v52
	v_exp_f32_e32 v51, v51
	v_mul_f32_e32 v39, 0xbfb8aa3b, v39
	v_cvt_pk_bf16_f32 v38, v38, s0
	v_exp_f32_e32 v39, v39
	ds_write_b16 v0, v38 offset:17680
	v_lshlrev_b32_e32 v38, 16, v91
	v_mul_f32_e32 v38, 0x3db504f3, v38
	v_mul_f32_e32 v38, v38, v51
	v_lshlrev_b32_e32 v51, 16, v90
	v_mul_f32_e32 v39, v39, v51
	v_cvt_pk_bf16_f32 v38, v38, s0
	ds_write_b16 v0, v38 offset:544
	v_cvt_pk_bf16_f32 v38, v39, s0
	v_mul_f32_e32 v39, 0x3fb8aa3b, v40
	v_exp_f32_e32 v39, v39
	v_mul_f32_e32 v40, 0xbfb8aa3b, v40
	v_exp_f32_e32 v40, v40
	ds_write_b16 v0, v38 offset:17952
	v_lshlrev_b32_e32 v38, 16, v89
	v_mul_f32_e32 v38, 0x3db504f3, v38
	v_mul_f32_e32 v38, v38, v39
	v_lshlrev_b32_e32 v39, 16, v88
	v_mul_f32_e32 v39, v40, v39
	v_cvt_pk_bf16_f32 v38, v38, s0
	ds_write_b16 v0, v38 offset:816
	v_cvt_pk_bf16_f32 v38, v39, s0
	v_mul_f32_e32 v39, 0x3fb8aa3b, v41
	v_exp_f32_e32 v39, v39
	v_mul_f32_e32 v40, 0xbfb8aa3b, v41
	v_exp_f32_e32 v40, v40
	ds_write_b16 v0, v38 offset:18224
	v_lshlrev_b32_e32 v38, 16, v87
	v_mul_f32_e32 v38, 0x3db504f3, v38
	v_mul_f32_e32 v38, v38, v39
	v_lshlrev_b32_e32 v39, 16, v86
	v_mul_f32_e32 v39, v40, v39
	v_cvt_pk_bf16_f32 v38, v38, s0
	ds_write_b16 v0, v38 offset:1088
	v_cvt_pk_bf16_f32 v38, v39, s0
	v_mul_f32_e32 v39, 0x3fb8aa3b, v42
	v_exp_f32_e32 v39, v39
	v_mul_f32_e32 v40, 0xbfb8aa3b, v42
	v_exp_f32_e32 v40, v40
	ds_write_b16 v0, v38 offset:18496
	v_lshlrev_b32_e32 v38, 16, v85
	v_mul_f32_e32 v38, 0x3db504f3, v38
	v_mul_f32_e32 v38, v38, v39
	v_lshlrev_b32_e32 v39, 16, v84
	v_mul_f32_e32 v39, v40, v39
	v_cvt_pk_bf16_f32 v38, v38, s0
	ds_write_b16 v0, v38 offset:1360
	v_cvt_pk_bf16_f32 v38, v39, s0
	v_mul_f32_e32 v39, 0x3fb8aa3b, v43
	v_exp_f32_e32 v39, v39
	v_mul_f32_e32 v40, 0xbfb8aa3b, v43
	v_exp_f32_e32 v40, v40
	ds_write_b16 v0, v38 offset:18768
	v_lshlrev_b32_e32 v38, 16, v82
	v_mul_f32_e32 v38, 0x3db504f3, v38
	v_mul_f32_e32 v38, v38, v39
	v_lshlrev_b32_e32 v39, 16, v81
	v_mul_f32_e32 v39, v40, v39
	v_cvt_pk_bf16_f32 v38, v38, s0
	ds_write_b16 v0, v38 offset:1632
	v_cvt_pk_bf16_f32 v38, v39, s0
	v_mul_f32_e32 v39, 0x3fb8aa3b, v44
	v_exp_f32_e32 v39, v39
	v_mul_f32_e32 v40, 0xbfb8aa3b, v44
	v_exp_f32_e32 v40, v40
	ds_write_b16 v0, v38 offset:19040
	v_lshlrev_b32_e32 v38, 16, v80
	v_mul_f32_e32 v38, 0x3db504f3, v38
	v_mul_f32_e32 v38, v38, v39
	v_lshlrev_b32_e32 v39, 16, v79
	v_mul_f32_e32 v39, v40, v39
	v_cvt_pk_bf16_f32 v38, v38, s0
	ds_write_b16 v0, v38 offset:1904
	v_cvt_pk_bf16_f32 v38, v39, s0
	v_mul_f32_e32 v39, 0x3fb8aa3b, v45
	v_exp_f32_e32 v39, v39
	v_mul_f32_e32 v40, 0xbfb8aa3b, v45
	v_exp_f32_e32 v40, v40
	ds_write_b16 v0, v38 offset:19312
	v_lshlrev_b32_e32 v38, 16, v78
	v_mul_f32_e32 v38, 0x3db504f3, v38
	v_mul_f32_e32 v38, v38, v39
	v_lshlrev_b32_e32 v39, 16, v76
	v_mul_f32_e32 v39, v40, v39
	v_cvt_pk_bf16_f32 v38, v38, s0
	ds_write_b16 v0, v38 offset:2176
	v_cvt_pk_bf16_f32 v38, v39, s0
	v_mul_f32_e32 v39, 0x3fb8aa3b, v46
	v_exp_f32_e32 v39, v39
	v_mul_f32_e32 v40, 0xbfb8aa3b, v46
	v_exp_f32_e32 v40, v40
	ds_write_b16 v0, v38 offset:19584
	v_lshlrev_b32_e32 v38, 16, v75
	v_mul_f32_e32 v38, 0x3db504f3, v38
	v_mul_f32_e32 v38, v38, v39
	v_lshlrev_b32_e32 v39, 16, v74
	v_mul_f32_e32 v39, v40, v39
	v_cvt_pk_bf16_f32 v38, v38, s0
	ds_write_b16 v0, v38 offset:2448
	v_cvt_pk_bf16_f32 v38, v39, s0
	v_mul_f32_e32 v39, 0x3fb8aa3b, v47
	v_exp_f32_e32 v39, v39
	v_mul_f32_e32 v40, 0xbfb8aa3b, v47
	v_exp_f32_e32 v40, v40
	ds_write_b16 v0, v38 offset:19856
	v_lshlrev_b32_e32 v38, 16, v73
	v_mul_f32_e32 v38, 0x3db504f3, v38
	v_mul_f32_e32 v38, v38, v39
	v_lshlrev_b32_e32 v39, 16, v72
	v_mul_f32_e32 v39, v40, v39
	v_cvt_pk_bf16_f32 v38, v38, s0
	ds_write_b16 v0, v38 offset:2720
	v_cvt_pk_bf16_f32 v38, v39, s0
	v_mul_f32_e32 v39, 0x3fb8aa3b, v48
	v_exp_f32_e32 v39, v39
	v_mul_f32_e32 v40, 0xbfb8aa3b, v48
	v_exp_f32_e32 v40, v40
	ds_write_b16 v0, v38 offset:20128
	v_lshlrev_b32_e32 v38, 16, v71
	v_mul_f32_e32 v38, 0x3db504f3, v38
	v_mul_f32_e32 v38, v38, v39
	v_lshlrev_b32_e32 v39, 16, v70
; #define LAS __attribute__((address_space(3)))
; __device__ __forceinline__ unsigned pk2(float lo, float hi) { const f32x2c_t v = {lo, hi}; return __builtin_bit_cast(unsigned, __builtin_convertvector(v, bf16x2c_t)); }
; __device__ __forceinline__ unsigned f2bf(float f) { return pk2(f, 0.f) & 0xffffu; }
; __device__ __forceinline__ float bf2f(bf16 v) { return __uint_as_float(((unsigned)v) << 16); }
; #define MFMA16(a, b, c) __builtin_amdgcn_mfma_f32_16x16x32_bf16((a), (b), (c), 0, 0, 0)
; __device__ __forceinline__ void gla_step3(const Params& P, int l, LAS unsigned char* lds, int item, int tid) {
;     ...
; #pragma unroll
;     for (int c = 0; c < 16; ++c) { const int row = rg * 16 + c;
;         const float q = bf2f(qraw[c]) * 0.08838834764831845f * __expf(bv[c]), k = bf2f(kraw[c]) * __expf(-bv[c]);
;         *(LAS bf16*)(QT + row * 272 + d * 2) = (bf16)f2bf(q); *(LAS bf16*)(KT + row * 272 + d * 2) = (bf16)f2bf(k); }
;     __syncthreads();
;     { const int cpt = w & 3;
; #pragma unroll
;       for (int hf = 0; hf < 2; ++hf) { const int ct = 2 * (w >> 2) + hf; f32x4 a4 = (f32x4){0.f, 0.f, 0.f, 0.f};
; #pragma unroll
;           for (int ks = 0; ks < 4; ++ks) { const bf16x8 ka = *(const LAS bf16x8*)(KT + (cpt * 16 + i) * 272 + (ks * 32 + quad * 8) * 2), qb = *(const LAS bf16x8*)(QT + (ct * 16 + i) * 272 + (ks * 32 + quad * 8) * 2);
;               a4 = MFMA16(ka, qb, a4); }
;           const int cq = ct * 16 + i, ck = cpt * 16 + quad * 4;
;           v2u o; o.x = pk2(ck <= cq ? a4[0] : 0.f, ck + 1 <= cq ? a4[1] : 0.f); o.y = pk2(ck + 2 <= cq ? a4[2] : 0.f, ck + 3 <= cq ? a4[3] : 0.f);
;           *(LAS v2u*)(PL + cq * 144 + ck * 2) = o; } }
;     __syncthreads();
	v_mul_f32_e32 v39, v40, v39
	v_cvt_pk_bf16_f32 v38, v38, s0
	ds_write_b16 v0, v38 offset:2992
	v_cvt_pk_bf16_f32 v38, v39, s0
	v_mul_f32_e32 v39, 0x3fb8aa3b, v49
	v_exp_f32_e32 v39, v39
	v_mul_f32_e32 v40, 0xbfb8aa3b, v49
	v_exp_f32_e32 v40, v40
	ds_write_b16 v0, v38 offset:20400
	v_lshlrev_b32_e32 v38, 16, v69
	v_mul_f32_e32 v38, 0x3db504f3, v38
	v_mul_f32_e32 v38, v38, v39
	v_lshlrev_b32_e32 v39, 16, v68
	v_mul_f32_e32 v39, v40, v39
	v_cvt_pk_bf16_f32 v38, v38, s0
	ds_write_b16 v0, v38 offset:3264
	v_cvt_pk_bf16_f32 v38, v39, s0
	v_mul_f32_e32 v39, 0x3fb8aa3b, v50
	v_exp_f32_e32 v39, v39
	v_mul_f32_e32 v40, 0xbfb8aa3b, v50
	v_exp_f32_e32 v40, v40
	ds_write_b16 v0, v38 offset:20672
	v_lshlrev_b32_e32 v38, 16, v67
	v_mul_f32_e32 v38, 0x3db504f3, v38
	v_mul_f32_e32 v38, v38, v39
	v_lshlrev_b32_e32 v39, 16, v66
	v_mul_f32_e32 v39, v40, v39
	v_cvt_pk_bf16_f32 v38, v38, s0
	ds_write_b16 v0, v38 offset:3536
	v_cvt_pk_bf16_f32 v38, v39, s0
	v_mul_f32_e32 v39, 0x3fb8aa3b, v37
	v_exp_f32_e32 v39, v39
	ds_write_b16 v0, v38 offset:20944
	v_lshlrev_b32_e32 v38, 16, v65
	v_mul_f32_e32 v37, 0xbfb8aa3b, v37
	v_mul_f32_e32 v38, 0x3db504f3, v38
	v_exp_f32_e32 v37, v37
	v_mul_f32_e32 v38, v38, v39
	v_cvt_pk_bf16_f32 v38, v38, s0
	v_lshlrev_b32_e32 v39, 16, v64
	ds_write_b16 v0, v38 offset:3808
	v_mul_f32_e32 v38, 0x3fb8aa3b, v36
	v_mul_f32_e32 v37, v37, v39
	v_exp_f32_e32 v38, v38
	v_mul_f32_e32 v36, 0xbfb8aa3b, v36
	v_cvt_pk_bf16_f32 v37, v37, s0
	v_exp_f32_e32 v36, v36
	ds_write_b16 v0, v37 offset:21216
	v_lshlrev_b32_e32 v37, 16, v63
	v_mul_f32_e32 v37, 0x3db504f3, v37
	v_mul_f32_e32 v37, v37, v38
	v_lshlrev_b32_e32 v38, 16, v62
	v_mul_f32_e32 v36, v36, v38
	v_cvt_pk_bf16_f32 v37, v37, s0
	v_cvt_pk_bf16_f32 v36, v36, s0
	ds_write_b16 v0, v37 offset:4080
	ds_write_b16 v0, v36 offset:21488
	v_lshlrev_b32_e32 v0, 4, v58
	v_and_b32_e32 v0, 48, v0
	v_lshlrev_b32_e32 v41, 4, v35
	v_or_b32_e32 v36, v0, v61
	v_add_u32_e32 v40, 0, v41
	v_mad_u32_u24 v62, v36, s16, v40
	s_waitcnt lgkmcnt(0)
	s_barrier
	ds_read_b128 v[36:39], v62 offset:17408
	s_movk_i32 s0, 0xffe0
	v_and_or_b32 v63, v60, s0, v61
	v_mad_u64_u32 v[50:51], s[0:1], v63, s16, v[40:41]
	ds_read_b128 v[42:45], v50
	s_waitcnt lgkmcnt(0)
	v_mfma_f32_16x16x32_bf16 v[36:39], v[36:39], v[42:45], 0
	ds_read_b128 v[42:45], v62 offset:17472
	ds_read_b128 v[46:49], v50 offset:64
	v_lshlrev_b32_e32 v35, 2, v35
	v_or_b32_e32 v52, v0, v35
	s_waitcnt lgkmcnt(0)
	v_mfma_f32_16x16x32_bf16 v[36:39], v[42:45], v[46:49], v[36:39]
	ds_read_b128 v[42:45], v62 offset:17536
	ds_read_b128 v[46:49], v50 offset:128
	v_cmp_le_i32_e32 vcc, v52, v63
	v_or_b32_e32 v53, 2, v52
	s_waitcnt lgkmcnt(0)
	v_mfma_f32_16x16x32_bf16 v[36:39], v[42:45], v[46:49], v[36:39]
	ds_read_b128 v[42:45], v62 offset:17600
	ds_read_b128 v[46:49], v50 offset:192
	v_or_b32_e32 v58, 3, v52
	v_lshl_add_u32 v0, v52, 1, s17
	s_waitcnt lgkmcnt(0)
	v_mfma_f32_16x16x32_bf16 v[36:39], v[42:45], v[46:49], v[36:39]
	v_or3_b32 v60, v61, v60, 16
	v_mad_u64_u32 v[50:51], s[0:1], v60, s16, v[40:41]
	s_nop 5
	v_cndmask_b32_e32 v36, 0, v36, vcc
	v_cmp_lt_i32_e32 vcc, v52, v63
	s_nop 1
	v_cndmask_b32_e32 v37, 0, v37, vcc
	v_cmp_le_i32_e32 vcc, v53, v63
	v_cvt_pk_bf16_f32 v36, v36, v37
	s_nop 0
	v_cndmask_b32_e32 v37, 0, v38, vcc
	v_cmp_le_i32_e32 vcc, v58, v63
	s_nop 1
	v_cndmask_b32_e32 v38, 0, v39, vcc
	v_cvt_pk_bf16_f32 v37, v37, v38
	v_mad_u64_u32 v[38:39], s[0:1], v63, s9, v[0:1]
	ds_write_b64 v38, v[36:37]
	ds_read_b128 v[36:39], v62 offset:17408
	ds_read_b128 v[42:45], v50
	s_waitcnt lgkmcnt(0)
	v_mfma_f32_16x16x32_bf16 v[36:39], v[36:39], v[42:45], 0
	ds_read_b128 v[42:45], v62 offset:17472
	ds_read_b128 v[46:49], v50 offset:64
	v_cmp_le_i32_e32 vcc, v52, v60
	s_waitcnt lgkmcnt(0)
	v_mfma_f32_16x16x32_bf16 v[36:39], v[42:45], v[46:49], v[36:39]
	ds_read_b128 v[42:45], v62 offset:17536
	ds_read_b128 v[46:49], v50 offset:128
	s_waitcnt lgkmcnt(0)
	v_mfma_f32_16x16x32_bf16 v[36:39], v[42:45], v[46:49], v[36:39]
	ds_read_b128 v[42:45], v62 offset:17600
	ds_read_b128 v[46:49], v50 offset:192
	s_waitcnt lgkmcnt(0)
	v_mfma_f32_16x16x32_bf16 v[36:39], v[42:45], v[46:49], v[36:39]
	s_nop 7
	v_cndmask_b32_e32 v36, 0, v36, vcc
	v_cmp_lt_i32_e32 vcc, v52, v60
	s_nop 1
	v_cndmask_b32_e32 v37, 0, v37, vcc
	v_cmp_le_i32_e32 vcc, v53, v60
	v_cvt_pk_bf16_f32 v36, v36, v37
	s_nop 0
	v_cndmask_b32_e32 v37, 0, v38, vcc
	v_cmp_le_i32_e32 vcc, v58, v60
	s_nop 1
	v_cndmask_b32_e32 v38, 0, v39, vcc
	v_cvt_pk_bf16_f32 v37, v37, v38
	v_mad_u64_u32 v[38:39], s[0:1], v60, s9, v[0:1]
	v_mad_u32_u24 v0, v61, s16, v40
	ds_write_b64 v38, v[36:37]
	s_waitcnt lgkmcnt(0)
	s_barrier
; #define LAS __attribute__((address_space(3)))
; #define MFMA16(a, b, c) __builtin_amdgcn_mfma_f32_16x16x32_bf16((a), (b), (c), 0, 0, 0)
; __device__ __forceinline__ s16x4 trread(const LAS unsigned char* p) { return __builtin_bit_cast(s16x4, __builtin_amdgcn_ds_read_tr16_b64_v4i16((LAS s16x4*)p)); }
; __device__ __forceinline__ bf16x8 cat8(s16x4 lo, s16x4 hi) { return (bf16x8){lo[0], lo[1], lo[2], lo[3], hi[0], hi[1], hi[2], hi[3]}; }
; __device__ __forceinline__ void gla_step3(const Params& P, int l, LAS unsigned char* lds, int item, int tid) {
;     ...
;     f32x4 acc[4][2];
; #pragma unroll
;     for (int ct = 0; ct < 4; ++ct) { acc[ct][0] = (f32x4){0.f, 0.f, 0.f, 0.f}; acc[ct][1] = (f32x4){0.f, 0.f, 0.f, 0.f}; }
; #pragma unroll
;     for (int ks = 0; ks < 4; ++ks) { const bf16x8 s0 = sfr[0][ks], s1 = sfr[1][ks];
; #pragma unroll
;         for (int ct = 0; ct < 4; ++ct) { const bf16x8 qa = *(const LAS bf16x8*)(QT + (ct * 16 + i) * 272 + (ks * 32 + quad * 8) * 2); acc[ct][0] = MFMA16(qa, s0, acc[ct][0]); acc[ct][1] = MFMA16(qa, s1, acc[ct][1]); } }
; #pragma unroll
;     for (int ks = 0; ks < 2; ++ks) { const LAS unsigned char* p0 = VT + (ks * 32 + quad * 8 + (i >> 2)) * 544 + (e0 + 4 * (i & 3)) * 2;
;         const bf16x8 v0 = cat8(trread(p0), trread(p0 + 4 * 544)), v1 = cat8(trread(p0 + 32), trread(p0 + 32 + 4 * 544));
; #pragma unroll
;         for (int ct = 0; ct < 4; ++ct) { const bf16x8 pa = *(const LAS bf16x8*)(PL + (ct * 16 + i) * 144 + (ks * 32 + quad * 8) * 2); acc[ct][0] = MFMA16(pa, v0, acc[ct][0]); acc[ct][1] = MFMA16(pa, v1, acc[ct][1]); } }
	ds_read_b128 v[36:39], v0
	ds_read_b128 v[46:49], v0 offset:4352
	ds_read_b128 v[62:65], v0 offset:8704
	ds_read_b128 v[70:73], v0 offset:13056
	s_waitcnt lgkmcnt(3)
	s_waitcnt vmcnt(0)
	v_mfma_f32_16x16x32_bf16 v[42:45], v[36:39], v[26:29], 0
	v_mfma_f32_16x16x32_bf16 v[36:39], v[36:39], v[30:33], 0
	s_waitcnt lgkmcnt(2)
	v_mfma_f32_16x16x32_bf16 v[50:53], v[46:49], v[26:29], 0
	v_mfma_f32_16x16x32_bf16 v[46:49], v[46:49], v[30:33], 0
	s_waitcnt lgkmcnt(1)
	v_mfma_f32_16x16x32_bf16 v[66:69], v[62:65], v[26:29], 0
	v_mfma_f32_16x16x32_bf16 v[62:65], v[62:65], v[30:33], 0
	s_waitcnt lgkmcnt(0)
	v_mfma_f32_16x16x32_bf16 v[26:29], v[70:73], v[26:29], 0
	v_mfma_f32_16x16x32_bf16 v[30:33], v[70:73], v[30:33], 0
	ds_read_b128 v[70:73], v0 offset:64
	s_waitcnt lgkmcnt(0)
	v_mfma_f32_16x16x32_bf16 v[42:45], v[70:73], v[14:17], v[42:45]
	v_mfma_f32_16x16x32_bf16 v[36:39], v[70:73], v[22:25], v[36:39]
	ds_read_b128 v[70:73], v0 offset:4416
	s_waitcnt lgkmcnt(0)
	v_mfma_f32_16x16x32_bf16 v[50:53], v[70:73], v[14:17], v[50:53]
	v_mfma_f32_16x16x32_bf16 v[46:49], v[70:73], v[22:25], v[46:49]
	ds_read_b128 v[70:73], v0 offset:8768
	s_waitcnt lgkmcnt(0)
	v_mfma_f32_16x16x32_bf16 v[66:69], v[70:73], v[14:17], v[66:69]
	v_mfma_f32_16x16x32_bf16 v[62:65], v[70:73], v[22:25], v[62:65]
	ds_read_b128 v[70:73], v0 offset:13120
	s_waitcnt lgkmcnt(0)
	v_mfma_f32_16x16x32_bf16 v[14:17], v[70:73], v[14:17], v[26:29]
	s_nop 2
	ds_read_b128 v[26:29], v0 offset:128
	v_mfma_f32_16x16x32_bf16 v[22:25], v[70:73], v[22:25], v[30:33]
	s_waitcnt lgkmcnt(0)
	v_mfma_f32_16x16x32_bf16 v[30:33], v[26:29], v[10:13], v[42:45]
	v_mfma_f32_16x16x32_bf16 v[26:29], v[26:29], v[18:21], v[36:39]
	s_nop 2
	ds_read_b128 v[36:39], v0 offset:4480
	s_waitcnt lgkmcnt(0)
	v_mfma_f32_16x16x32_bf16 v[42:45], v[36:39], v[10:13], v[50:53]
	v_mfma_f32_16x16x32_bf16 v[36:39], v[36:39], v[18:21], v[46:49]
	s_nop 2
	ds_read_b128 v[46:49], v0 offset:8832
	s_waitcnt lgkmcnt(0)
	v_mfma_f32_16x16x32_bf16 v[50:53], v[46:49], v[10:13], v[66:69]
	v_mfma_f32_16x16x32_bf16 v[46:49], v[46:49], v[18:21], v[62:65]
	s_nop 2
	ds_read_b128 v[62:65], v0 offset:13184
	s_waitcnt lgkmcnt(0)
	v_mfma_f32_16x16x32_bf16 v[10:13], v[62:65], v[10:13], v[14:17]
	v_mfma_f32_16x16x32_bf16 v[14:17], v[62:65], v[18:21], v[22:25]
	ds_read_b128 v[18:21], v0 offset:192
	s_waitcnt lgkmcnt(0)
	v_mfma_f32_16x16x32_bf16 v[22:25], v[18:21], v[2:5], v[30:33]
	v_mfma_f32_16x16x32_bf16 v[18:21], v[18:21], v[6:9], v[26:29]
	s_nop 2
	ds_read_b128 v[26:29], v0 offset:4544
	s_waitcnt lgkmcnt(0)
	v_mfma_f32_16x16x32_bf16 v[30:33], v[26:29], v[2:5], v[42:45]
	v_mfma_f32_16x16x32_bf16 v[26:29], v[26:29], v[6:9], v[36:39]
	s_nop 2
	ds_read_b128 v[36:39], v0 offset:8896
	s_waitcnt lgkmcnt(0)
	v_mfma_f32_16x16x32_bf16 v[42:45], v[36:39], v[2:5], v[50:53]
	v_mfma_f32_16x16x32_bf16 v[36:39], v[36:39], v[6:9], v[46:49]
	s_nop 2
	ds_read_b128 v[46:49], v0 offset:13248
	s_waitcnt lgkmcnt(0)
	v_mfma_f32_16x16x32_bf16 v[2:5], v[46:49], v[2:5], v[10:13]
	v_lshrrev_b32_e32 v0, 2, v61
	s_nop 1
	v_or_b32_e32 v10, v55, v54
	v_lshl_add_u32 v40, v10, 1, 0
	v_or_b32_e32 v10, v34, v0
	v_add_u32_e32 v55, s17, v41
	v_mfma_f32_16x16x32_bf16 v[6:9], v[46:49], v[6:9], v[14:17]
	v_mad_u32_u24 v46, v61, s9, v55
	s_nop 1
	v_mad_u32_u24 v16, v10, s15, v40
	ds_read_b64_tr_b16 v[12:13], v16 offset:36992
	ds_read_b64_tr_b16 v[10:11], v16 offset:34816
	ds_read_b64_tr_b16 v[14:15], v16 offset:34848
	ds_read_b64_tr_b16 v[16:17], v16 offset:37024
	ds_read_b128 v[46:49], v46
	s_waitcnt lgkmcnt(0)
	v_mfma_f32_16x16x32_bf16 v[22:25], v[46:49], v[10:13], v[22:25]
	v_mfma_f32_16x16x32_bf16 v[18:21], v[46:49], v[14:17], v[18:21]
	v_mov_b32_e32 v46, 0x900
	v_mad_u32_u24 v58, v61, s9, v46
	v_add_u32_e32 v46, v55, v58
	ds_read_b128 v[46:49], v46
	s_waitcnt lgkmcnt(0)
	v_mfma_f32_16x16x32_bf16 v[50:53], v[46:49], v[10:13], v[30:33]
	v_mfma_f32_16x16x32_bf16 v[46:49], v[46:49], v[14:17], v[26:29]
	s_nop 2
	v_mov_b32_e32 v26, 0x1200
	v_mad_u32_u24 v60, v61, s9, v26
	v_add_u32_e32 v26, v55, v60
	ds_read_b128 v[26:29], v26
	s_waitcnt lgkmcnt(0)
	v_mfma_f32_16x16x32_bf16 v[42:45], v[26:29], v[10:13], v[42:45]
	v_mfma_f32_16x16x32_bf16 v[36:39], v[26:29], v[14:17], v[36:39]
	v_mov_b32_e32 v26, 0x1b00
	v_mad_u32_u24 v70, v61, s9, v26
	v_add_u32_e32 v26, v55, v70
	ds_read_b128 v[26:29], v26
	v_ashrrev_i32_e32 v55, 31, v54
	s_waitcnt lgkmcnt(0)
	v_mfma_f32_16x16x32_bf16 v[2:5], v[26:29], v[10:13], v[2:5]
	v_or_b32_e32 v10, 32, v34
	v_or_b32_e32 v0, v10, v0
	v_mad_u32_u24 v0, v0, s15, v40
	v_mfma_f32_16x16x32_bf16 v[62:65], v[26:29], v[14:17], v[6:9]
	s_nop 2
	ds_read_b64_tr_b16 v[8:9], v0 offset:36992
	ds_read_b64_tr_b16 v[6:7], v0 offset:34816
	ds_read_b64_tr_b16 v[66:67], v0 offset:34848
	ds_read_b64_tr_b16 v[68:69], v0 offset:37024
	v_lshl_add_u32 v0, v10, 1, s17
	v_mad_u32_u24 v10, v61, s9, v0
	ds_read_b128 v[10:13], v10
	s_lshl_b32 s9, s76, 1
	s_waitcnt lgkmcnt(0)
	v_mfma_f32_16x16x32_bf16 v[30:33], v[10:13], v[6:9], v[22:25]
	s_add_u32 s0, s92, s9
	s_addc_u32 s1, s93, 0
	v_mfma_f32_16x16x32_bf16 v[26:29], v[10:13], v[66:69], v[18:21]
	v_add_u32_e32 v10, v0, v58
	ds_read_b128 v[10:13], v10
	s_waitcnt lgkmcnt(0)
	v_mfma_f32_16x16x32_bf16 v[22:25], v[10:13], v[6:9], v[50:53]
	s_nop 2
	v_mov_b64_e32 v[52:53], s[0:1]
	v_mfma_f32_16x16x32_bf16 v[18:21], v[10:13], v[66:69], v[46:49]
	v_add_u32_e32 v10, v0, v60
	ds_read_b128 v[10:13], v10
	v_add_u32_e32 v0, v0, v70
	s_waitcnt lgkmcnt(0)
	v_mfma_f32_16x16x32_bf16 v[14:17], v[10:13], v[6:9], v[42:45]
	v_mfma_f32_16x16x32_bf16 v[10:13], v[10:13], v[66:69], v[36:39]
	s_nop 2
	ds_read_b128 v[36:39], v0
	s_waitcnt lgkmcnt(0)
; #define LAS __attribute__((address_space(3)))
; #define MFMA16(a, b, c) __builtin_amdgcn_mfma_f32_16x16x32_bf16((a), (b), (c), 0, 0, 0)
; __device__ __forceinline__ void gla_step3(const Params& P, int l, LAS unsigned char* lds, int item, int tid) {
;     ...
;         for (int ct = 0; ct < 4; ++ct) { const bf16x8 pa = *(const LAS bf16x8*)(PL + (ct * 16 + i) * 144 + (ks * 32 + quad * 8) * 2); acc[ct][0] = MFMA16(pa, v0, acc[ct][0]); acc[ct][1] = MFMA16(pa, v1, acc[ct][1]); } }
;     bf16 gra[4][4], grb[4][4];
; #pragma unroll
;     for (int ct = 0; ct < 4; ++ct)
; #pragma unroll
;         for (int j = 0; j < 4; ++j) { const size_t tt = (size_t)(t0 + ct * 16 + quad * 4 + j); gra[ct][j] = z[tt * ZP + ZC_GG + h * 256 + e0 + i]; grb[ct][j] = z[tt * ZP + ZC_GG + h * 256 + e0 + 16 + i]; }
	v_mfma_f32_16x16x32_bf16 v[6:9], v[36:39], v[6:9], v[2:5]
	v_lshlrev_b32_e32 v0, 1, v61
	v_mfma_f32_16x16x32_bf16 v[2:5], v[36:39], v[66:69], v[62:65]
	v_lshlrev_b64 v[66:67], 1, v[54:55]
	s_nop 1
	v_or_b32_e32 v64, s8, v35
	v_mad_i64_i32 v[36:37], s[0:1], v64, s80, v[52:53]
	v_lshl_add_u64 v[36:37], v[36:37], 0, v[66:67]
	v_lshl_add_u64 v[36:37], v[36:37], 0, v[0:1]
	v_lshl_add_u64 v[38:39], v[36:37], 0, s[96:97]
	v_add_co_u32_e32 v36, vcc, s68, v36
	v_or_b32_e32 v62, 1, v64
	s_nop 0
	v_addc_co_u32_e32 v37, vcc, 0, v37, vcc
	global_load_ushort v63, v[36:37], off
	global_load_ushort v89, v[38:39], off offset:32
	v_mad_i64_i32 v[36:37], s[0:1], v62, s80, v[52:53]
	v_lshl_add_u64 v[36:37], v[36:37], 0, v[66:67]
	v_lshl_add_u64 v[36:37], v[36:37], 0, v[0:1]
	v_lshl_add_u64 v[38:39], v[36:37], 0, s[96:97]
	v_add_co_u32_e32 v36, vcc, s68, v36
	v_or_b32_e32 v60, 2, v64
	s_nop 0
	v_addc_co_u32_e32 v37, vcc, 0, v37, vcc
	global_load_ushort v87, v[36:37], off
	global_load_ushort v88, v[38:39], off offset:32
	v_mad_i64_i32 v[36:37], s[0:1], v60, s80, v[52:53]
	v_lshl_add_u64 v[36:37], v[36:37], 0, v[66:67]
	v_lshl_add_u64 v[36:37], v[36:37], 0, v[0:1]
	v_lshl_add_u64 v[38:39], v[36:37], 0, s[96:97]
	v_add_co_u32_e32 v36, vcc, s68, v36
	v_or_b32_e32 v58, 3, v64
	s_nop 0
	v_addc_co_u32_e32 v37, vcc, 0, v37, vcc
	global_load_ushort v85, v[36:37], off
	global_load_ushort v86, v[38:39], off offset:32
	v_mad_i64_i32 v[36:37], s[0:1], v58, s80, v[52:53]
	v_lshl_add_u64 v[36:37], v[36:37], 0, v[66:67]
	v_lshl_add_u64 v[36:37], v[36:37], 0, v[0:1]
	v_lshl_add_u64 v[38:39], v[36:37], 0, s[96:97]
	v_add_co_u32_e32 v36, vcc, s68, v36
	v_or_b32_e32 v34, 16, v64
	s_nop 0
	v_addc_co_u32_e32 v37, vcc, 0, v37, vcc
	global_load_ushort v83, v[36:37], off
	global_load_ushort v84, v[38:39], off offset:32
	v_mad_i64_i32 v[36:37], s[0:1], v34, s80, v[52:53]
	v_lshl_add_u64 v[36:37], v[36:37], 0, v[66:67]
	v_lshl_add_u64 v[36:37], v[36:37], 0, v[0:1]
	v_lshl_add_u64 v[38:39], v[36:37], 0, s[96:97]
	v_add_co_u32_e32 v36, vcc, s68, v36
	v_or_b32_e32 v40, 17, v64
	s_nop 0
	v_addc_co_u32_e32 v37, vcc, 0, v37, vcc
	global_load_ushort v81, v[36:37], off
	global_load_ushort v82, v[38:39], off offset:32
	v_mad_i64_i32 v[36:37], s[0:1], v40, s80, v[52:53]
	v_lshl_add_u64 v[36:37], v[36:37], 0, v[66:67]
	v_lshl_add_u64 v[36:37], v[36:37], 0, v[0:1]
	v_lshl_add_u64 v[38:39], v[36:37], 0, s[96:97]
	v_add_co_u32_e32 v36, vcc, s68, v36
	v_or_b32_e32 v42, 18, v64
	s_nop 0
	v_addc_co_u32_e32 v37, vcc, 0, v37, vcc
	global_load_ushort v43, v[36:37], off
	global_load_ushort v45, v[38:39], off offset:32
	v_mad_i64_i32 v[36:37], s[0:1], v42, s80, v[52:53]
	v_lshl_add_u64 v[36:37], v[36:37], 0, v[66:67]
	v_lshl_add_u64 v[36:37], v[36:37], 0, v[0:1]
	v_lshl_add_u64 v[38:39], v[36:37], 0, s[96:97]
	v_add_co_u32_e32 v36, vcc, s68, v36
	v_or_b32_e32 v44, 19, v64
	s_nop 0
	v_addc_co_u32_e32 v37, vcc, 0, v37, vcc
	global_load_ushort v47, v[36:37], off
	global_load_ushort v49, v[38:39], off offset:32
	v_mad_i64_i32 v[36:37], s[0:1], v44, s80, v[52:53]
	v_lshl_add_u64 v[36:37], v[36:37], 0, v[66:67]
	v_lshl_add_u64 v[36:37], v[36:37], 0, v[0:1]
	v_lshl_add_u64 v[38:39], v[36:37], 0, s[96:97]
	v_add_co_u32_e32 v36, vcc, s68, v36
	v_or_b32_e32 v34, 32, v64
	s_nop 0
	v_addc_co_u32_e32 v37, vcc, 0, v37, vcc
	global_load_ushort v75, v[36:37], off
	global_load_ushort v76, v[38:39], off offset:32
	v_mad_i64_i32 v[36:37], s[0:1], v34, s80, v[52:53]
	v_lshl_add_u64 v[36:37], v[36:37], 0, v[66:67]
	v_lshl_add_u64 v[36:37], v[36:37], 0, v[0:1]
	v_lshl_add_u64 v[38:39], v[36:37], 0, s[96:97]
	v_add_co_u32_e32 v36, vcc, s68, v36
	v_or_b32_e32 v46, 33, v64
	s_nop 0
	v_addc_co_u32_e32 v37, vcc, 0, v37, vcc
	global_load_ushort v51, v[36:37], off
	global_load_ushort v72, v[38:39], off offset:32
	v_mad_i64_i32 v[36:37], s[0:1], v46, s80, v[52:53]
	v_lshl_add_u64 v[36:37], v[36:37], 0, v[66:67]
	v_lshl_add_u64 v[36:37], v[36:37], 0, v[0:1]
	v_lshl_add_u64 v[38:39], v[36:37], 0, s[96:97]
	v_add_co_u32_e32 v36, vcc, s68, v36
	v_or_b32_e32 v48, 34, v64
	s_nop 0
	v_addc_co_u32_e32 v37, vcc, 0, v37, vcc
	global_load_ushort v73, v[36:37], off
	global_load_ushort v74, v[38:39], off offset:32
	v_mad_i64_i32 v[36:37], s[0:1], v48, s80, v[52:53]
	v_lshl_add_u64 v[36:37], v[36:37], 0, v[66:67]
	v_lshl_add_u64 v[36:37], v[36:37], 0, v[0:1]
	v_lshl_add_u64 v[38:39], v[36:37], 0, s[96:97]
	v_add_co_u32_e32 v36, vcc, s68, v36
	v_or_b32_e32 v50, 35, v64
	s_nop 0
	v_addc_co_u32_e32 v37, vcc, 0, v37, vcc
	global_load_ushort v77, v[36:37], off
	global_load_ushort v78, v[38:39], off offset:32
	v_mad_i64_i32 v[36:37], s[0:1], v50, s80, v[52:53]
	v_lshl_add_u64 v[36:37], v[36:37], 0, v[66:67]
	v_lshl_add_u64 v[36:37], v[36:37], 0, v[0:1]
	v_lshl_add_u64 v[38:39], v[36:37], 0, s[96:97]
	v_add_co_u32_e32 v36, vcc, s68, v36
	v_or_b32_e32 v34, 48, v64
	s_nop 0
	v_addc_co_u32_e32 v37, vcc, 0, v37, vcc
	global_load_ushort v79, v[36:37], off
	global_load_ushort v80, v[38:39], off offset:32
	v_mad_i64_i32 v[36:37], s[0:1], v34, s80, v[52:53]
	v_lshl_add_u64 v[36:37], v[36:37], 0, v[66:67]
	v_or_b32_e32 v34, 49, v64
	v_lshl_add_u64 v[36:37], v[36:37], 0, v[0:1]
	v_mad_i64_i32 v[68:69], s[0:1], v34, s80, v[52:53]
	v_lshl_add_u64 v[38:39], v[36:37], 0, s[96:97]
	v_add_co_u32_e32 v36, vcc, s68, v36
	v_lshl_add_u64 v[68:69], v[68:69], 0, v[66:67]
	s_nop 0
	v_addc_co_u32_e32 v37, vcc, 0, v37, vcc
	v_lshl_add_u64 v[68:69], v[68:69], 0, v[0:1]
	v_lshl_add_u64 v[70:71], v[68:69], 0, s[96:97]
	v_add_co_u32_e32 v68, vcc, s68, v68
	global_load_ushort v37, v[36:37], off
	s_nop 0
	global_load_ushort v39, v[38:39], off offset:32
	v_addc_co_u32_e32 v69, vcc, 0, v69, vcc
; __device__ __forceinline__ float row16_sum(float v) { v = DPP_ADD(v, 0xB1); v = DPP_ADD(v, 0x4E); v = DPP_ADD(v, 0x141); v = DPP_ADD(v, 0x140); return v; }
; __device__ __forceinline__ void gla_step3(const Params& P, int l, LAS unsigned char* lds, int item, int tid) {
;     ...
;         for (int j = 0; j < 4; ++j) { const size_t tt = (size_t)(t0 + ct * 16 + quad * 4 + j); gra[ct][j] = z[tt * ZP + ZC_GG + h * 256 + e0 + i]; grb[ct][j] = z[tt * ZP + ZC_GG + h * 256 + e0 + 16 + i]; }
; #pragma unroll
;     for (int ct = 0; ct < 4; ++ct)
; #pragma unroll
;         for (int j = 0; j < 4; ++j) { float s = acc[ct][0][j] * acc[ct][0][j] + acc[ct][1][j] * acc[ct][1][j];
;             s = row16_sum(s);
;             if (i == 0) PART[w * 64 + ct * 16 + quad * 4 + j] = s; }
	v_or_b32_e32 v36, 50, v64
	global_load_ushort v68, v[68:69], off
	s_nop 0
	global_load_ushort v69, v[70:71], off offset:32
	v_mad_i64_i32 v[70:71], s[0:1], v36, s80, v[52:53]
	v_lshl_add_u64 v[70:71], v[70:71], 0, v[66:67]
	v_or_b32_e32 v38, 51, v64
	v_lshl_add_u64 v[70:71], v[70:71], 0, v[0:1]
	v_mad_i64_i32 v[52:53], s[0:1], v38, s80, v[52:53]
	v_lshl_add_u64 v[90:91], v[70:71], 0, s[96:97]
	v_add_co_u32_e32 v70, vcc, s68, v70
	v_lshl_add_u64 v[52:53], v[52:53], 0, v[66:67]
	s_nop 0
	v_addc_co_u32_e32 v71, vcc, 0, v71, vcc
	v_lshl_add_u64 v[52:53], v[52:53], 0, v[0:1]
	global_load_ushort v70, v[70:71], off
	s_nop 0
	global_load_ushort v71, v[90:91], off offset:32
	v_lshl_add_u64 v[90:91], v[52:53], 0, s[96:97]
	v_add_co_u32_e32 v52, vcc, s68, v52
	v_readlane_b32 s0, v255, 20
	s_nop 0
	v_addc_co_u32_e32 v53, vcc, 0, v53, vcc
	global_load_ushort v66, v[52:53], off
	global_load_ushort v67, v[90:91], off offset:32
	v_and_b32_e32 v52, 0x3fffffc0, v59
	v_cmp_eq_u32_e32 vcc, 0, v61
	v_lshl_add_u32 v61, v52, 2, s0
	v_mul_f32_e32 v52, v26, v26
	v_fmac_f32_e32 v52, v30, v30
	v_add_u32_e32 v41, v61, v41
	s_nop 0
	v_add_f32_dpp v52, v52, v52 quad_perm:[1,0,3,2] row_mask:0xf bank_mask:0xf bound_ctrl:1
	s_nop 1
	v_add_f32_dpp v52, v52, v52 quad_perm:[2,3,0,1] row_mask:0xf bank_mask:0xf bound_ctrl:1
	s_nop 1
	v_add_f32_dpp v52, v52, v52 row_half_mirror row_mask:0xf bank_mask:0xf bound_ctrl:1
	s_nop 1
	v_mov_b32_dpp v53, v52 row_mirror row_mask:0xf bank_mask:0xf bound_ctrl:1
	s_and_saveexec_b64 s[0:1], vcc
	v_add_f32_e32 v52, v52, v53
	ds_write_b32 v41, v52
	s_or_b64 exec, exec, s[0:1]
	v_mul_f32_e32 v52, v27, v27
	v_fmac_f32_e32 v52, v31, v31
	s_nop 1
	v_add_f32_dpp v52, v52, v52 quad_perm:[1,0,3,2] row_mask:0xf bank_mask:0xf bound_ctrl:1
	s_nop 1
	v_add_f32_dpp v52, v52, v52 quad_perm:[2,3,0,1] row_mask:0xf bank_mask:0xf bound_ctrl:1
	s_nop 1
	v_add_f32_dpp v52, v52, v52 row_half_mirror row_mask:0xf bank_mask:0xf bound_ctrl:1
	s_nop 1
	v_mov_b32_dpp v53, v52 row_mirror row_mask:0xf bank_mask:0xf bound_ctrl:1
	s_and_saveexec_b64 s[0:1], vcc
	v_add_f32_e32 v52, v52, v53
	ds_write_b32 v41, v52 offset:4
	s_or_b64 exec, exec, s[0:1]
	v_mul_f32_e32 v52, v28, v28
	v_fmac_f32_e32 v52, v32, v32
	s_nop 1
	v_add_f32_dpp v52, v52, v52 quad_perm:[1,0,3,2] row_mask:0xf bank_mask:0xf bound_ctrl:1
	s_nop 1
	v_add_f32_dpp v52, v52, v52 quad_perm:[2,3,0,1] row_mask:0xf bank_mask:0xf bound_ctrl:1
	s_nop 1
	v_add_f32_dpp v52, v52, v52 row_half_mirror row_mask:0xf bank_mask:0xf bound_ctrl:1
	s_nop 1
	v_mov_b32_dpp v53, v52 row_mirror row_mask:0xf bank_mask:0xf bound_ctrl:1
	s_and_saveexec_b64 s[0:1], vcc
	v_add_f32_e32 v52, v52, v53
	ds_write_b32 v41, v52 offset:8
	s_or_b64 exec, exec, s[0:1]
	v_mul_f32_e32 v52, v29, v29
	v_fmac_f32_e32 v52, v33, v33
	s_nop 1
	v_add_f32_dpp v52, v52, v52 quad_perm:[1,0,3,2] row_mask:0xf bank_mask:0xf bound_ctrl:1
	s_nop 1
	v_add_f32_dpp v52, v52, v52 quad_perm:[2,3,0,1] row_mask:0xf bank_mask:0xf bound_ctrl:1
	s_nop 1
	v_add_f32_dpp v52, v52, v52 row_half_mirror row_mask:0xf bank_mask:0xf bound_ctrl:1
	s_nop 1
	v_mov_b32_dpp v53, v52 row_mirror row_mask:0xf bank_mask:0xf bound_ctrl:1
	s_and_saveexec_b64 s[0:1], vcc
	v_add_f32_e32 v52, v52, v53
	ds_write_b32 v41, v52 offset:12
	s_or_b64 exec, exec, s[0:1]
	v_mul_f32_e32 v52, v18, v18
	v_fmac_f32_e32 v52, v22, v22
	s_nop 1
	v_add_f32_dpp v52, v52, v52 quad_perm:[1,0,3,2] row_mask:0xf bank_mask:0xf bound_ctrl:1
	s_nop 1
	v_add_f32_dpp v52, v52, v52 quad_perm:[2,3,0,1] row_mask:0xf bank_mask:0xf bound_ctrl:1
	s_nop 1
	v_add_f32_dpp v52, v52, v52 row_half_mirror row_mask:0xf bank_mask:0xf bound_ctrl:1
	s_nop 1
	v_mov_b32_dpp v53, v52 row_mirror row_mask:0xf bank_mask:0xf bound_ctrl:1
	s_and_saveexec_b64 s[0:1], vcc
	v_add_f32_e32 v52, v52, v53
	ds_write_b32 v41, v52 offset:64
	s_or_b64 exec, exec, s[0:1]
	v_mul_f32_e32 v52, v19, v19
	v_fmac_f32_e32 v52, v23, v23
	s_nop 1
	v_add_f32_dpp v52, v52, v52 quad_perm:[1,0,3,2] row_mask:0xf bank_mask:0xf bound_ctrl:1
	s_nop 1
	v_add_f32_dpp v52, v52, v52 quad_perm:[2,3,0,1] row_mask:0xf bank_mask:0xf bound_ctrl:1
	s_nop 1
	v_add_f32_dpp v52, v52, v52 row_half_mirror row_mask:0xf bank_mask:0xf bound_ctrl:1
	s_nop 1
	v_mov_b32_dpp v53, v52 row_mirror row_mask:0xf bank_mask:0xf bound_ctrl:1
	s_and_saveexec_b64 s[0:1], vcc
	v_add_f32_e32 v52, v52, v53
	ds_write_b32 v41, v52 offset:68
	s_or_b64 exec, exec, s[0:1]
	v_mul_f32_e32 v52, v20, v20
	v_fmac_f32_e32 v52, v24, v24
	s_nop 1
	v_add_f32_dpp v52, v52, v52 quad_perm:[1,0,3,2] row_mask:0xf bank_mask:0xf bound_ctrl:1
	s_nop 1
	v_add_f32_dpp v52, v52, v52 quad_perm:[2,3,0,1] row_mask:0xf bank_mask:0xf bound_ctrl:1
	s_nop 1
	v_add_f32_dpp v52, v52, v52 row_half_mirror row_mask:0xf bank_mask:0xf bound_ctrl:1
	s_nop 1
	v_mov_b32_dpp v53, v52 row_mirror row_mask:0xf bank_mask:0xf bound_ctrl:1
	s_and_saveexec_b64 s[0:1], vcc
	v_add_f32_e32 v52, v52, v53
	ds_write_b32 v41, v52 offset:72
	s_or_b64 exec, exec, s[0:1]
	v_mul_f32_e32 v52, v21, v21
	v_fmac_f32_e32 v52, v25, v25
	s_nop 1
	v_add_f32_dpp v52, v52, v52 quad_perm:[1,0,3,2] row_mask:0xf bank_mask:0xf bound_ctrl:1
	s_nop 1
	v_add_f32_dpp v52, v52, v52 quad_perm:[2,3,0,1] row_mask:0xf bank_mask:0xf bound_ctrl:1
	s_nop 1
	v_add_f32_dpp v52, v52, v52 row_half_mirror row_mask:0xf bank_mask:0xf bound_ctrl:1
	s_nop 1
	v_mov_b32_dpp v53, v52 row_mirror row_mask:0xf bank_mask:0xf bound_ctrl:1
	s_and_saveexec_b64 s[0:1], vcc
	v_add_f32_e32 v52, v52, v53
	ds_write_b32 v41, v52 offset:76
; __device__ __forceinline__ float row16_sum(float v) { v = DPP_ADD(v, 0xB1); v = DPP_ADD(v, 0x4E); v = DPP_ADD(v, 0x141); v = DPP_ADD(v, 0x140); return v; }
; __device__ __forceinline__ void gla_step3(const Params& P, int l, LAS unsigned char* lds, int item, int tid) {
;     ...
;     for (int ct = 0; ct < 4; ++ct)
; #pragma unroll
;         for (int j = 0; j < 4; ++j) { float s = acc[ct][0][j] * acc[ct][0][j] + acc[ct][1][j] * acc[ct][1][j];
;             s = row16_sum(s);
;             if (i == 0) PART[w * 64 + ct * 16 + quad * 4 + j] = s; }
;     __syncthreads();
;     if (tid < 64) { float s = 0.f;
; #pragma unroll
;         for (int ww = 0; ww < 8; ++ww) s += PART[ww * 64 + tid];
;         PART[512 + tid] = rsqrtf(s * (1.0f / 256.0f) + 1e-6f); }
;     __syncthreads();
	s_or_b64 exec, exec, s[0:1]
	v_mul_f32_e32 v52, v10, v10
	v_fmac_f32_e32 v52, v14, v14
	s_nop 1
	v_add_f32_dpp v52, v52, v52 quad_perm:[1,0,3,2] row_mask:0xf bank_mask:0xf bound_ctrl:1
	s_nop 1
	v_add_f32_dpp v52, v52, v52 quad_perm:[2,3,0,1] row_mask:0xf bank_mask:0xf bound_ctrl:1
	s_nop 1
	v_add_f32_dpp v52, v52, v52 row_half_mirror row_mask:0xf bank_mask:0xf bound_ctrl:1
	s_nop 1
	v_mov_b32_dpp v53, v52 row_mirror row_mask:0xf bank_mask:0xf bound_ctrl:1
	s_and_saveexec_b64 s[0:1], vcc
	v_add_f32_e32 v52, v52, v53
	ds_write_b32 v41, v52 offset:128
	s_or_b64 exec, exec, s[0:1]
	v_mul_f32_e32 v52, v11, v11
	v_fmac_f32_e32 v52, v15, v15
	s_nop 1
	v_add_f32_dpp v52, v52, v52 quad_perm:[1,0,3,2] row_mask:0xf bank_mask:0xf bound_ctrl:1
	s_nop 1
	v_add_f32_dpp v52, v52, v52 quad_perm:[2,3,0,1] row_mask:0xf bank_mask:0xf bound_ctrl:1
	s_nop 1
	v_add_f32_dpp v52, v52, v52 row_half_mirror row_mask:0xf bank_mask:0xf bound_ctrl:1
	s_nop 1
	v_mov_b32_dpp v53, v52 row_mirror row_mask:0xf bank_mask:0xf bound_ctrl:1
	s_and_saveexec_b64 s[0:1], vcc
	v_add_f32_e32 v52, v52, v53
	ds_write_b32 v41, v52 offset:132
	s_or_b64 exec, exec, s[0:1]
	v_mul_f32_e32 v52, v12, v12
	v_fmac_f32_e32 v52, v16, v16
	s_nop 1
	v_add_f32_dpp v52, v52, v52 quad_perm:[1,0,3,2] row_mask:0xf bank_mask:0xf bound_ctrl:1
	s_nop 1
	v_add_f32_dpp v52, v52, v52 quad_perm:[2,3,0,1] row_mask:0xf bank_mask:0xf bound_ctrl:1
	s_nop 1
	v_add_f32_dpp v52, v52, v52 row_half_mirror row_mask:0xf bank_mask:0xf bound_ctrl:1
	s_nop 1
	v_mov_b32_dpp v53, v52 row_mirror row_mask:0xf bank_mask:0xf bound_ctrl:1
	s_and_saveexec_b64 s[0:1], vcc
	v_add_f32_e32 v52, v52, v53
	ds_write_b32 v41, v52 offset:136
	s_or_b64 exec, exec, s[0:1]
	v_mul_f32_e32 v52, v13, v13
	v_fmac_f32_e32 v52, v17, v17
	s_nop 1
	v_add_f32_dpp v52, v52, v52 quad_perm:[1,0,3,2] row_mask:0xf bank_mask:0xf bound_ctrl:1
	s_nop 1
	v_add_f32_dpp v52, v52, v52 quad_perm:[2,3,0,1] row_mask:0xf bank_mask:0xf bound_ctrl:1
	s_nop 1
	v_add_f32_dpp v52, v52, v52 row_half_mirror row_mask:0xf bank_mask:0xf bound_ctrl:1
	s_nop 1
	v_mov_b32_dpp v53, v52 row_mirror row_mask:0xf bank_mask:0xf bound_ctrl:1
	s_and_saveexec_b64 s[0:1], vcc
	v_add_f32_e32 v52, v52, v53
	ds_write_b32 v41, v52 offset:140
	s_or_b64 exec, exec, s[0:1]
	v_mul_f32_e32 v52, v2, v2
	v_fmac_f32_e32 v52, v6, v6
	s_nop 1
	v_add_f32_dpp v52, v52, v52 quad_perm:[1,0,3,2] row_mask:0xf bank_mask:0xf bound_ctrl:1
	s_nop 1
	v_add_f32_dpp v52, v52, v52 quad_perm:[2,3,0,1] row_mask:0xf bank_mask:0xf bound_ctrl:1
	s_nop 1
	v_add_f32_dpp v52, v52, v52 row_half_mirror row_mask:0xf bank_mask:0xf bound_ctrl:1
	s_nop 1
	v_mov_b32_dpp v53, v52 row_mirror row_mask:0xf bank_mask:0xf bound_ctrl:1
	s_and_saveexec_b64 s[0:1], vcc
	v_add_f32_e32 v52, v52, v53
	ds_write_b32 v41, v52 offset:192
	s_or_b64 exec, exec, s[0:1]
	v_mul_f32_e32 v52, v3, v3
	v_fmac_f32_e32 v52, v7, v7
	s_nop 1
	v_add_f32_dpp v52, v52, v52 quad_perm:[1,0,3,2] row_mask:0xf bank_mask:0xf bound_ctrl:1
	s_nop 1
	v_add_f32_dpp v52, v52, v52 quad_perm:[2,3,0,1] row_mask:0xf bank_mask:0xf bound_ctrl:1
	s_nop 1
	v_add_f32_dpp v52, v52, v52 row_half_mirror row_mask:0xf bank_mask:0xf bound_ctrl:1
	s_nop 1
	v_mov_b32_dpp v53, v52 row_mirror row_mask:0xf bank_mask:0xf bound_ctrl:1
	s_and_saveexec_b64 s[0:1], vcc
	v_add_f32_e32 v52, v52, v53
	ds_write_b32 v41, v52 offset:196
	s_or_b64 exec, exec, s[0:1]
	v_mul_f32_e32 v52, v4, v4
	v_fmac_f32_e32 v52, v8, v8
	s_nop 1
	v_add_f32_dpp v52, v52, v52 quad_perm:[1,0,3,2] row_mask:0xf bank_mask:0xf bound_ctrl:1
	s_nop 1
	v_add_f32_dpp v52, v52, v52 quad_perm:[2,3,0,1] row_mask:0xf bank_mask:0xf bound_ctrl:1
	s_nop 1
	v_add_f32_dpp v52, v52, v52 row_half_mirror row_mask:0xf bank_mask:0xf bound_ctrl:1
	s_nop 1
	v_mov_b32_dpp v53, v52 row_mirror row_mask:0xf bank_mask:0xf bound_ctrl:1
	s_and_saveexec_b64 s[0:1], vcc
	v_add_f32_e32 v52, v52, v53
	ds_write_b32 v41, v52 offset:200
	s_or_b64 exec, exec, s[0:1]
	v_mul_f32_e32 v52, v5, v5
	v_fmac_f32_e32 v52, v9, v9
	s_nop 1
	v_add_f32_dpp v52, v52, v52 quad_perm:[1,0,3,2] row_mask:0xf bank_mask:0xf bound_ctrl:1
	s_nop 1
	v_add_f32_dpp v52, v52, v52 quad_perm:[2,3,0,1] row_mask:0xf bank_mask:0xf bound_ctrl:1
	s_nop 1
	v_add_f32_dpp v52, v52, v52 row_half_mirror row_mask:0xf bank_mask:0xf bound_ctrl:1
	s_nop 1
	v_mov_b32_dpp v53, v52 row_mirror row_mask:0xf bank_mask:0xf bound_ctrl:1
	s_and_saveexec_b64 s[0:1], vcc
	v_add_f32_e32 v52, v52, v53
	ds_write_b32 v41, v52 offset:204
	s_or_b64 exec, exec, s[0:1]
	v_cmp_gt_i32_e32 vcc, 64, v59
	s_waitcnt lgkmcnt(0)
	s_barrier
	s_and_saveexec_b64 s[0:1], vcc
	s_cbranch_execz .LBB0_633
	v_lshl_add_u32 v41, v59, 2, 0
	v_add_u32_e32 v41, 0x24400, v41
	ds_read2st64_b32 v[52:53], v41 offset1:1
	s_waitcnt lgkmcnt(0)
	v_add_f32_e32 v52, 0, v52
	v_add_f32_e32 v59, v52, v53
	ds_read2st64_b32 v[52:53], v41 offset0:2 offset1:3
	s_waitcnt lgkmcnt(0)
	v_add_f32_e32 v52, v59, v52
	v_add_f32_e32 v59, v52, v53
	ds_read2st64_b32 v[52:53], v41 offset0:4 offset1:5
	s_waitcnt lgkmcnt(0)
	v_add_f32_e32 v52, v59, v52
	v_add_f32_e32 v59, v52, v53
	ds_read2st64_b32 v[52:53], v41 offset0:6 offset1:7
	s_waitcnt lgkmcnt(0)
	v_add_f32_e32 v52, v59, v52
	v_add_f32_e32 v52, v52, v53
	v_fmamk_f32 v52, v52, 0x3b800000, v239
	v_cmp_gt_f32_e32 vcc, s74, v52
	v_mul_f32_e32 v53, 0x4b800000, v52
	s_nop 0
	v_cndmask_b32_e32 v52, v52, v53, vcc
	v_rsq_f32_e32 v52, v52
	s_nop 0
	v_mul_f32_e32 v53, 0x45800000, v52
	v_cndmask_b32_e32 v52, v52, v53, vcc
	ds_write_b32 v41, v52 offset:2048
	s_branch .LBB0_633
